# speedup vs baseline: 1.1651x; 1.0005x over previous
; __device__ __forceinline__ void phase_rwkv_scan(const Params& p, int l, const int tidx) {
;     ...
;       RW_LD(0);
; #pragma unroll
;       for (int s = 0; s < RTC; s++) {
;         const bf16x8 A0 = nA0, A1 = nA1;
;         const float wA[8] = {nw0.x, nw0.y, nw0.z, nw0.w, nw1.x, nw1.y, nw1.z, nw1.w};
;         const float wB[8] = {nw2.x, nw2.y, nw2.z, nw2.w, nw3.x, nw3.y, nw3.z, nw3.w};
;         const float kaA[8] = {nka0.x, nka0.y, nka0.z, nka0.w, nka1.x, nka1.y, nka1.z, nka1.w};
;         const float kaB[8] = {nka2.x, nka2.y, nka2.z, nka2.w, nka3.x, nka3.y, nka3.z, nka3.w};
;         const float kdA[8] = {nkd0.x, nkd0.y, nkd0.z, nkd0.w, nkd1.x, nkd1.y, nkd1.z, nkd1.w};
;         const float kdB[8] = {nkd2.x, nkd2.y, nkd2.z, nkd2.w, nkd3.x, nkd3.y, nkd3.z, nkd3.w};
;         const float v = nv;
;         float c1 = nc.x, c2 = nc.y;
;         asm volatile("" : "+v"(c1), "+v"(c2));
;         if (s + 1 < RTC) RW_LD(s + 1);
;         u32x4 pa = {pack2(Sa[0], Sa[1]), pack2(Sa[2], Sa[3]), pack2(Sa[4], Sa[5]), pack2(Sa[6], Sa[7])};
;         u32x4 pb = {pack2(Sb[0], Sb[1]), pack2(Sb[2], Sb[3]), pack2(Sb[4], Sb[5]), pack2(Sb[6], Sb[7])};
;         f32x4 acc = {0.f, 0.f, 0.f, 0.f};
;         acc = __builtin_amdgcn_mfma_f32_16x16x32_bf16(A0, __builtin_bit_cast(bf16x8, pa), acc, 0, 0, 0);
;         acc = __builtin_amdgcn_mfma_f32_16x16x32_bf16(A1, __builtin_bit_cast(bf16x8, pb), acc, 0, 0, 0);
;         float tA[8], tB[8];
; #pragma unroll
;         for (int c = 0; c < 8; c++) { tA[c] = Sa[c] * wA[c] + v * kdA[c]; tB[c] = Sb[c] * wB[c] + v * kdB[c]; }
;         const float sa = -acc[0];
;         const float yq = acc[1];
; #pragma unroll
;         for (int c = 0; c < 8; c++) { Sa[c] = tA[c] + sa * kaA[c]; Sb[c] = tB[c] + sa * kaB[c]; }
;         const float y = yq + sa * c1 + v * c2;
;         if (quad == 0) by[s * 64 + row] = y;
;       }
.Lrw_chunk:
	s_bitcmp1_b32 s0, 0
	s_cselect_b32 s10, 0xc100, 0
	v_add_u32_e32 v104, s10, v100
	v_add_u32_e32 v105, s10, v101
	v_add_u32_e32 v106, s10, v102
	v_add_u32_e32 v107, s10, v103
	v_mov_b32_e32 v108, s10
	ds_read_b128 v[40:43], v104 offset:0
	ds_read_b128 v[44:47], v104 offset:16
	ds_read_b32 v65, v105 offset:16384
	ds_read_b32 v66, v107 offset:0
	ds_read_b32 v48, v105 offset:8192
	ds_read_b64 v[68:69], v108 offset:49152
	ds_read_b128 v[70:73], v104 offset:256
	ds_read_b128 v[74:77], v104 offset:272
	ds_read_b32 v95, v105 offset:16640
	ds_read_b32 v96, v107 offset:256
	ds_read_b32 v78, v105 offset:8448
	ds_read_b64 v[98:99], v108 offset:49160
	v_cvt_pk_bf16_f32 v24, v8, v9
	v_cvt_pk_bf16_f32 v25, v10, v11
	v_cvt_pk_bf16_f32 v26, v12, v13
	v_cvt_pk_bf16_f32 v27, v14, v15
	v_cvt_pk_bf16_f32 v28, v16, v17
	v_cvt_pk_bf16_f32 v29, v18, v19
	s_waitcnt lgkmcnt(8)
	v_mfma_f32_16x16x32_bf16 v[32:35], v[40:43], v[24:27], 0
	v_cvt_pk_bf16_f32 v30, v20, v21
	v_cvt_pk_bf16_f32 v31, v22, v23
	v_fmac_f32_dpp v8, v65, v66 row_newbcast:0 row_mask:0xf bank_mask:0xf
	v_fmac_f32_dpp v9, v65, v66 row_newbcast:1 row_mask:0xf bank_mask:0xf
	v_mfma_f32_16x16x32_bf16 v[32:35], v[44:47], v[28:31], v[32:35]
	v_fmac_f32_dpp v10, v65, v66 row_newbcast:2 row_mask:0xf bank_mask:0xf
	v_fmac_f32_dpp v11, v65, v66 row_newbcast:3 row_mask:0xf bank_mask:0xf
	ds_read_b128 v[112:115], v104 offset:512
	v_fmac_f32_dpp v12, v65, v66 row_newbcast:4 row_mask:0xf bank_mask:0xf
	v_fmac_f32_dpp v13, v65, v66 row_newbcast:5 row_mask:0xf bank_mask:0xf
	ds_read_b128 v[116:119], v104 offset:528
	v_fmac_f32_dpp v14, v65, v66 row_newbcast:6 row_mask:0xf bank_mask:0xf
	v_fmac_f32_dpp v15, v65, v66 row_newbcast:7 row_mask:0xf bank_mask:0xf
	ds_read_b32 v137, v105 offset:16896
	v_fmac_f32_dpp v16, v65, v66 row_newbcast:8 row_mask:0xf bank_mask:0xf
	v_fmac_f32_dpp v17, v65, v66 row_newbcast:9 row_mask:0xf bank_mask:0xf
	ds_read_b32 v138, v107 offset:512
	v_fmac_f32_dpp v18, v65, v66 row_newbcast:10 row_mask:0xf bank_mask:0xf
	v_fmac_f32_dpp v19, v65, v66 row_newbcast:11 row_mask:0xf bank_mask:0xf
	ds_read_b32 v120, v105 offset:8704
	v_fmac_f32_dpp v20, v65, v66 row_newbcast:12 row_mask:0xf bank_mask:0xf
	v_fmac_f32_dpp v21, v65, v66 row_newbcast:13 row_mask:0xf bank_mask:0xf
	ds_read_b64 v[140:141], v108 offset:49168
	v_fmac_f32_dpp v22, v65, v66 row_newbcast:14 row_mask:0xf bank_mask:0xf
	v_fmac_f32_dpp v23, v65, v66 row_newbcast:15 row_mask:0xf bank_mask:0xf
	s_waitcnt lgkmcnt(12)
	v_fmac_f32_dpp v8, v48, v32 row_newbcast:0 row_mask:0xf bank_mask:0xf
	v_fmac_f32_dpp v9, v48, v32 row_newbcast:1 row_mask:0xf bank_mask:0xf
	v_fmac_f32_dpp v10, v48, v32 row_newbcast:2 row_mask:0xf bank_mask:0xf
	v_fmac_f32_dpp v11, v48, v32 row_newbcast:3 row_mask:0xf bank_mask:0xf
	v_fmac_f32_dpp v12, v48, v32 row_newbcast:4 row_mask:0xf bank_mask:0xf
	v_fmac_f32_dpp v13, v48, v32 row_newbcast:5 row_mask:0xf bank_mask:0xf
	v_fmac_f32_dpp v14, v48, v32 row_newbcast:6 row_mask:0xf bank_mask:0xf
	v_fmac_f32_dpp v15, v48, v32 row_newbcast:7 row_mask:0xf bank_mask:0xf
	v_fmac_f32_dpp v16, v48, v32 row_newbcast:8 row_mask:0xf bank_mask:0xf
	v_fmac_f32_dpp v17, v48, v32 row_newbcast:9 row_mask:0xf bank_mask:0xf
	v_fmac_f32_dpp v18, v48, v32 row_newbcast:10 row_mask:0xf bank_mask:0xf
	v_fmac_f32_dpp v19, v48, v32 row_newbcast:11 row_mask:0xf bank_mask:0xf
	v_fmac_f32_dpp v20, v48, v32 row_newbcast:12 row_mask:0xf bank_mask:0xf
	v_fmac_f32_dpp v21, v48, v32 row_newbcast:13 row_mask:0xf bank_mask:0xf
	v_fmac_f32_dpp v22, v48, v32 row_newbcast:14 row_mask:0xf bank_mask:0xf
	v_fmac_f32_dpp v23, v48, v32 row_newbcast:15 row_mask:0xf bank_mask:0xf
	v_fma_f32 v109, -v32, v68, v33
	v_fma_f32 v109, v66, v69, v109
	ds_write_b32 v107, v109 offset:8192
	v_cvt_pk_bf16_f32 v24, v8, v9
	v_cvt_pk_bf16_f32 v25, v10, v11
	v_cvt_pk_bf16_f32 v26, v12, v13
	v_cvt_pk_bf16_f32 v27, v14, v15
	v_cvt_pk_bf16_f32 v28, v16, v17
	v_cvt_pk_bf16_f32 v29, v18, v19
	s_waitcnt lgkmcnt(9)
	v_mfma_f32_16x16x32_bf16 v[32:35], v[70:73], v[24:27], 0
	v_cvt_pk_bf16_f32 v30, v20, v21
	v_cvt_pk_bf16_f32 v31, v22, v23
	v_fmac_f32_dpp v8, v95, v96 row_newbcast:0 row_mask:0xf bank_mask:0xf
	v_fmac_f32_dpp v9, v95, v96 row_newbcast:1 row_mask:0xf bank_mask:0xf
	v_mfma_f32_16x16x32_bf16 v[32:35], v[74:77], v[28:31], v[32:35]
	v_fmac_f32_dpp v10, v95, v96 row_newbcast:2 row_mask:0xf bank_mask:0xf
	v_fmac_f32_dpp v11, v95, v96 row_newbcast:3 row_mask:0xf bank_mask:0xf
	ds_read_b128 v[40:43], v104 offset:768
	v_fmac_f32_dpp v12, v95, v96 row_newbcast:4 row_mask:0xf bank_mask:0xf
	v_fmac_f32_dpp v13, v95, v96 row_newbcast:5 row_mask:0xf bank_mask:0xf
	ds_read_b128 v[44:47], v104 offset:784
	v_fmac_f32_dpp v14, v95, v96 row_newbcast:6 row_mask:0xf bank_mask:0xf
	v_fmac_f32_dpp v15, v95, v96 row_newbcast:7 row_mask:0xf bank_mask:0xf
	ds_read_b32 v65, v105 offset:17152
	v_fmac_f32_dpp v16, v95, v96 row_newbcast:8 row_mask:0xf bank_mask:0xf
	v_fmac_f32_dpp v17, v95, v96 row_newbcast:9 row_mask:0xf bank_mask:0xf
	ds_read_b32 v66, v107 offset:768
	v_fmac_f32_dpp v18, v95, v96 row_newbcast:10 row_mask:0xf bank_mask:0xf
	v_fmac_f32_dpp v19, v95, v96 row_newbcast:11 row_mask:0xf bank_mask:0xf
	ds_read_b32 v48, v105 offset:8960
	v_fmac_f32_dpp v20, v95, v96 row_newbcast:12 row_mask:0xf bank_mask:0xf
	v_fmac_f32_dpp v21, v95, v96 row_newbcast:13 row_mask:0xf bank_mask:0xf
	ds_read_b64 v[68:69], v108 offset:49176
	v_fmac_f32_dpp v22, v95, v96 row_newbcast:14 row_mask:0xf bank_mask:0xf
	v_fmac_f32_dpp v23, v95, v96 row_newbcast:15 row_mask:0xf bank_mask:0xf
	s_waitcnt lgkmcnt(13)
; __device__ __forceinline__ void phase_rwkv_scan(const Params& p, int l, const int tidx) {
;     ...
;       for (int s = 0; s < RTC; s++) {
;         const bf16x8 A0 = nA0, A1 = nA1;
;         const float wA[8] = {nw0.x, nw0.y, nw0.z, nw0.w, nw1.x, nw1.y, nw1.z, nw1.w};
;         const float wB[8] = {nw2.x, nw2.y, nw2.z, nw2.w, nw3.x, nw3.y, nw3.z, nw3.w};
;         const float kaA[8] = {nka0.x, nka0.y, nka0.z, nka0.w, nka1.x, nka1.y, nka1.z, nka1.w};
;         const float kaB[8] = {nka2.x, nka2.y, nka2.z, nka2.w, nka3.x, nka3.y, nka3.z, nka3.w};
;         const float kdA[8] = {nkd0.x, nkd0.y, nkd0.z, nkd0.w, nkd1.x, nkd1.y, nkd1.z, nkd1.w};
;         const float kdB[8] = {nkd2.x, nkd2.y, nkd2.z, nkd2.w, nkd3.x, nkd3.y, nkd3.z, nkd3.w};
;         const float v = nv;
;         float c1 = nc.x, c2 = nc.y;
;         asm volatile("" : "+v"(c1), "+v"(c2));
;         if (s + 1 < RTC) RW_LD(s + 1);
;         u32x4 pa = {pack2(Sa[0], Sa[1]), pack2(Sa[2], Sa[3]), pack2(Sa[4], Sa[5]), pack2(Sa[6], Sa[7])};
;         u32x4 pb = {pack2(Sb[0], Sb[1]), pack2(Sb[2], Sb[3]), pack2(Sb[4], Sb[5]), pack2(Sb[6], Sb[7])};
;         f32x4 acc = {0.f, 0.f, 0.f, 0.f};
;         acc = __builtin_amdgcn_mfma_f32_16x16x32_bf16(A0, __builtin_bit_cast(bf16x8, pa), acc, 0, 0, 0);
;         acc = __builtin_amdgcn_mfma_f32_16x16x32_bf16(A1, __builtin_bit_cast(bf16x8, pb), acc, 0, 0, 0);
;         float tA[8], tB[8];
; #pragma unroll
;         for (int c = 0; c < 8; c++) { tA[c] = Sa[c] * wA[c] + v * kdA[c]; tB[c] = Sb[c] * wB[c] + v * kdB[c]; }
;         const float sa = -acc[0];
;         const float yq = acc[1];
; #pragma unroll
;         for (int c = 0; c < 8; c++) { Sa[c] = tA[c] + sa * kaA[c]; Sb[c] = tB[c] + sa * kaB[c]; }
;         const float y = yq + sa * c1 + v * c2;
;         if (quad == 0) by[s * 64 + row] = y;
;       }
	v_fmac_f32_dpp v8, v78, v32 row_newbcast:0 row_mask:0xf bank_mask:0xf
	v_fmac_f32_dpp v9, v78, v32 row_newbcast:1 row_mask:0xf bank_mask:0xf
	v_fmac_f32_dpp v10, v78, v32 row_newbcast:2 row_mask:0xf bank_mask:0xf
	v_fmac_f32_dpp v11, v78, v32 row_newbcast:3 row_mask:0xf bank_mask:0xf
	v_fmac_f32_dpp v12, v78, v32 row_newbcast:4 row_mask:0xf bank_mask:0xf
	v_fmac_f32_dpp v13, v78, v32 row_newbcast:5 row_mask:0xf bank_mask:0xf
	v_fmac_f32_dpp v14, v78, v32 row_newbcast:6 row_mask:0xf bank_mask:0xf
	v_fmac_f32_dpp v15, v78, v32 row_newbcast:7 row_mask:0xf bank_mask:0xf
	v_fmac_f32_dpp v16, v78, v32 row_newbcast:8 row_mask:0xf bank_mask:0xf
	v_fmac_f32_dpp v17, v78, v32 row_newbcast:9 row_mask:0xf bank_mask:0xf
	v_fmac_f32_dpp v18, v78, v32 row_newbcast:10 row_mask:0xf bank_mask:0xf
	v_fmac_f32_dpp v19, v78, v32 row_newbcast:11 row_mask:0xf bank_mask:0xf
	v_fmac_f32_dpp v20, v78, v32 row_newbcast:12 row_mask:0xf bank_mask:0xf
	v_fmac_f32_dpp v21, v78, v32 row_newbcast:13 row_mask:0xf bank_mask:0xf
	v_fmac_f32_dpp v22, v78, v32 row_newbcast:14 row_mask:0xf bank_mask:0xf
	v_fmac_f32_dpp v23, v78, v32 row_newbcast:15 row_mask:0xf bank_mask:0xf
	v_fma_f32 v109, -v32, v98, v33
	v_fma_f32 v109, v96, v99, v109
	ds_write_b32 v107, v109 offset:8448
	v_cvt_pk_bf16_f32 v24, v8, v9
	v_cvt_pk_bf16_f32 v25, v10, v11
	v_cvt_pk_bf16_f32 v26, v12, v13
	v_cvt_pk_bf16_f32 v27, v14, v15
	v_cvt_pk_bf16_f32 v28, v16, v17
	v_cvt_pk_bf16_f32 v29, v18, v19
	s_waitcnt lgkmcnt(10)
	v_mfma_f32_16x16x32_bf16 v[32:35], v[112:115], v[24:27], 0
	v_cvt_pk_bf16_f32 v30, v20, v21
	v_cvt_pk_bf16_f32 v31, v22, v23
	v_fmac_f32_dpp v8, v137, v138 row_newbcast:0 row_mask:0xf bank_mask:0xf
	v_fmac_f32_dpp v9, v137, v138 row_newbcast:1 row_mask:0xf bank_mask:0xf
	v_mfma_f32_16x16x32_bf16 v[32:35], v[116:119], v[28:31], v[32:35]
	v_fmac_f32_dpp v10, v137, v138 row_newbcast:2 row_mask:0xf bank_mask:0xf
	v_fmac_f32_dpp v11, v137, v138 row_newbcast:3 row_mask:0xf bank_mask:0xf
	ds_read_b128 v[70:73], v104 offset:1024
	v_fmac_f32_dpp v12, v137, v138 row_newbcast:4 row_mask:0xf bank_mask:0xf
	v_fmac_f32_dpp v13, v137, v138 row_newbcast:5 row_mask:0xf bank_mask:0xf
	ds_read_b128 v[74:77], v104 offset:1040
	v_fmac_f32_dpp v14, v137, v138 row_newbcast:6 row_mask:0xf bank_mask:0xf
	v_fmac_f32_dpp v15, v137, v138 row_newbcast:7 row_mask:0xf bank_mask:0xf
	ds_read_b32 v95, v105 offset:17408
	v_fmac_f32_dpp v16, v137, v138 row_newbcast:8 row_mask:0xf bank_mask:0xf
	v_fmac_f32_dpp v17, v137, v138 row_newbcast:9 row_mask:0xf bank_mask:0xf
	ds_read_b32 v96, v107 offset:1024
	v_fmac_f32_dpp v18, v137, v138 row_newbcast:10 row_mask:0xf bank_mask:0xf
	v_fmac_f32_dpp v19, v137, v138 row_newbcast:11 row_mask:0xf bank_mask:0xf
	ds_read_b32 v78, v105 offset:9216
	v_fmac_f32_dpp v20, v137, v138 row_newbcast:12 row_mask:0xf bank_mask:0xf
	v_fmac_f32_dpp v21, v137, v138 row_newbcast:13 row_mask:0xf bank_mask:0xf
	ds_read_b64 v[98:99], v108 offset:49184
	v_fmac_f32_dpp v22, v137, v138 row_newbcast:14 row_mask:0xf bank_mask:0xf
	v_fmac_f32_dpp v23, v137, v138 row_newbcast:15 row_mask:0xf bank_mask:0xf
	s_waitcnt lgkmcnt(14)
	v_fmac_f32_dpp v8, v120, v32 row_newbcast:0 row_mask:0xf bank_mask:0xf
	v_fmac_f32_dpp v9, v120, v32 row_newbcast:1 row_mask:0xf bank_mask:0xf
	v_fmac_f32_dpp v10, v120, v32 row_newbcast:2 row_mask:0xf bank_mask:0xf
	v_fmac_f32_dpp v11, v120, v32 row_newbcast:3 row_mask:0xf bank_mask:0xf
	v_fmac_f32_dpp v12, v120, v32 row_newbcast:4 row_mask:0xf bank_mask:0xf
	v_fmac_f32_dpp v13, v120, v32 row_newbcast:5 row_mask:0xf bank_mask:0xf
	v_fmac_f32_dpp v14, v120, v32 row_newbcast:6 row_mask:0xf bank_mask:0xf
	v_fmac_f32_dpp v15, v120, v32 row_newbcast:7 row_mask:0xf bank_mask:0xf
	v_fmac_f32_dpp v16, v120, v32 row_newbcast:8 row_mask:0xf bank_mask:0xf
	v_fmac_f32_dpp v17, v120, v32 row_newbcast:9 row_mask:0xf bank_mask:0xf
	v_fmac_f32_dpp v18, v120, v32 row_newbcast:10 row_mask:0xf bank_mask:0xf
	v_fmac_f32_dpp v19, v120, v32 row_newbcast:11 row_mask:0xf bank_mask:0xf
	v_fmac_f32_dpp v20, v120, v32 row_newbcast:12 row_mask:0xf bank_mask:0xf
	v_fmac_f32_dpp v21, v120, v32 row_newbcast:13 row_mask:0xf bank_mask:0xf
	v_fmac_f32_dpp v22, v120, v32 row_newbcast:14 row_mask:0xf bank_mask:0xf
	v_fmac_f32_dpp v23, v120, v32 row_newbcast:15 row_mask:0xf bank_mask:0xf
	v_fma_f32 v109, -v32, v140, v33
	v_fma_f32 v109, v138, v141, v109
	ds_write_b32 v107, v109 offset:8704
	v_cvt_pk_bf16_f32 v24, v8, v9
	v_cvt_pk_bf16_f32 v25, v10, v11
	v_cvt_pk_bf16_f32 v26, v12, v13
	v_cvt_pk_bf16_f32 v27, v14, v15
	v_cvt_pk_bf16_f32 v28, v16, v17
	v_cvt_pk_bf16_f32 v29, v18, v19
	s_waitcnt lgkmcnt(10)
	v_mfma_f32_16x16x32_bf16 v[32:35], v[40:43], v[24:27], 0
	v_cvt_pk_bf16_f32 v30, v20, v21
	v_cvt_pk_bf16_f32 v31, v22, v23
	v_fmac_f32_dpp v8, v65, v66 row_newbcast:0 row_mask:0xf bank_mask:0xf
	v_fmac_f32_dpp v9, v65, v66 row_newbcast:1 row_mask:0xf bank_mask:0xf
	v_mfma_f32_16x16x32_bf16 v[32:35], v[44:47], v[28:31], v[32:35]
	v_fmac_f32_dpp v10, v65, v66 row_newbcast:2 row_mask:0xf bank_mask:0xf
	v_fmac_f32_dpp v11, v65, v66 row_newbcast:3 row_mask:0xf bank_mask:0xf
	ds_read_b128 v[112:115], v104 offset:1280
	v_fmac_f32_dpp v12, v65, v66 row_newbcast:4 row_mask:0xf bank_mask:0xf
	v_fmac_f32_dpp v13, v65, v66 row_newbcast:5 row_mask:0xf bank_mask:0xf
	ds_read_b128 v[116:119], v104 offset:1296
	v_fmac_f32_dpp v14, v65, v66 row_newbcast:6 row_mask:0xf bank_mask:0xf
	v_fmac_f32_dpp v15, v65, v66 row_newbcast:7 row_mask:0xf bank_mask:0xf
	ds_read_b32 v137, v105 offset:17664
	v_fmac_f32_dpp v16, v65, v66 row_newbcast:8 row_mask:0xf bank_mask:0xf
	v_fmac_f32_dpp v17, v65, v66 row_newbcast:9 row_mask:0xf bank_mask:0xf
	ds_read_b32 v138, v107 offset:1280
	v_fmac_f32_dpp v18, v65, v66 row_newbcast:10 row_mask:0xf bank_mask:0xf
	v_fmac_f32_dpp v19, v65, v66 row_newbcast:11 row_mask:0xf bank_mask:0xf
	ds_read_b32 v120, v105 offset:9472
	v_fmac_f32_dpp v20, v65, v66 row_newbcast:12 row_mask:0xf bank_mask:0xf
	v_fmac_f32_dpp v21, v65, v66 row_newbcast:13 row_mask:0xf bank_mask:0xf
	ds_read_b64 v[140:141], v108 offset:49192
	v_fmac_f32_dpp v22, v65, v66 row_newbcast:14 row_mask:0xf bank_mask:0xf
	v_fmac_f32_dpp v23, v65, v66 row_newbcast:15 row_mask:0xf bank_mask:0xf
	s_waitcnt lgkmcnt(14)
; __device__ __forceinline__ void phase_rwkv_scan(const Params& p, int l, const int tidx) {
;     ...
;       for (int s = 0; s < RTC; s++) {
;         const bf16x8 A0 = nA0, A1 = nA1;
;         const float wA[8] = {nw0.x, nw0.y, nw0.z, nw0.w, nw1.x, nw1.y, nw1.z, nw1.w};
;         const float wB[8] = {nw2.x, nw2.y, nw2.z, nw2.w, nw3.x, nw3.y, nw3.z, nw3.w};
;         const float kaA[8] = {nka0.x, nka0.y, nka0.z, nka0.w, nka1.x, nka1.y, nka1.z, nka1.w};
;         const float kaB[8] = {nka2.x, nka2.y, nka2.z, nka2.w, nka3.x, nka3.y, nka3.z, nka3.w};
;         const float kdA[8] = {nkd0.x, nkd0.y, nkd0.z, nkd0.w, nkd1.x, nkd1.y, nkd1.z, nkd1.w};
;         const float kdB[8] = {nkd2.x, nkd2.y, nkd2.z, nkd2.w, nkd3.x, nkd3.y, nkd3.z, nkd3.w};
;         const float v = nv;
;         float c1 = nc.x, c2 = nc.y;
;         asm volatile("" : "+v"(c1), "+v"(c2));
;         if (s + 1 < RTC) RW_LD(s + 1);
;         u32x4 pa = {pack2(Sa[0], Sa[1]), pack2(Sa[2], Sa[3]), pack2(Sa[4], Sa[5]), pack2(Sa[6], Sa[7])};
;         u32x4 pb = {pack2(Sb[0], Sb[1]), pack2(Sb[2], Sb[3]), pack2(Sb[4], Sb[5]), pack2(Sb[6], Sb[7])};
;         f32x4 acc = {0.f, 0.f, 0.f, 0.f};
;         acc = __builtin_amdgcn_mfma_f32_16x16x32_bf16(A0, __builtin_bit_cast(bf16x8, pa), acc, 0, 0, 0);
;         acc = __builtin_amdgcn_mfma_f32_16x16x32_bf16(A1, __builtin_bit_cast(bf16x8, pb), acc, 0, 0, 0);
;         float tA[8], tB[8];
; #pragma unroll
;         for (int c = 0; c < 8; c++) { tA[c] = Sa[c] * wA[c] + v * kdA[c]; tB[c] = Sb[c] * wB[c] + v * kdB[c]; }
;         const float sa = -acc[0];
;         const float yq = acc[1];
; #pragma unroll
;         for (int c = 0; c < 8; c++) { Sa[c] = tA[c] + sa * kaA[c]; Sb[c] = tB[c] + sa * kaB[c]; }
;         const float y = yq + sa * c1 + v * c2;
;         if (quad == 0) by[s * 64 + row] = y;
;       }
	v_fmac_f32_dpp v8, v48, v32 row_newbcast:0 row_mask:0xf bank_mask:0xf
	v_fmac_f32_dpp v9, v48, v32 row_newbcast:1 row_mask:0xf bank_mask:0xf
	v_fmac_f32_dpp v10, v48, v32 row_newbcast:2 row_mask:0xf bank_mask:0xf
	v_fmac_f32_dpp v11, v48, v32 row_newbcast:3 row_mask:0xf bank_mask:0xf
	v_fmac_f32_dpp v12, v48, v32 row_newbcast:4 row_mask:0xf bank_mask:0xf
	v_fmac_f32_dpp v13, v48, v32 row_newbcast:5 row_mask:0xf bank_mask:0xf
	v_fmac_f32_dpp v14, v48, v32 row_newbcast:6 row_mask:0xf bank_mask:0xf
	v_fmac_f32_dpp v15, v48, v32 row_newbcast:7 row_mask:0xf bank_mask:0xf
	v_fmac_f32_dpp v16, v48, v32 row_newbcast:8 row_mask:0xf bank_mask:0xf
	v_fmac_f32_dpp v17, v48, v32 row_newbcast:9 row_mask:0xf bank_mask:0xf
	v_fmac_f32_dpp v18, v48, v32 row_newbcast:10 row_mask:0xf bank_mask:0xf
	v_fmac_f32_dpp v19, v48, v32 row_newbcast:11 row_mask:0xf bank_mask:0xf
	v_fmac_f32_dpp v20, v48, v32 row_newbcast:12 row_mask:0xf bank_mask:0xf
	v_fmac_f32_dpp v21, v48, v32 row_newbcast:13 row_mask:0xf bank_mask:0xf
	v_fmac_f32_dpp v22, v48, v32 row_newbcast:14 row_mask:0xf bank_mask:0xf
	v_fmac_f32_dpp v23, v48, v32 row_newbcast:15 row_mask:0xf bank_mask:0xf
	v_fma_f32 v109, -v32, v68, v33
	v_fma_f32 v109, v66, v69, v109
	ds_write_b32 v107, v109 offset:8960
	v_cvt_pk_bf16_f32 v24, v8, v9
	v_cvt_pk_bf16_f32 v25, v10, v11
	v_cvt_pk_bf16_f32 v26, v12, v13
	v_cvt_pk_bf16_f32 v27, v14, v15
	v_cvt_pk_bf16_f32 v28, v16, v17
	v_cvt_pk_bf16_f32 v29, v18, v19
	s_waitcnt lgkmcnt(10)
	v_mfma_f32_16x16x32_bf16 v[32:35], v[70:73], v[24:27], 0
	v_cvt_pk_bf16_f32 v30, v20, v21
	v_cvt_pk_bf16_f32 v31, v22, v23
	v_fmac_f32_dpp v8, v95, v96 row_newbcast:0 row_mask:0xf bank_mask:0xf
	v_fmac_f32_dpp v9, v95, v96 row_newbcast:1 row_mask:0xf bank_mask:0xf
	v_mfma_f32_16x16x32_bf16 v[32:35], v[74:77], v[28:31], v[32:35]
	v_fmac_f32_dpp v10, v95, v96 row_newbcast:2 row_mask:0xf bank_mask:0xf
	v_fmac_f32_dpp v11, v95, v96 row_newbcast:3 row_mask:0xf bank_mask:0xf
	ds_read_b128 v[40:43], v104 offset:1536
	v_fmac_f32_dpp v12, v95, v96 row_newbcast:4 row_mask:0xf bank_mask:0xf
	v_fmac_f32_dpp v13, v95, v96 row_newbcast:5 row_mask:0xf bank_mask:0xf
	ds_read_b128 v[44:47], v104 offset:1552
	v_fmac_f32_dpp v14, v95, v96 row_newbcast:6 row_mask:0xf bank_mask:0xf
	v_fmac_f32_dpp v15, v95, v96 row_newbcast:7 row_mask:0xf bank_mask:0xf
	ds_read_b32 v65, v105 offset:17920
	v_fmac_f32_dpp v16, v95, v96 row_newbcast:8 row_mask:0xf bank_mask:0xf
	v_fmac_f32_dpp v17, v95, v96 row_newbcast:9 row_mask:0xf bank_mask:0xf
	ds_read_b32 v66, v107 offset:1536
	v_fmac_f32_dpp v18, v95, v96 row_newbcast:10 row_mask:0xf bank_mask:0xf
	v_fmac_f32_dpp v19, v95, v96 row_newbcast:11 row_mask:0xf bank_mask:0xf
	ds_read_b32 v48, v105 offset:9728
	v_fmac_f32_dpp v20, v95, v96 row_newbcast:12 row_mask:0xf bank_mask:0xf
	v_fmac_f32_dpp v21, v95, v96 row_newbcast:13 row_mask:0xf bank_mask:0xf
	ds_read_b64 v[68:69], v108 offset:49200
	v_fmac_f32_dpp v22, v95, v96 row_newbcast:14 row_mask:0xf bank_mask:0xf
	v_fmac_f32_dpp v23, v95, v96 row_newbcast:15 row_mask:0xf bank_mask:0xf
	s_waitcnt lgkmcnt(14)
	v_fmac_f32_dpp v8, v78, v32 row_newbcast:0 row_mask:0xf bank_mask:0xf
	v_fmac_f32_dpp v9, v78, v32 row_newbcast:1 row_mask:0xf bank_mask:0xf
	v_fmac_f32_dpp v10, v78, v32 row_newbcast:2 row_mask:0xf bank_mask:0xf
	v_fmac_f32_dpp v11, v78, v32 row_newbcast:3 row_mask:0xf bank_mask:0xf
	v_fmac_f32_dpp v12, v78, v32 row_newbcast:4 row_mask:0xf bank_mask:0xf
	v_fmac_f32_dpp v13, v78, v32 row_newbcast:5 row_mask:0xf bank_mask:0xf
	v_fmac_f32_dpp v14, v78, v32 row_newbcast:6 row_mask:0xf bank_mask:0xf
	v_fmac_f32_dpp v15, v78, v32 row_newbcast:7 row_mask:0xf bank_mask:0xf
	v_fmac_f32_dpp v16, v78, v32 row_newbcast:8 row_mask:0xf bank_mask:0xf
	v_fmac_f32_dpp v17, v78, v32 row_newbcast:9 row_mask:0xf bank_mask:0xf
	v_fmac_f32_dpp v18, v78, v32 row_newbcast:10 row_mask:0xf bank_mask:0xf
	v_fmac_f32_dpp v19, v78, v32 row_newbcast:11 row_mask:0xf bank_mask:0xf
	v_fmac_f32_dpp v20, v78, v32 row_newbcast:12 row_mask:0xf bank_mask:0xf
	v_fmac_f32_dpp v21, v78, v32 row_newbcast:13 row_mask:0xf bank_mask:0xf
	v_fmac_f32_dpp v22, v78, v32 row_newbcast:14 row_mask:0xf bank_mask:0xf
	v_fmac_f32_dpp v23, v78, v32 row_newbcast:15 row_mask:0xf bank_mask:0xf
	v_fma_f32 v109, -v32, v98, v33
	v_fma_f32 v109, v96, v99, v109
	ds_write_b32 v107, v109 offset:9216
	v_cvt_pk_bf16_f32 v24, v8, v9
	v_cvt_pk_bf16_f32 v25, v10, v11
	v_cvt_pk_bf16_f32 v26, v12, v13
	v_cvt_pk_bf16_f32 v27, v14, v15
	v_cvt_pk_bf16_f32 v28, v16, v17
	v_cvt_pk_bf16_f32 v29, v18, v19
	s_waitcnt lgkmcnt(10)
	v_mfma_f32_16x16x32_bf16 v[32:35], v[112:115], v[24:27], 0
	v_cvt_pk_bf16_f32 v30, v20, v21
	v_cvt_pk_bf16_f32 v31, v22, v23
	v_fmac_f32_dpp v8, v137, v138 row_newbcast:0 row_mask:0xf bank_mask:0xf
	v_fmac_f32_dpp v9, v137, v138 row_newbcast:1 row_mask:0xf bank_mask:0xf
	v_mfma_f32_16x16x32_bf16 v[32:35], v[116:119], v[28:31], v[32:35]
	v_fmac_f32_dpp v10, v137, v138 row_newbcast:2 row_mask:0xf bank_mask:0xf
	v_fmac_f32_dpp v11, v137, v138 row_newbcast:3 row_mask:0xf bank_mask:0xf
	ds_read_b128 v[70:73], v104 offset:1792
	v_fmac_f32_dpp v12, v137, v138 row_newbcast:4 row_mask:0xf bank_mask:0xf
	v_fmac_f32_dpp v13, v137, v138 row_newbcast:5 row_mask:0xf bank_mask:0xf
	ds_read_b128 v[74:77], v104 offset:1808
	v_fmac_f32_dpp v14, v137, v138 row_newbcast:6 row_mask:0xf bank_mask:0xf
	v_fmac_f32_dpp v15, v137, v138 row_newbcast:7 row_mask:0xf bank_mask:0xf
	ds_read_b32 v95, v105 offset:18176
	v_fmac_f32_dpp v16, v137, v138 row_newbcast:8 row_mask:0xf bank_mask:0xf
	v_fmac_f32_dpp v17, v137, v138 row_newbcast:9 row_mask:0xf bank_mask:0xf
	ds_read_b32 v96, v107 offset:1792
	v_fmac_f32_dpp v18, v137, v138 row_newbcast:10 row_mask:0xf bank_mask:0xf
	v_fmac_f32_dpp v19, v137, v138 row_newbcast:11 row_mask:0xf bank_mask:0xf
	ds_read_b32 v94, v105 offset:1792
	v_fmac_f32_dpp v20, v137, v138 row_newbcast:12 row_mask:0xf bank_mask:0xf
	v_fmac_f32_dpp v21, v137, v138 row_newbcast:13 row_mask:0xf bank_mask:0xf
	ds_read_b32 v78, v105 offset:9984
	v_fmac_f32_dpp v22, v137, v138 row_newbcast:14 row_mask:0xf bank_mask:0xf
	v_fmac_f32_dpp v23, v137, v138 row_newbcast:15 row_mask:0xf bank_mask:0xf
	ds_read_b64 v[98:99], v108 offset:49208
	s_waitcnt lgkmcnt(15)
; __device__ __forceinline__ void phase_rwkv_scan(const Params& p, int l, const int tidx) {
;     ...
;       for (int s = 0; s < RTC; s++) {
;         const bf16x8 A0 = nA0, A1 = nA1;
;         const float wA[8] = {nw0.x, nw0.y, nw0.z, nw0.w, nw1.x, nw1.y, nw1.z, nw1.w};
;         const float wB[8] = {nw2.x, nw2.y, nw2.z, nw2.w, nw3.x, nw3.y, nw3.z, nw3.w};
;         const float kaA[8] = {nka0.x, nka0.y, nka0.z, nka0.w, nka1.x, nka1.y, nka1.z, nka1.w};
;         const float kaB[8] = {nka2.x, nka2.y, nka2.z, nka2.w, nka3.x, nka3.y, nka3.z, nka3.w};
;         const float kdA[8] = {nkd0.x, nkd0.y, nkd0.z, nkd0.w, nkd1.x, nkd1.y, nkd1.z, nkd1.w};
;         const float kdB[8] = {nkd2.x, nkd2.y, nkd2.z, nkd2.w, nkd3.x, nkd3.y, nkd3.z, nkd3.w};
;         const float v = nv;
;         float c1 = nc.x, c2 = nc.y;
;         asm volatile("" : "+v"(c1), "+v"(c2));
;         if (s + 1 < RTC) RW_LD(s + 1);
;         u32x4 pa = {pack2(Sa[0], Sa[1]), pack2(Sa[2], Sa[3]), pack2(Sa[4], Sa[5]), pack2(Sa[6], Sa[7])};
;         u32x4 pb = {pack2(Sb[0], Sb[1]), pack2(Sb[2], Sb[3]), pack2(Sb[4], Sb[5]), pack2(Sb[6], Sb[7])};
;         f32x4 acc = {0.f, 0.f, 0.f, 0.f};
;         acc = __builtin_amdgcn_mfma_f32_16x16x32_bf16(A0, __builtin_bit_cast(bf16x8, pa), acc, 0, 0, 0);
;         acc = __builtin_amdgcn_mfma_f32_16x16x32_bf16(A1, __builtin_bit_cast(bf16x8, pb), acc, 0, 0, 0);
;         float tA[8], tB[8];
; #pragma unroll
;         for (int c = 0; c < 8; c++) { tA[c] = Sa[c] * wA[c] + v * kdA[c]; tB[c] = Sb[c] * wB[c] + v * kdB[c]; }
;         const float sa = -acc[0];
;         const float yq = acc[1];
; #pragma unroll
;         for (int c = 0; c < 8; c++) { Sa[c] = tA[c] + sa * kaA[c]; Sb[c] = tB[c] + sa * kaB[c]; }
;         const float y = yq + sa * c1 + v * c2;
;         if (quad == 0) by[s * 64 + row] = y;
;       }
	v_fmac_f32_dpp v8, v120, v32 row_newbcast:0 row_mask:0xf bank_mask:0xf
	v_fmac_f32_dpp v9, v120, v32 row_newbcast:1 row_mask:0xf bank_mask:0xf
	v_fmac_f32_dpp v10, v120, v32 row_newbcast:2 row_mask:0xf bank_mask:0xf
	v_fmac_f32_dpp v11, v120, v32 row_newbcast:3 row_mask:0xf bank_mask:0xf
	v_fmac_f32_dpp v12, v120, v32 row_newbcast:4 row_mask:0xf bank_mask:0xf
	v_fmac_f32_dpp v13, v120, v32 row_newbcast:5 row_mask:0xf bank_mask:0xf
	v_fmac_f32_dpp v14, v120, v32 row_newbcast:6 row_mask:0xf bank_mask:0xf
	v_fmac_f32_dpp v15, v120, v32 row_newbcast:7 row_mask:0xf bank_mask:0xf
	v_fmac_f32_dpp v16, v120, v32 row_newbcast:8 row_mask:0xf bank_mask:0xf
	v_fmac_f32_dpp v17, v120, v32 row_newbcast:9 row_mask:0xf bank_mask:0xf
	v_fmac_f32_dpp v18, v120, v32 row_newbcast:10 row_mask:0xf bank_mask:0xf
	v_fmac_f32_dpp v19, v120, v32 row_newbcast:11 row_mask:0xf bank_mask:0xf
	v_fmac_f32_dpp v20, v120, v32 row_newbcast:12 row_mask:0xf bank_mask:0xf
	v_fmac_f32_dpp v21, v120, v32 row_newbcast:13 row_mask:0xf bank_mask:0xf
	v_fmac_f32_dpp v22, v120, v32 row_newbcast:14 row_mask:0xf bank_mask:0xf
	v_fmac_f32_dpp v23, v120, v32 row_newbcast:15 row_mask:0xf bank_mask:0xf
	v_fma_f32 v109, -v32, v140, v33
	v_fma_f32 v109, v138, v141, v109
	ds_write_b32 v107, v109 offset:9472
	v_cvt_pk_bf16_f32 v24, v8, v9
	v_cvt_pk_bf16_f32 v25, v10, v11
	v_cvt_pk_bf16_f32 v26, v12, v13
	v_cvt_pk_bf16_f32 v27, v14, v15
	v_cvt_pk_bf16_f32 v28, v16, v17
	v_cvt_pk_bf16_f32 v29, v18, v19
	s_waitcnt lgkmcnt(11)
	v_mfma_f32_16x16x32_bf16 v[32:35], v[40:43], v[24:27], 0
	v_cvt_pk_bf16_f32 v30, v20, v21
	v_cvt_pk_bf16_f32 v31, v22, v23
	v_fmac_f32_dpp v8, v65, v66 row_newbcast:0 row_mask:0xf bank_mask:0xf
	v_fmac_f32_dpp v9, v65, v66 row_newbcast:1 row_mask:0xf bank_mask:0xf
	v_mfma_f32_16x16x32_bf16 v[32:35], v[44:47], v[28:31], v[32:35]
	v_fmac_f32_dpp v10, v65, v66 row_newbcast:2 row_mask:0xf bank_mask:0xf
	v_fmac_f32_dpp v11, v65, v66 row_newbcast:3 row_mask:0xf bank_mask:0xf
	ds_read_b128 v[112:115], v104 offset:2048
	v_fmac_f32_dpp v12, v65, v66 row_newbcast:4 row_mask:0xf bank_mask:0xf
	v_fmac_f32_dpp v13, v65, v66 row_newbcast:5 row_mask:0xf bank_mask:0xf
	ds_read_b128 v[116:119], v104 offset:2064
	v_fmac_f32_dpp v14, v65, v66 row_newbcast:6 row_mask:0xf bank_mask:0xf
	v_fmac_f32_dpp v15, v65, v66 row_newbcast:7 row_mask:0xf bank_mask:0xf
	ds_read_b32 v137, v105 offset:18432
	v_fmac_f32_dpp v16, v65, v66 row_newbcast:8 row_mask:0xf bank_mask:0xf
	v_fmac_f32_dpp v17, v65, v66 row_newbcast:9 row_mask:0xf bank_mask:0xf
	ds_read_b32 v138, v107 offset:2048
	v_fmac_f32_dpp v18, v65, v66 row_newbcast:10 row_mask:0xf bank_mask:0xf
	v_fmac_f32_dpp v19, v65, v66 row_newbcast:11 row_mask:0xf bank_mask:0xf
	ds_read_b32 v120, v105 offset:10240
	v_fmac_f32_dpp v20, v65, v66 row_newbcast:12 row_mask:0xf bank_mask:0xf
	v_fmac_f32_dpp v21, v65, v66 row_newbcast:13 row_mask:0xf bank_mask:0xf
	ds_read_b64 v[140:141], v108 offset:49216
	v_fmac_f32_dpp v22, v65, v66 row_newbcast:14 row_mask:0xf bank_mask:0xf
	v_fmac_f32_dpp v23, v65, v66 row_newbcast:15 row_mask:0xf bank_mask:0xf
	s_waitcnt lgkmcnt(15)
	v_fmac_f32_dpp v8, v48, v32 row_newbcast:0 row_mask:0xf bank_mask:0xf
	v_fmac_f32_dpp v9, v48, v32 row_newbcast:1 row_mask:0xf bank_mask:0xf
	v_fmac_f32_dpp v10, v48, v32 row_newbcast:2 row_mask:0xf bank_mask:0xf
	v_fmac_f32_dpp v11, v48, v32 row_newbcast:3 row_mask:0xf bank_mask:0xf
	v_fmac_f32_dpp v12, v48, v32 row_newbcast:4 row_mask:0xf bank_mask:0xf
	v_fmac_f32_dpp v13, v48, v32 row_newbcast:5 row_mask:0xf bank_mask:0xf
	v_fmac_f32_dpp v14, v48, v32 row_newbcast:6 row_mask:0xf bank_mask:0xf
	v_fmac_f32_dpp v15, v48, v32 row_newbcast:7 row_mask:0xf bank_mask:0xf
	v_fmac_f32_dpp v16, v48, v32 row_newbcast:8 row_mask:0xf bank_mask:0xf
	v_fmac_f32_dpp v17, v48, v32 row_newbcast:9 row_mask:0xf bank_mask:0xf
	v_fmac_f32_dpp v18, v48, v32 row_newbcast:10 row_mask:0xf bank_mask:0xf
	v_fmac_f32_dpp v19, v48, v32 row_newbcast:11 row_mask:0xf bank_mask:0xf
	v_fmac_f32_dpp v20, v48, v32 row_newbcast:12 row_mask:0xf bank_mask:0xf
	v_fmac_f32_dpp v21, v48, v32 row_newbcast:13 row_mask:0xf bank_mask:0xf
	v_fmac_f32_dpp v22, v48, v32 row_newbcast:14 row_mask:0xf bank_mask:0xf
	v_fmac_f32_dpp v23, v48, v32 row_newbcast:15 row_mask:0xf bank_mask:0xf
	v_fma_f32 v109, -v32, v68, v33
	v_fma_f32 v109, v66, v69, v109
	ds_write_b32 v107, v109 offset:9728
	v_cvt_pk_bf16_f32 v24, v8, v9
	v_cvt_pk_bf16_f32 v25, v10, v11
	v_cvt_pk_bf16_f32 v26, v12, v13
	v_cvt_pk_bf16_f32 v27, v14, v15
	v_cvt_pk_bf16_f32 v28, v16, v17
	v_cvt_pk_bf16_f32 v29, v18, v19
	s_waitcnt lgkmcnt(11)
	v_mfma_f32_16x16x32_bf16 v[32:35], v[70:73], v[24:27], 0
	v_cvt_pk_bf16_f32 v30, v20, v21
	v_cvt_pk_bf16_f32 v31, v22, v23
	v_fmac_f32_dpp v8, v95, v96 row_newbcast:0 row_mask:0xf bank_mask:0xf
	v_fmac_f32_dpp v9, v95, v96 row_newbcast:1 row_mask:0xf bank_mask:0xf
	v_mfma_f32_16x16x32_bf16 v[32:35], v[74:77], v[28:31], v[32:35]
	v_fmac_f32_dpp v10, v95, v96 row_newbcast:2 row_mask:0xf bank_mask:0xf
	v_fmac_f32_dpp v11, v95, v96 row_newbcast:3 row_mask:0xf bank_mask:0xf
	ds_read_b128 v[40:43], v104 offset:2304
	v_fmac_f32_dpp v12, v95, v96 row_newbcast:4 row_mask:0xf bank_mask:0xf
	v_fmac_f32_dpp v13, v95, v96 row_newbcast:5 row_mask:0xf bank_mask:0xf
	ds_read_b128 v[44:47], v104 offset:2320
	v_fmac_f32_dpp v14, v95, v96 row_newbcast:6 row_mask:0xf bank_mask:0xf
	v_fmac_f32_dpp v15, v95, v96 row_newbcast:7 row_mask:0xf bank_mask:0xf
	ds_read_b32 v65, v105 offset:18688
	v_fmac_f32_dpp v16, v95, v96 row_newbcast:8 row_mask:0xf bank_mask:0xf
	v_fmac_f32_dpp v17, v95, v96 row_newbcast:9 row_mask:0xf bank_mask:0xf
	ds_read_b32 v66, v107 offset:2304
	v_fmac_f32_dpp v18, v95, v96 row_newbcast:10 row_mask:0xf bank_mask:0xf
	v_fmac_f32_dpp v19, v95, v96 row_newbcast:11 row_mask:0xf bank_mask:0xf
	ds_read_b32 v48, v105 offset:10496
	v_fmac_f32_dpp v20, v95, v96 row_newbcast:12 row_mask:0xf bank_mask:0xf
	v_fmac_f32_dpp v21, v95, v96 row_newbcast:13 row_mask:0xf bank_mask:0xf
	ds_read_b64 v[68:69], v108 offset:49224
	v_fmac_f32_dpp v22, v95, v96 row_newbcast:14 row_mask:0xf bank_mask:0xf
	v_fmac_f32_dpp v23, v95, v96 row_newbcast:15 row_mask:0xf bank_mask:0xf
	s_waitcnt lgkmcnt(14)
; __device__ __forceinline__ void phase_rwkv_scan(const Params& p, int l, const int tidx) {
;     ...
;       for (int s = 0; s < RTC; s++) {
;         const bf16x8 A0 = nA0, A1 = nA1;
;         const float wA[8] = {nw0.x, nw0.y, nw0.z, nw0.w, nw1.x, nw1.y, nw1.z, nw1.w};
;         const float wB[8] = {nw2.x, nw2.y, nw2.z, nw2.w, nw3.x, nw3.y, nw3.z, nw3.w};
;         const float kaA[8] = {nka0.x, nka0.y, nka0.z, nka0.w, nka1.x, nka1.y, nka1.z, nka1.w};
;         const float kaB[8] = {nka2.x, nka2.y, nka2.z, nka2.w, nka3.x, nka3.y, nka3.z, nka3.w};
;         const float kdA[8] = {nkd0.x, nkd0.y, nkd0.z, nkd0.w, nkd1.x, nkd1.y, nkd1.z, nkd1.w};
;         const float kdB[8] = {nkd2.x, nkd2.y, nkd2.z, nkd2.w, nkd3.x, nkd3.y, nkd3.z, nkd3.w};
;         const float v = nv;
;         float c1 = nc.x, c2 = nc.y;
;         asm volatile("" : "+v"(c1), "+v"(c2));
;         if (s + 1 < RTC) RW_LD(s + 1);
;         u32x4 pa = {pack2(Sa[0], Sa[1]), pack2(Sa[2], Sa[3]), pack2(Sa[4], Sa[5]), pack2(Sa[6], Sa[7])};
;         u32x4 pb = {pack2(Sb[0], Sb[1]), pack2(Sb[2], Sb[3]), pack2(Sb[4], Sb[5]), pack2(Sb[6], Sb[7])};
;         f32x4 acc = {0.f, 0.f, 0.f, 0.f};
;         acc = __builtin_amdgcn_mfma_f32_16x16x32_bf16(A0, __builtin_bit_cast(bf16x8, pa), acc, 0, 0, 0);
;         acc = __builtin_amdgcn_mfma_f32_16x16x32_bf16(A1, __builtin_bit_cast(bf16x8, pb), acc, 0, 0, 0);
;         float tA[8], tB[8];
; #pragma unroll
;         for (int c = 0; c < 8; c++) { tA[c] = Sa[c] * wA[c] + v * kdA[c]; tB[c] = Sb[c] * wB[c] + v * kdB[c]; }
;         const float sa = -acc[0];
;         const float yq = acc[1];
; #pragma unroll
;         for (int c = 0; c < 8; c++) { Sa[c] = tA[c] + sa * kaA[c]; Sb[c] = tB[c] + sa * kaB[c]; }
;         const float y = yq + sa * c1 + v * c2;
;         if (quad == 0) by[s * 64 + row] = y;
;       }
	v_fmac_f32_dpp v8, v78, v32 row_newbcast:0 row_mask:0xf bank_mask:0xf
	v_fmac_f32_dpp v9, v78, v32 row_newbcast:1 row_mask:0xf bank_mask:0xf
	v_fmac_f32_dpp v10, v78, v32 row_newbcast:2 row_mask:0xf bank_mask:0xf
	v_fmac_f32_dpp v11, v78, v32 row_newbcast:3 row_mask:0xf bank_mask:0xf
	v_fmac_f32_dpp v12, v78, v32 row_newbcast:4 row_mask:0xf bank_mask:0xf
	v_fmac_f32_dpp v13, v78, v32 row_newbcast:5 row_mask:0xf bank_mask:0xf
	v_fmac_f32_dpp v14, v78, v32 row_newbcast:6 row_mask:0xf bank_mask:0xf
	v_fmac_f32_dpp v15, v78, v32 row_newbcast:7 row_mask:0xf bank_mask:0xf
	v_fmac_f32_dpp v16, v78, v32 row_newbcast:8 row_mask:0xf bank_mask:0xf
	v_fmac_f32_dpp v17, v78, v32 row_newbcast:9 row_mask:0xf bank_mask:0xf
	v_fmac_f32_dpp v18, v78, v32 row_newbcast:10 row_mask:0xf bank_mask:0xf
	v_fmac_f32_dpp v19, v78, v32 row_newbcast:11 row_mask:0xf bank_mask:0xf
	v_fmac_f32_dpp v20, v78, v32 row_newbcast:12 row_mask:0xf bank_mask:0xf
	v_fmac_f32_dpp v21, v78, v32 row_newbcast:13 row_mask:0xf bank_mask:0xf
	v_fmac_f32_dpp v22, v78, v32 row_newbcast:14 row_mask:0xf bank_mask:0xf
	v_fmac_f32_dpp v23, v78, v32 row_newbcast:15 row_mask:0xf bank_mask:0xf
	v_fma_f32 v109, -v32, v98, v33
	v_fma_f32 v109, v96, v99, v109
	v_mul_f32_dpp v8, v94, v8 row_newbcast:0 row_mask:0xf bank_mask:0xf
	v_mul_f32_dpp v9, v94, v9 row_newbcast:1 row_mask:0xf bank_mask:0xf
	v_mul_f32_dpp v10, v94, v10 row_newbcast:2 row_mask:0xf bank_mask:0xf
	v_mul_f32_dpp v11, v94, v11 row_newbcast:3 row_mask:0xf bank_mask:0xf
	v_mul_f32_dpp v12, v94, v12 row_newbcast:4 row_mask:0xf bank_mask:0xf
	v_mul_f32_dpp v13, v94, v13 row_newbcast:5 row_mask:0xf bank_mask:0xf
	v_mul_f32_dpp v14, v94, v14 row_newbcast:6 row_mask:0xf bank_mask:0xf
	v_mul_f32_dpp v15, v94, v15 row_newbcast:7 row_mask:0xf bank_mask:0xf
	v_mul_f32_dpp v16, v94, v16 row_newbcast:8 row_mask:0xf bank_mask:0xf
	v_mul_f32_dpp v17, v94, v17 row_newbcast:9 row_mask:0xf bank_mask:0xf
	v_mul_f32_dpp v18, v94, v18 row_newbcast:10 row_mask:0xf bank_mask:0xf
	v_mul_f32_dpp v19, v94, v19 row_newbcast:11 row_mask:0xf bank_mask:0xf
	v_mul_f32_dpp v20, v94, v20 row_newbcast:12 row_mask:0xf bank_mask:0xf
	v_mul_f32_dpp v21, v94, v21 row_newbcast:13 row_mask:0xf bank_mask:0xf
	v_mul_f32_dpp v22, v94, v22 row_newbcast:14 row_mask:0xf bank_mask:0xf
	v_mul_f32_dpp v23, v94, v23 row_newbcast:15 row_mask:0xf bank_mask:0xf
	ds_write_b32 v107, v109 offset:9984
	v_cvt_pk_bf16_f32 v24, v8, v9
	v_cvt_pk_bf16_f32 v25, v10, v11
	v_cvt_pk_bf16_f32 v26, v12, v13
	v_cvt_pk_bf16_f32 v27, v14, v15
	v_cvt_pk_bf16_f32 v28, v16, v17
	v_cvt_pk_bf16_f32 v29, v18, v19
	s_waitcnt lgkmcnt(10)
	v_mfma_f32_16x16x32_bf16 v[32:35], v[112:115], v[24:27], 0
	v_cvt_pk_bf16_f32 v30, v20, v21
	v_cvt_pk_bf16_f32 v31, v22, v23
	v_fmac_f32_dpp v8, v137, v138 row_newbcast:0 row_mask:0xf bank_mask:0xf
	v_fmac_f32_dpp v9, v137, v138 row_newbcast:1 row_mask:0xf bank_mask:0xf
	v_mfma_f32_16x16x32_bf16 v[32:35], v[116:119], v[28:31], v[32:35]
	v_fmac_f32_dpp v10, v137, v138 row_newbcast:2 row_mask:0xf bank_mask:0xf
	v_fmac_f32_dpp v11, v137, v138 row_newbcast:3 row_mask:0xf bank_mask:0xf
	ds_read_b128 v[70:73], v104 offset:2560
	v_fmac_f32_dpp v12, v137, v138 row_newbcast:4 row_mask:0xf bank_mask:0xf
	v_fmac_f32_dpp v13, v137, v138 row_newbcast:5 row_mask:0xf bank_mask:0xf
	ds_read_b128 v[74:77], v104 offset:2576
	v_fmac_f32_dpp v14, v137, v138 row_newbcast:6 row_mask:0xf bank_mask:0xf
	v_fmac_f32_dpp v15, v137, v138 row_newbcast:7 row_mask:0xf bank_mask:0xf
	ds_read_b32 v95, v105 offset:18944
	v_fmac_f32_dpp v16, v137, v138 row_newbcast:8 row_mask:0xf bank_mask:0xf
	v_fmac_f32_dpp v17, v137, v138 row_newbcast:9 row_mask:0xf bank_mask:0xf
	ds_read_b32 v96, v107 offset:2560
	v_fmac_f32_dpp v18, v137, v138 row_newbcast:10 row_mask:0xf bank_mask:0xf
	v_fmac_f32_dpp v19, v137, v138 row_newbcast:11 row_mask:0xf bank_mask:0xf
	ds_read_b32 v78, v105 offset:10752
	v_fmac_f32_dpp v20, v137, v138 row_newbcast:12 row_mask:0xf bank_mask:0xf
	v_fmac_f32_dpp v21, v137, v138 row_newbcast:13 row_mask:0xf bank_mask:0xf
	ds_read_b64 v[98:99], v108 offset:49232
	v_fmac_f32_dpp v22, v137, v138 row_newbcast:14 row_mask:0xf bank_mask:0xf
	v_fmac_f32_dpp v23, v137, v138 row_newbcast:15 row_mask:0xf bank_mask:0xf
	s_waitcnt lgkmcnt(14)
	v_fmac_f32_dpp v8, v120, v32 row_newbcast:0 row_mask:0xf bank_mask:0xf
	v_fmac_f32_dpp v9, v120, v32 row_newbcast:1 row_mask:0xf bank_mask:0xf
	v_fmac_f32_dpp v10, v120, v32 row_newbcast:2 row_mask:0xf bank_mask:0xf
	v_fmac_f32_dpp v11, v120, v32 row_newbcast:3 row_mask:0xf bank_mask:0xf
	v_fmac_f32_dpp v12, v120, v32 row_newbcast:4 row_mask:0xf bank_mask:0xf
	v_fmac_f32_dpp v13, v120, v32 row_newbcast:5 row_mask:0xf bank_mask:0xf
	v_fmac_f32_dpp v14, v120, v32 row_newbcast:6 row_mask:0xf bank_mask:0xf
	v_fmac_f32_dpp v15, v120, v32 row_newbcast:7 row_mask:0xf bank_mask:0xf
	v_fmac_f32_dpp v16, v120, v32 row_newbcast:8 row_mask:0xf bank_mask:0xf
	v_fmac_f32_dpp v17, v120, v32 row_newbcast:9 row_mask:0xf bank_mask:0xf
	v_fmac_f32_dpp v18, v120, v32 row_newbcast:10 row_mask:0xf bank_mask:0xf
	v_fmac_f32_dpp v19, v120, v32 row_newbcast:11 row_mask:0xf bank_mask:0xf
	v_fmac_f32_dpp v20, v120, v32 row_newbcast:12 row_mask:0xf bank_mask:0xf
	v_fmac_f32_dpp v21, v120, v32 row_newbcast:13 row_mask:0xf bank_mask:0xf
	v_fmac_f32_dpp v22, v120, v32 row_newbcast:14 row_mask:0xf bank_mask:0xf
	v_fmac_f32_dpp v23, v120, v32 row_newbcast:15 row_mask:0xf bank_mask:0xf
	v_fma_f32 v109, -v32, v140, v33
	v_fma_f32 v109, v138, v141, v109
	ds_write_b32 v107, v109 offset:10240
	v_cvt_pk_bf16_f32 v24, v8, v9
	v_cvt_pk_bf16_f32 v25, v10, v11
	v_cvt_pk_bf16_f32 v26, v12, v13
	v_cvt_pk_bf16_f32 v27, v14, v15
	v_cvt_pk_bf16_f32 v28, v16, v17
	v_cvt_pk_bf16_f32 v29, v18, v19
	s_waitcnt lgkmcnt(10)
; __device__ __forceinline__ void phase_rwkv_scan(const Params& p, int l, const int tidx) {
;     ...
;       for (int s = 0; s < RTC; s++) {
;         const bf16x8 A0 = nA0, A1 = nA1;
;         const float wA[8] = {nw0.x, nw0.y, nw0.z, nw0.w, nw1.x, nw1.y, nw1.z, nw1.w};
;         const float wB[8] = {nw2.x, nw2.y, nw2.z, nw2.w, nw3.x, nw3.y, nw3.z, nw3.w};
;         const float kaA[8] = {nka0.x, nka0.y, nka0.z, nka0.w, nka1.x, nka1.y, nka1.z, nka1.w};
;         const float kaB[8] = {nka2.x, nka2.y, nka2.z, nka2.w, nka3.x, nka3.y, nka3.z, nka3.w};
;         const float kdA[8] = {nkd0.x, nkd0.y, nkd0.z, nkd0.w, nkd1.x, nkd1.y, nkd1.z, nkd1.w};
;         const float kdB[8] = {nkd2.x, nkd2.y, nkd2.z, nkd2.w, nkd3.x, nkd3.y, nkd3.z, nkd3.w};
;         const float v = nv;
;         float c1 = nc.x, c2 = nc.y;
;         asm volatile("" : "+v"(c1), "+v"(c2));
;         if (s + 1 < RTC) RW_LD(s + 1);
;         u32x4 pa = {pack2(Sa[0], Sa[1]), pack2(Sa[2], Sa[3]), pack2(Sa[4], Sa[5]), pack2(Sa[6], Sa[7])};
;         u32x4 pb = {pack2(Sb[0], Sb[1]), pack2(Sb[2], Sb[3]), pack2(Sb[4], Sb[5]), pack2(Sb[6], Sb[7])};
;         f32x4 acc = {0.f, 0.f, 0.f, 0.f};
;         acc = __builtin_amdgcn_mfma_f32_16x16x32_bf16(A0, __builtin_bit_cast(bf16x8, pa), acc, 0, 0, 0);
;         acc = __builtin_amdgcn_mfma_f32_16x16x32_bf16(A1, __builtin_bit_cast(bf16x8, pb), acc, 0, 0, 0);
;         float tA[8], tB[8];
; #pragma unroll
;         for (int c = 0; c < 8; c++) { tA[c] = Sa[c] * wA[c] + v * kdA[c]; tB[c] = Sb[c] * wB[c] + v * kdB[c]; }
;         const float sa = -acc[0];
;         const float yq = acc[1];
; #pragma unroll
;         for (int c = 0; c < 8; c++) { Sa[c] = tA[c] + sa * kaA[c]; Sb[c] = tB[c] + sa * kaB[c]; }
;         const float y = yq + sa * c1 + v * c2;
;         if (quad == 0) by[s * 64 + row] = y;
;       }
	v_mfma_f32_16x16x32_bf16 v[32:35], v[40:43], v[24:27], 0
	v_cvt_pk_bf16_f32 v30, v20, v21
	v_cvt_pk_bf16_f32 v31, v22, v23
	v_fmac_f32_dpp v8, v65, v66 row_newbcast:0 row_mask:0xf bank_mask:0xf
	v_fmac_f32_dpp v9, v65, v66 row_newbcast:1 row_mask:0xf bank_mask:0xf
	v_mfma_f32_16x16x32_bf16 v[32:35], v[44:47], v[28:31], v[32:35]
	v_fmac_f32_dpp v10, v65, v66 row_newbcast:2 row_mask:0xf bank_mask:0xf
	v_fmac_f32_dpp v11, v65, v66 row_newbcast:3 row_mask:0xf bank_mask:0xf
	ds_read_b128 v[112:115], v104 offset:2816
	v_fmac_f32_dpp v12, v65, v66 row_newbcast:4 row_mask:0xf bank_mask:0xf
	v_fmac_f32_dpp v13, v65, v66 row_newbcast:5 row_mask:0xf bank_mask:0xf
	ds_read_b128 v[116:119], v104 offset:2832
	v_fmac_f32_dpp v14, v65, v66 row_newbcast:6 row_mask:0xf bank_mask:0xf
	v_fmac_f32_dpp v15, v65, v66 row_newbcast:7 row_mask:0xf bank_mask:0xf
	ds_read_b32 v137, v105 offset:19200
	v_fmac_f32_dpp v16, v65, v66 row_newbcast:8 row_mask:0xf bank_mask:0xf
	v_fmac_f32_dpp v17, v65, v66 row_newbcast:9 row_mask:0xf bank_mask:0xf
	ds_read_b32 v138, v107 offset:2816
	v_fmac_f32_dpp v18, v65, v66 row_newbcast:10 row_mask:0xf bank_mask:0xf
	v_fmac_f32_dpp v19, v65, v66 row_newbcast:11 row_mask:0xf bank_mask:0xf
	ds_read_b32 v120, v105 offset:11008
	v_fmac_f32_dpp v20, v65, v66 row_newbcast:12 row_mask:0xf bank_mask:0xf
	v_fmac_f32_dpp v21, v65, v66 row_newbcast:13 row_mask:0xf bank_mask:0xf
	ds_read_b64 v[140:141], v108 offset:49240
	v_fmac_f32_dpp v22, v65, v66 row_newbcast:14 row_mask:0xf bank_mask:0xf
	v_fmac_f32_dpp v23, v65, v66 row_newbcast:15 row_mask:0xf bank_mask:0xf
	s_waitcnt lgkmcnt(14)
	v_fmac_f32_dpp v8, v48, v32 row_newbcast:0 row_mask:0xf bank_mask:0xf
	v_fmac_f32_dpp v9, v48, v32 row_newbcast:1 row_mask:0xf bank_mask:0xf
	v_fmac_f32_dpp v10, v48, v32 row_newbcast:2 row_mask:0xf bank_mask:0xf
	v_fmac_f32_dpp v11, v48, v32 row_newbcast:3 row_mask:0xf bank_mask:0xf
	v_fmac_f32_dpp v12, v48, v32 row_newbcast:4 row_mask:0xf bank_mask:0xf
	v_fmac_f32_dpp v13, v48, v32 row_newbcast:5 row_mask:0xf bank_mask:0xf
	v_fmac_f32_dpp v14, v48, v32 row_newbcast:6 row_mask:0xf bank_mask:0xf
	v_fmac_f32_dpp v15, v48, v32 row_newbcast:7 row_mask:0xf bank_mask:0xf
	v_fmac_f32_dpp v16, v48, v32 row_newbcast:8 row_mask:0xf bank_mask:0xf
	v_fmac_f32_dpp v17, v48, v32 row_newbcast:9 row_mask:0xf bank_mask:0xf
	v_fmac_f32_dpp v18, v48, v32 row_newbcast:10 row_mask:0xf bank_mask:0xf
	v_fmac_f32_dpp v19, v48, v32 row_newbcast:11 row_mask:0xf bank_mask:0xf
	v_fmac_f32_dpp v20, v48, v32 row_newbcast:12 row_mask:0xf bank_mask:0xf
	v_fmac_f32_dpp v21, v48, v32 row_newbcast:13 row_mask:0xf bank_mask:0xf
	v_fmac_f32_dpp v22, v48, v32 row_newbcast:14 row_mask:0xf bank_mask:0xf
	v_fmac_f32_dpp v23, v48, v32 row_newbcast:15 row_mask:0xf bank_mask:0xf
	v_fma_f32 v109, -v32, v68, v33
	v_fma_f32 v109, v66, v69, v109
	ds_write_b32 v107, v109 offset:10496
	v_cvt_pk_bf16_f32 v24, v8, v9
	v_cvt_pk_bf16_f32 v25, v10, v11
	v_cvt_pk_bf16_f32 v26, v12, v13
	v_cvt_pk_bf16_f32 v27, v14, v15
	v_cvt_pk_bf16_f32 v28, v16, v17
	v_cvt_pk_bf16_f32 v29, v18, v19
	s_waitcnt lgkmcnt(10)
	v_mfma_f32_16x16x32_bf16 v[32:35], v[70:73], v[24:27], 0
	v_cvt_pk_bf16_f32 v30, v20, v21
	v_cvt_pk_bf16_f32 v31, v22, v23
	v_fmac_f32_dpp v8, v95, v96 row_newbcast:0 row_mask:0xf bank_mask:0xf
	v_fmac_f32_dpp v9, v95, v96 row_newbcast:1 row_mask:0xf bank_mask:0xf
	v_mfma_f32_16x16x32_bf16 v[32:35], v[74:77], v[28:31], v[32:35]
	v_fmac_f32_dpp v10, v95, v96 row_newbcast:2 row_mask:0xf bank_mask:0xf
	v_fmac_f32_dpp v11, v95, v96 row_newbcast:3 row_mask:0xf bank_mask:0xf
	ds_read_b128 v[40:43], v104 offset:3072
	v_fmac_f32_dpp v12, v95, v96 row_newbcast:4 row_mask:0xf bank_mask:0xf
	v_fmac_f32_dpp v13, v95, v96 row_newbcast:5 row_mask:0xf bank_mask:0xf
	ds_read_b128 v[44:47], v104 offset:3088
	v_fmac_f32_dpp v14, v95, v96 row_newbcast:6 row_mask:0xf bank_mask:0xf
	v_fmac_f32_dpp v15, v95, v96 row_newbcast:7 row_mask:0xf bank_mask:0xf
	ds_read_b32 v65, v105 offset:19456
	v_fmac_f32_dpp v16, v95, v96 row_newbcast:8 row_mask:0xf bank_mask:0xf
	v_fmac_f32_dpp v17, v95, v96 row_newbcast:9 row_mask:0xf bank_mask:0xf
	ds_read_b32 v66, v107 offset:3072
	v_fmac_f32_dpp v18, v95, v96 row_newbcast:10 row_mask:0xf bank_mask:0xf
	v_fmac_f32_dpp v19, v95, v96 row_newbcast:11 row_mask:0xf bank_mask:0xf
	ds_read_b32 v48, v105 offset:11264
	v_fmac_f32_dpp v20, v95, v96 row_newbcast:12 row_mask:0xf bank_mask:0xf
	v_fmac_f32_dpp v21, v95, v96 row_newbcast:13 row_mask:0xf bank_mask:0xf
	ds_read_b64 v[68:69], v108 offset:49248
	v_fmac_f32_dpp v22, v95, v96 row_newbcast:14 row_mask:0xf bank_mask:0xf
	v_fmac_f32_dpp v23, v95, v96 row_newbcast:15 row_mask:0xf bank_mask:0xf
	s_waitcnt lgkmcnt(14)
	v_fmac_f32_dpp v8, v78, v32 row_newbcast:0 row_mask:0xf bank_mask:0xf
	v_fmac_f32_dpp v9, v78, v32 row_newbcast:1 row_mask:0xf bank_mask:0xf
	v_fmac_f32_dpp v10, v78, v32 row_newbcast:2 row_mask:0xf bank_mask:0xf
	v_fmac_f32_dpp v11, v78, v32 row_newbcast:3 row_mask:0xf bank_mask:0xf
	v_fmac_f32_dpp v12, v78, v32 row_newbcast:4 row_mask:0xf bank_mask:0xf
	v_fmac_f32_dpp v13, v78, v32 row_newbcast:5 row_mask:0xf bank_mask:0xf
	v_fmac_f32_dpp v14, v78, v32 row_newbcast:6 row_mask:0xf bank_mask:0xf
	v_fmac_f32_dpp v15, v78, v32 row_newbcast:7 row_mask:0xf bank_mask:0xf
	v_fmac_f32_dpp v16, v78, v32 row_newbcast:8 row_mask:0xf bank_mask:0xf
	v_fmac_f32_dpp v17, v78, v32 row_newbcast:9 row_mask:0xf bank_mask:0xf
	v_fmac_f32_dpp v18, v78, v32 row_newbcast:10 row_mask:0xf bank_mask:0xf
	v_fmac_f32_dpp v19, v78, v32 row_newbcast:11 row_mask:0xf bank_mask:0xf
	v_fmac_f32_dpp v20, v78, v32 row_newbcast:12 row_mask:0xf bank_mask:0xf
	v_fmac_f32_dpp v21, v78, v32 row_newbcast:13 row_mask:0xf bank_mask:0xf
	v_fmac_f32_dpp v22, v78, v32 row_newbcast:14 row_mask:0xf bank_mask:0xf
	v_fmac_f32_dpp v23, v78, v32 row_newbcast:15 row_mask:0xf bank_mask:0xf
	v_fma_f32 v109, -v32, v98, v33
	v_fma_f32 v109, v96, v99, v109
	ds_write_b32 v107, v109 offset:10752
	v_cvt_pk_bf16_f32 v24, v8, v9
	v_cvt_pk_bf16_f32 v25, v10, v11
	v_cvt_pk_bf16_f32 v26, v12, v13
	v_cvt_pk_bf16_f32 v27, v14, v15
	v_cvt_pk_bf16_f32 v28, v16, v17
	v_cvt_pk_bf16_f32 v29, v18, v19
	s_waitcnt lgkmcnt(10)
; __device__ __forceinline__ void phase_rwkv_scan(const Params& p, int l, const int tidx) {
;     ...
;       for (int s = 0; s < RTC; s++) {
;         const bf16x8 A0 = nA0, A1 = nA1;
;         const float wA[8] = {nw0.x, nw0.y, nw0.z, nw0.w, nw1.x, nw1.y, nw1.z, nw1.w};
;         const float wB[8] = {nw2.x, nw2.y, nw2.z, nw2.w, nw3.x, nw3.y, nw3.z, nw3.w};
;         const float kaA[8] = {nka0.x, nka0.y, nka0.z, nka0.w, nka1.x, nka1.y, nka1.z, nka1.w};
;         const float kaB[8] = {nka2.x, nka2.y, nka2.z, nka2.w, nka3.x, nka3.y, nka3.z, nka3.w};
;         const float kdA[8] = {nkd0.x, nkd0.y, nkd0.z, nkd0.w, nkd1.x, nkd1.y, nkd1.z, nkd1.w};
;         const float kdB[8] = {nkd2.x, nkd2.y, nkd2.z, nkd2.w, nkd3.x, nkd3.y, nkd3.z, nkd3.w};
;         const float v = nv;
;         float c1 = nc.x, c2 = nc.y;
;         asm volatile("" : "+v"(c1), "+v"(c2));
;         if (s + 1 < RTC) RW_LD(s + 1);
;         u32x4 pa = {pack2(Sa[0], Sa[1]), pack2(Sa[2], Sa[3]), pack2(Sa[4], Sa[5]), pack2(Sa[6], Sa[7])};
;         u32x4 pb = {pack2(Sb[0], Sb[1]), pack2(Sb[2], Sb[3]), pack2(Sb[4], Sb[5]), pack2(Sb[6], Sb[7])};
;         f32x4 acc = {0.f, 0.f, 0.f, 0.f};
;         acc = __builtin_amdgcn_mfma_f32_16x16x32_bf16(A0, __builtin_bit_cast(bf16x8, pa), acc, 0, 0, 0);
;         acc = __builtin_amdgcn_mfma_f32_16x16x32_bf16(A1, __builtin_bit_cast(bf16x8, pb), acc, 0, 0, 0);
;         float tA[8], tB[8];
; #pragma unroll
;         for (int c = 0; c < 8; c++) { tA[c] = Sa[c] * wA[c] + v * kdA[c]; tB[c] = Sb[c] * wB[c] + v * kdB[c]; }
;         const float sa = -acc[0];
;         const float yq = acc[1];
; #pragma unroll
;         for (int c = 0; c < 8; c++) { Sa[c] = tA[c] + sa * kaA[c]; Sb[c] = tB[c] + sa * kaB[c]; }
;         const float y = yq + sa * c1 + v * c2;
;         if (quad == 0) by[s * 64 + row] = y;
;       }
	v_mfma_f32_16x16x32_bf16 v[32:35], v[112:115], v[24:27], 0
	v_cvt_pk_bf16_f32 v30, v20, v21
	v_cvt_pk_bf16_f32 v31, v22, v23
	v_fmac_f32_dpp v8, v137, v138 row_newbcast:0 row_mask:0xf bank_mask:0xf
	v_fmac_f32_dpp v9, v137, v138 row_newbcast:1 row_mask:0xf bank_mask:0xf
	v_mfma_f32_16x16x32_bf16 v[32:35], v[116:119], v[28:31], v[32:35]
	v_fmac_f32_dpp v10, v137, v138 row_newbcast:2 row_mask:0xf bank_mask:0xf
	v_fmac_f32_dpp v11, v137, v138 row_newbcast:3 row_mask:0xf bank_mask:0xf
	ds_read_b128 v[70:73], v104 offset:3328
	v_fmac_f32_dpp v12, v137, v138 row_newbcast:4 row_mask:0xf bank_mask:0xf
	v_fmac_f32_dpp v13, v137, v138 row_newbcast:5 row_mask:0xf bank_mask:0xf
	ds_read_b128 v[74:77], v104 offset:3344
	v_fmac_f32_dpp v14, v137, v138 row_newbcast:6 row_mask:0xf bank_mask:0xf
	v_fmac_f32_dpp v15, v137, v138 row_newbcast:7 row_mask:0xf bank_mask:0xf
	ds_read_b32 v95, v105 offset:19712
	v_fmac_f32_dpp v16, v137, v138 row_newbcast:8 row_mask:0xf bank_mask:0xf
	v_fmac_f32_dpp v17, v137, v138 row_newbcast:9 row_mask:0xf bank_mask:0xf
	ds_read_b32 v96, v107 offset:3328
	v_fmac_f32_dpp v18, v137, v138 row_newbcast:10 row_mask:0xf bank_mask:0xf
	v_fmac_f32_dpp v19, v137, v138 row_newbcast:11 row_mask:0xf bank_mask:0xf
	ds_read_b32 v78, v105 offset:11520
	v_fmac_f32_dpp v20, v137, v138 row_newbcast:12 row_mask:0xf bank_mask:0xf
	v_fmac_f32_dpp v21, v137, v138 row_newbcast:13 row_mask:0xf bank_mask:0xf
	ds_read_b64 v[98:99], v108 offset:49256
	v_fmac_f32_dpp v22, v137, v138 row_newbcast:14 row_mask:0xf bank_mask:0xf
	v_fmac_f32_dpp v23, v137, v138 row_newbcast:15 row_mask:0xf bank_mask:0xf
	s_waitcnt lgkmcnt(14)
	v_fmac_f32_dpp v8, v120, v32 row_newbcast:0 row_mask:0xf bank_mask:0xf
	v_fmac_f32_dpp v9, v120, v32 row_newbcast:1 row_mask:0xf bank_mask:0xf
	v_fmac_f32_dpp v10, v120, v32 row_newbcast:2 row_mask:0xf bank_mask:0xf
	v_fmac_f32_dpp v11, v120, v32 row_newbcast:3 row_mask:0xf bank_mask:0xf
	v_fmac_f32_dpp v12, v120, v32 row_newbcast:4 row_mask:0xf bank_mask:0xf
	v_fmac_f32_dpp v13, v120, v32 row_newbcast:5 row_mask:0xf bank_mask:0xf
	v_fmac_f32_dpp v14, v120, v32 row_newbcast:6 row_mask:0xf bank_mask:0xf
	v_fmac_f32_dpp v15, v120, v32 row_newbcast:7 row_mask:0xf bank_mask:0xf
	v_fmac_f32_dpp v16, v120, v32 row_newbcast:8 row_mask:0xf bank_mask:0xf
	v_fmac_f32_dpp v17, v120, v32 row_newbcast:9 row_mask:0xf bank_mask:0xf
	v_fmac_f32_dpp v18, v120, v32 row_newbcast:10 row_mask:0xf bank_mask:0xf
	v_fmac_f32_dpp v19, v120, v32 row_newbcast:11 row_mask:0xf bank_mask:0xf
	v_fmac_f32_dpp v20, v120, v32 row_newbcast:12 row_mask:0xf bank_mask:0xf
	v_fmac_f32_dpp v21, v120, v32 row_newbcast:13 row_mask:0xf bank_mask:0xf
	v_fmac_f32_dpp v22, v120, v32 row_newbcast:14 row_mask:0xf bank_mask:0xf
	v_fmac_f32_dpp v23, v120, v32 row_newbcast:15 row_mask:0xf bank_mask:0xf
	v_fma_f32 v109, -v32, v140, v33
	v_fma_f32 v109, v138, v141, v109
	ds_write_b32 v107, v109 offset:11008
	v_cvt_pk_bf16_f32 v24, v8, v9
	v_cvt_pk_bf16_f32 v25, v10, v11
	v_cvt_pk_bf16_f32 v26, v12, v13
	v_cvt_pk_bf16_f32 v27, v14, v15
	v_cvt_pk_bf16_f32 v28, v16, v17
	v_cvt_pk_bf16_f32 v29, v18, v19
	s_waitcnt lgkmcnt(10)
	v_mfma_f32_16x16x32_bf16 v[32:35], v[40:43], v[24:27], 0
	v_cvt_pk_bf16_f32 v30, v20, v21
	v_cvt_pk_bf16_f32 v31, v22, v23
	v_fmac_f32_dpp v8, v65, v66 row_newbcast:0 row_mask:0xf bank_mask:0xf
	v_fmac_f32_dpp v9, v65, v66 row_newbcast:1 row_mask:0xf bank_mask:0xf
	v_mfma_f32_16x16x32_bf16 v[32:35], v[44:47], v[28:31], v[32:35]
	v_fmac_f32_dpp v10, v65, v66 row_newbcast:2 row_mask:0xf bank_mask:0xf
	v_fmac_f32_dpp v11, v65, v66 row_newbcast:3 row_mask:0xf bank_mask:0xf
	ds_read_b128 v[112:115], v104 offset:3584
	v_fmac_f32_dpp v12, v65, v66 row_newbcast:4 row_mask:0xf bank_mask:0xf
	v_fmac_f32_dpp v13, v65, v66 row_newbcast:5 row_mask:0xf bank_mask:0xf
	ds_read_b128 v[116:119], v104 offset:3600
	v_fmac_f32_dpp v14, v65, v66 row_newbcast:6 row_mask:0xf bank_mask:0xf
	v_fmac_f32_dpp v15, v65, v66 row_newbcast:7 row_mask:0xf bank_mask:0xf
	ds_read_b32 v137, v105 offset:19968
	v_fmac_f32_dpp v16, v65, v66 row_newbcast:8 row_mask:0xf bank_mask:0xf
	v_fmac_f32_dpp v17, v65, v66 row_newbcast:9 row_mask:0xf bank_mask:0xf
	ds_read_b32 v138, v107 offset:3584
	v_fmac_f32_dpp v18, v65, v66 row_newbcast:10 row_mask:0xf bank_mask:0xf
	v_fmac_f32_dpp v19, v65, v66 row_newbcast:11 row_mask:0xf bank_mask:0xf
	ds_read_b32 v120, v105 offset:11776
	v_fmac_f32_dpp v20, v65, v66 row_newbcast:12 row_mask:0xf bank_mask:0xf
	v_fmac_f32_dpp v21, v65, v66 row_newbcast:13 row_mask:0xf bank_mask:0xf
	ds_read_b64 v[140:141], v108 offset:49264
	v_fmac_f32_dpp v22, v65, v66 row_newbcast:14 row_mask:0xf bank_mask:0xf
	v_fmac_f32_dpp v23, v65, v66 row_newbcast:15 row_mask:0xf bank_mask:0xf
	s_waitcnt lgkmcnt(14)
	v_fmac_f32_dpp v8, v48, v32 row_newbcast:0 row_mask:0xf bank_mask:0xf
	v_fmac_f32_dpp v9, v48, v32 row_newbcast:1 row_mask:0xf bank_mask:0xf
	v_fmac_f32_dpp v10, v48, v32 row_newbcast:2 row_mask:0xf bank_mask:0xf
	v_fmac_f32_dpp v11, v48, v32 row_newbcast:3 row_mask:0xf bank_mask:0xf
	v_fmac_f32_dpp v12, v48, v32 row_newbcast:4 row_mask:0xf bank_mask:0xf
	v_fmac_f32_dpp v13, v48, v32 row_newbcast:5 row_mask:0xf bank_mask:0xf
	v_fmac_f32_dpp v14, v48, v32 row_newbcast:6 row_mask:0xf bank_mask:0xf
	v_fmac_f32_dpp v15, v48, v32 row_newbcast:7 row_mask:0xf bank_mask:0xf
	v_fmac_f32_dpp v16, v48, v32 row_newbcast:8 row_mask:0xf bank_mask:0xf
	v_fmac_f32_dpp v17, v48, v32 row_newbcast:9 row_mask:0xf bank_mask:0xf
	v_fmac_f32_dpp v18, v48, v32 row_newbcast:10 row_mask:0xf bank_mask:0xf
	v_fmac_f32_dpp v19, v48, v32 row_newbcast:11 row_mask:0xf bank_mask:0xf
	v_fmac_f32_dpp v20, v48, v32 row_newbcast:12 row_mask:0xf bank_mask:0xf
	v_fmac_f32_dpp v21, v48, v32 row_newbcast:13 row_mask:0xf bank_mask:0xf
	v_fmac_f32_dpp v22, v48, v32 row_newbcast:14 row_mask:0xf bank_mask:0xf
	v_fmac_f32_dpp v23, v48, v32 row_newbcast:15 row_mask:0xf bank_mask:0xf
	v_fma_f32 v109, -v32, v68, v33
	v_fma_f32 v109, v66, v69, v109
	ds_write_b32 v107, v109 offset:11264
	v_cvt_pk_bf16_f32 v24, v8, v9
	v_cvt_pk_bf16_f32 v25, v10, v11
	v_cvt_pk_bf16_f32 v26, v12, v13
	v_cvt_pk_bf16_f32 v27, v14, v15
	v_cvt_pk_bf16_f32 v28, v16, v17
	v_cvt_pk_bf16_f32 v29, v18, v19
	s_waitcnt lgkmcnt(10)
; __device__ __forceinline__ void phase_rwkv_scan(const Params& p, int l, const int tidx) {
;     ...
;       for (int s = 0; s < RTC; s++) {
;         const bf16x8 A0 = nA0, A1 = nA1;
;         const float wA[8] = {nw0.x, nw0.y, nw0.z, nw0.w, nw1.x, nw1.y, nw1.z, nw1.w};
;         const float wB[8] = {nw2.x, nw2.y, nw2.z, nw2.w, nw3.x, nw3.y, nw3.z, nw3.w};
;         const float kaA[8] = {nka0.x, nka0.y, nka0.z, nka0.w, nka1.x, nka1.y, nka1.z, nka1.w};
;         const float kaB[8] = {nka2.x, nka2.y, nka2.z, nka2.w, nka3.x, nka3.y, nka3.z, nka3.w};
;         const float kdA[8] = {nkd0.x, nkd0.y, nkd0.z, nkd0.w, nkd1.x, nkd1.y, nkd1.z, nkd1.w};
;         const float kdB[8] = {nkd2.x, nkd2.y, nkd2.z, nkd2.w, nkd3.x, nkd3.y, nkd3.z, nkd3.w};
;         const float v = nv;
;         float c1 = nc.x, c2 = nc.y;
;         asm volatile("" : "+v"(c1), "+v"(c2));
;         if (s + 1 < RTC) RW_LD(s + 1);
;         u32x4 pa = {pack2(Sa[0], Sa[1]), pack2(Sa[2], Sa[3]), pack2(Sa[4], Sa[5]), pack2(Sa[6], Sa[7])};
;         u32x4 pb = {pack2(Sb[0], Sb[1]), pack2(Sb[2], Sb[3]), pack2(Sb[4], Sb[5]), pack2(Sb[6], Sb[7])};
;         f32x4 acc = {0.f, 0.f, 0.f, 0.f};
;         acc = __builtin_amdgcn_mfma_f32_16x16x32_bf16(A0, __builtin_bit_cast(bf16x8, pa), acc, 0, 0, 0);
;         acc = __builtin_amdgcn_mfma_f32_16x16x32_bf16(A1, __builtin_bit_cast(bf16x8, pb), acc, 0, 0, 0);
;         float tA[8], tB[8];
; #pragma unroll
;         for (int c = 0; c < 8; c++) { tA[c] = Sa[c] * wA[c] + v * kdA[c]; tB[c] = Sb[c] * wB[c] + v * kdB[c]; }
;         const float sa = -acc[0];
;         const float yq = acc[1];
; #pragma unroll
;         for (int c = 0; c < 8; c++) { Sa[c] = tA[c] + sa * kaA[c]; Sb[c] = tB[c] + sa * kaB[c]; }
;         const float y = yq + sa * c1 + v * c2;
;         if (quad == 0) by[s * 64 + row] = y;
;       }
	v_mfma_f32_16x16x32_bf16 v[32:35], v[70:73], v[24:27], 0
	v_cvt_pk_bf16_f32 v30, v20, v21
	v_cvt_pk_bf16_f32 v31, v22, v23
	v_fmac_f32_dpp v8, v95, v96 row_newbcast:0 row_mask:0xf bank_mask:0xf
	v_fmac_f32_dpp v9, v95, v96 row_newbcast:1 row_mask:0xf bank_mask:0xf
	v_mfma_f32_16x16x32_bf16 v[32:35], v[74:77], v[28:31], v[32:35]
	v_fmac_f32_dpp v10, v95, v96 row_newbcast:2 row_mask:0xf bank_mask:0xf
	v_fmac_f32_dpp v11, v95, v96 row_newbcast:3 row_mask:0xf bank_mask:0xf
	ds_read_b128 v[40:43], v104 offset:3840
	v_fmac_f32_dpp v12, v95, v96 row_newbcast:4 row_mask:0xf bank_mask:0xf
	v_fmac_f32_dpp v13, v95, v96 row_newbcast:5 row_mask:0xf bank_mask:0xf
	ds_read_b128 v[44:47], v104 offset:3856
	v_fmac_f32_dpp v14, v95, v96 row_newbcast:6 row_mask:0xf bank_mask:0xf
	v_fmac_f32_dpp v15, v95, v96 row_newbcast:7 row_mask:0xf bank_mask:0xf
	ds_read_b32 v65, v105 offset:20224
	v_fmac_f32_dpp v16, v95, v96 row_newbcast:8 row_mask:0xf bank_mask:0xf
	v_fmac_f32_dpp v17, v95, v96 row_newbcast:9 row_mask:0xf bank_mask:0xf
	ds_read_b32 v66, v107 offset:3840
	v_fmac_f32_dpp v18, v95, v96 row_newbcast:10 row_mask:0xf bank_mask:0xf
	v_fmac_f32_dpp v19, v95, v96 row_newbcast:11 row_mask:0xf bank_mask:0xf
	ds_read_b32 v64, v105 offset:3840
	v_fmac_f32_dpp v20, v95, v96 row_newbcast:12 row_mask:0xf bank_mask:0xf
	v_fmac_f32_dpp v21, v95, v96 row_newbcast:13 row_mask:0xf bank_mask:0xf
	ds_read_b32 v48, v105 offset:12032
	v_fmac_f32_dpp v22, v95, v96 row_newbcast:14 row_mask:0xf bank_mask:0xf
	v_fmac_f32_dpp v23, v95, v96 row_newbcast:15 row_mask:0xf bank_mask:0xf
	ds_read_b64 v[68:69], v108 offset:49272
	s_waitcnt lgkmcnt(15)
	v_fmac_f32_dpp v8, v78, v32 row_newbcast:0 row_mask:0xf bank_mask:0xf
	v_fmac_f32_dpp v9, v78, v32 row_newbcast:1 row_mask:0xf bank_mask:0xf
	v_fmac_f32_dpp v10, v78, v32 row_newbcast:2 row_mask:0xf bank_mask:0xf
	v_fmac_f32_dpp v11, v78, v32 row_newbcast:3 row_mask:0xf bank_mask:0xf
	v_fmac_f32_dpp v12, v78, v32 row_newbcast:4 row_mask:0xf bank_mask:0xf
	v_fmac_f32_dpp v13, v78, v32 row_newbcast:5 row_mask:0xf bank_mask:0xf
	v_fmac_f32_dpp v14, v78, v32 row_newbcast:6 row_mask:0xf bank_mask:0xf
	v_fmac_f32_dpp v15, v78, v32 row_newbcast:7 row_mask:0xf bank_mask:0xf
	v_fmac_f32_dpp v16, v78, v32 row_newbcast:8 row_mask:0xf bank_mask:0xf
	v_fmac_f32_dpp v17, v78, v32 row_newbcast:9 row_mask:0xf bank_mask:0xf
	v_fmac_f32_dpp v18, v78, v32 row_newbcast:10 row_mask:0xf bank_mask:0xf
	v_fmac_f32_dpp v19, v78, v32 row_newbcast:11 row_mask:0xf bank_mask:0xf
	v_fmac_f32_dpp v20, v78, v32 row_newbcast:12 row_mask:0xf bank_mask:0xf
	v_fmac_f32_dpp v21, v78, v32 row_newbcast:13 row_mask:0xf bank_mask:0xf
	v_fmac_f32_dpp v22, v78, v32 row_newbcast:14 row_mask:0xf bank_mask:0xf
	v_fmac_f32_dpp v23, v78, v32 row_newbcast:15 row_mask:0xf bank_mask:0xf
	v_fma_f32 v109, -v32, v98, v33
	v_fma_f32 v109, v96, v99, v109
	ds_write_b32 v107, v109 offset:11520
	v_cvt_pk_bf16_f32 v24, v8, v9
	v_cvt_pk_bf16_f32 v25, v10, v11
	v_cvt_pk_bf16_f32 v26, v12, v13
	v_cvt_pk_bf16_f32 v27, v14, v15
	v_cvt_pk_bf16_f32 v28, v16, v17
	v_cvt_pk_bf16_f32 v29, v18, v19
	s_waitcnt lgkmcnt(11)
	v_mfma_f32_16x16x32_bf16 v[32:35], v[112:115], v[24:27], 0
	v_cvt_pk_bf16_f32 v30, v20, v21
	v_cvt_pk_bf16_f32 v31, v22, v23
	v_fmac_f32_dpp v8, v137, v138 row_newbcast:0 row_mask:0xf bank_mask:0xf
	v_fmac_f32_dpp v9, v137, v138 row_newbcast:1 row_mask:0xf bank_mask:0xf
	v_mfma_f32_16x16x32_bf16 v[32:35], v[116:119], v[28:31], v[32:35]
	v_fmac_f32_dpp v10, v137, v138 row_newbcast:2 row_mask:0xf bank_mask:0xf
	v_fmac_f32_dpp v11, v137, v138 row_newbcast:3 row_mask:0xf bank_mask:0xf
	ds_read_b128 v[70:73], v104 offset:4096
	v_fmac_f32_dpp v12, v137, v138 row_newbcast:4 row_mask:0xf bank_mask:0xf
	v_fmac_f32_dpp v13, v137, v138 row_newbcast:5 row_mask:0xf bank_mask:0xf
	ds_read_b128 v[74:77], v104 offset:4112
	v_fmac_f32_dpp v14, v137, v138 row_newbcast:6 row_mask:0xf bank_mask:0xf
	v_fmac_f32_dpp v15, v137, v138 row_newbcast:7 row_mask:0xf bank_mask:0xf
	ds_read_b32 v95, v105 offset:20480
	v_fmac_f32_dpp v16, v137, v138 row_newbcast:8 row_mask:0xf bank_mask:0xf
	v_fmac_f32_dpp v17, v137, v138 row_newbcast:9 row_mask:0xf bank_mask:0xf
	ds_read_b32 v96, v107 offset:4096
	v_fmac_f32_dpp v18, v137, v138 row_newbcast:10 row_mask:0xf bank_mask:0xf
	v_fmac_f32_dpp v19, v137, v138 row_newbcast:11 row_mask:0xf bank_mask:0xf
	ds_read_b32 v78, v105 offset:12288
	v_fmac_f32_dpp v20, v137, v138 row_newbcast:12 row_mask:0xf bank_mask:0xf
	v_fmac_f32_dpp v21, v137, v138 row_newbcast:13 row_mask:0xf bank_mask:0xf
	ds_read_b64 v[98:99], v108 offset:49280
	v_fmac_f32_dpp v22, v137, v138 row_newbcast:14 row_mask:0xf bank_mask:0xf
	v_fmac_f32_dpp v23, v137, v138 row_newbcast:15 row_mask:0xf bank_mask:0xf
	s_waitcnt lgkmcnt(15)
	v_fmac_f32_dpp v8, v120, v32 row_newbcast:0 row_mask:0xf bank_mask:0xf
	v_fmac_f32_dpp v9, v120, v32 row_newbcast:1 row_mask:0xf bank_mask:0xf
	v_fmac_f32_dpp v10, v120, v32 row_newbcast:2 row_mask:0xf bank_mask:0xf
	v_fmac_f32_dpp v11, v120, v32 row_newbcast:3 row_mask:0xf bank_mask:0xf
	v_fmac_f32_dpp v12, v120, v32 row_newbcast:4 row_mask:0xf bank_mask:0xf
	v_fmac_f32_dpp v13, v120, v32 row_newbcast:5 row_mask:0xf bank_mask:0xf
	v_fmac_f32_dpp v14, v120, v32 row_newbcast:6 row_mask:0xf bank_mask:0xf
	v_fmac_f32_dpp v15, v120, v32 row_newbcast:7 row_mask:0xf bank_mask:0xf
	v_fmac_f32_dpp v16, v120, v32 row_newbcast:8 row_mask:0xf bank_mask:0xf
	v_fmac_f32_dpp v17, v120, v32 row_newbcast:9 row_mask:0xf bank_mask:0xf
	v_fmac_f32_dpp v18, v120, v32 row_newbcast:10 row_mask:0xf bank_mask:0xf
	v_fmac_f32_dpp v19, v120, v32 row_newbcast:11 row_mask:0xf bank_mask:0xf
	v_fmac_f32_dpp v20, v120, v32 row_newbcast:12 row_mask:0xf bank_mask:0xf
	v_fmac_f32_dpp v21, v120, v32 row_newbcast:13 row_mask:0xf bank_mask:0xf
	v_fmac_f32_dpp v22, v120, v32 row_newbcast:14 row_mask:0xf bank_mask:0xf
	v_fmac_f32_dpp v23, v120, v32 row_newbcast:15 row_mask:0xf bank_mask:0xf
	v_fma_f32 v109, -v32, v140, v33
	v_fma_f32 v109, v138, v141, v109
	ds_write_b32 v107, v109 offset:11776
	v_cvt_pk_bf16_f32 v24, v8, v9
	v_cvt_pk_bf16_f32 v25, v10, v11
	v_cvt_pk_bf16_f32 v26, v12, v13
	v_cvt_pk_bf16_f32 v27, v14, v15
	v_cvt_pk_bf16_f32 v28, v16, v17
	v_cvt_pk_bf16_f32 v29, v18, v19
	s_waitcnt lgkmcnt(11)
; __device__ __forceinline__ void phase_rwkv_scan(const Params& p, int l, const int tidx) {
;     ...
;       for (int s = 0; s < RTC; s++) {
;         const bf16x8 A0 = nA0, A1 = nA1;
;         const float wA[8] = {nw0.x, nw0.y, nw0.z, nw0.w, nw1.x, nw1.y, nw1.z, nw1.w};
;         const float wB[8] = {nw2.x, nw2.y, nw2.z, nw2.w, nw3.x, nw3.y, nw3.z, nw3.w};
;         const float kaA[8] = {nka0.x, nka0.y, nka0.z, nka0.w, nka1.x, nka1.y, nka1.z, nka1.w};
;         const float kaB[8] = {nka2.x, nka2.y, nka2.z, nka2.w, nka3.x, nka3.y, nka3.z, nka3.w};
;         const float kdA[8] = {nkd0.x, nkd0.y, nkd0.z, nkd0.w, nkd1.x, nkd1.y, nkd1.z, nkd1.w};
;         const float kdB[8] = {nkd2.x, nkd2.y, nkd2.z, nkd2.w, nkd3.x, nkd3.y, nkd3.z, nkd3.w};
;         const float v = nv;
;         float c1 = nc.x, c2 = nc.y;
;         asm volatile("" : "+v"(c1), "+v"(c2));
;         if (s + 1 < RTC) RW_LD(s + 1);
;         u32x4 pa = {pack2(Sa[0], Sa[1]), pack2(Sa[2], Sa[3]), pack2(Sa[4], Sa[5]), pack2(Sa[6], Sa[7])};
;         u32x4 pb = {pack2(Sb[0], Sb[1]), pack2(Sb[2], Sb[3]), pack2(Sb[4], Sb[5]), pack2(Sb[6], Sb[7])};
;         f32x4 acc = {0.f, 0.f, 0.f, 0.f};
;         acc = __builtin_amdgcn_mfma_f32_16x16x32_bf16(A0, __builtin_bit_cast(bf16x8, pa), acc, 0, 0, 0);
;         acc = __builtin_amdgcn_mfma_f32_16x16x32_bf16(A1, __builtin_bit_cast(bf16x8, pb), acc, 0, 0, 0);
;         float tA[8], tB[8];
; #pragma unroll
;         for (int c = 0; c < 8; c++) { tA[c] = Sa[c] * wA[c] + v * kdA[c]; tB[c] = Sb[c] * wB[c] + v * kdB[c]; }
;         const float sa = -acc[0];
;         const float yq = acc[1];
; #pragma unroll
;         for (int c = 0; c < 8; c++) { Sa[c] = tA[c] + sa * kaA[c]; Sb[c] = tB[c] + sa * kaB[c]; }
;         const float y = yq + sa * c1 + v * c2;
;         if (quad == 0) by[s * 64 + row] = y;
;       }
	v_mfma_f32_16x16x32_bf16 v[32:35], v[40:43], v[24:27], 0
	v_cvt_pk_bf16_f32 v30, v20, v21
	v_cvt_pk_bf16_f32 v31, v22, v23
	v_fmac_f32_dpp v8, v65, v66 row_newbcast:0 row_mask:0xf bank_mask:0xf
	v_fmac_f32_dpp v9, v65, v66 row_newbcast:1 row_mask:0xf bank_mask:0xf
	v_mfma_f32_16x16x32_bf16 v[32:35], v[44:47], v[28:31], v[32:35]
	v_fmac_f32_dpp v10, v65, v66 row_newbcast:2 row_mask:0xf bank_mask:0xf
	v_fmac_f32_dpp v11, v65, v66 row_newbcast:3 row_mask:0xf bank_mask:0xf
	ds_read_b128 v[112:115], v104 offset:4352
	v_fmac_f32_dpp v12, v65, v66 row_newbcast:4 row_mask:0xf bank_mask:0xf
	v_fmac_f32_dpp v13, v65, v66 row_newbcast:5 row_mask:0xf bank_mask:0xf
	ds_read_b128 v[116:119], v104 offset:4368
	v_fmac_f32_dpp v14, v65, v66 row_newbcast:6 row_mask:0xf bank_mask:0xf
	v_fmac_f32_dpp v15, v65, v66 row_newbcast:7 row_mask:0xf bank_mask:0xf
	ds_read_b32 v137, v105 offset:20736
	v_fmac_f32_dpp v16, v65, v66 row_newbcast:8 row_mask:0xf bank_mask:0xf
	v_fmac_f32_dpp v17, v65, v66 row_newbcast:9 row_mask:0xf bank_mask:0xf
	ds_read_b32 v138, v107 offset:4352
	v_fmac_f32_dpp v18, v65, v66 row_newbcast:10 row_mask:0xf bank_mask:0xf
	v_fmac_f32_dpp v19, v65, v66 row_newbcast:11 row_mask:0xf bank_mask:0xf
	ds_read_b32 v120, v105 offset:12544
	v_fmac_f32_dpp v20, v65, v66 row_newbcast:12 row_mask:0xf bank_mask:0xf
	v_fmac_f32_dpp v21, v65, v66 row_newbcast:13 row_mask:0xf bank_mask:0xf
	ds_read_b64 v[140:141], v108 offset:49288
	v_fmac_f32_dpp v22, v65, v66 row_newbcast:14 row_mask:0xf bank_mask:0xf
	v_fmac_f32_dpp v23, v65, v66 row_newbcast:15 row_mask:0xf bank_mask:0xf
	s_waitcnt lgkmcnt(14)
	v_fmac_f32_dpp v8, v48, v32 row_newbcast:0 row_mask:0xf bank_mask:0xf
	v_fmac_f32_dpp v9, v48, v32 row_newbcast:1 row_mask:0xf bank_mask:0xf
	v_fmac_f32_dpp v10, v48, v32 row_newbcast:2 row_mask:0xf bank_mask:0xf
	v_fmac_f32_dpp v11, v48, v32 row_newbcast:3 row_mask:0xf bank_mask:0xf
	v_fmac_f32_dpp v12, v48, v32 row_newbcast:4 row_mask:0xf bank_mask:0xf
	v_fmac_f32_dpp v13, v48, v32 row_newbcast:5 row_mask:0xf bank_mask:0xf
	v_fmac_f32_dpp v14, v48, v32 row_newbcast:6 row_mask:0xf bank_mask:0xf
	v_fmac_f32_dpp v15, v48, v32 row_newbcast:7 row_mask:0xf bank_mask:0xf
	v_fmac_f32_dpp v16, v48, v32 row_newbcast:8 row_mask:0xf bank_mask:0xf
	v_fmac_f32_dpp v17, v48, v32 row_newbcast:9 row_mask:0xf bank_mask:0xf
	v_fmac_f32_dpp v18, v48, v32 row_newbcast:10 row_mask:0xf bank_mask:0xf
	v_fmac_f32_dpp v19, v48, v32 row_newbcast:11 row_mask:0xf bank_mask:0xf
	v_fmac_f32_dpp v20, v48, v32 row_newbcast:12 row_mask:0xf bank_mask:0xf
	v_fmac_f32_dpp v21, v48, v32 row_newbcast:13 row_mask:0xf bank_mask:0xf
	v_fmac_f32_dpp v22, v48, v32 row_newbcast:14 row_mask:0xf bank_mask:0xf
	v_fmac_f32_dpp v23, v48, v32 row_newbcast:15 row_mask:0xf bank_mask:0xf
	v_fma_f32 v109, -v32, v68, v33
	v_fma_f32 v109, v66, v69, v109
	v_mul_f32_dpp v8, v64, v8 row_newbcast:0 row_mask:0xf bank_mask:0xf
	v_mul_f32_dpp v9, v64, v9 row_newbcast:1 row_mask:0xf bank_mask:0xf
	v_mul_f32_dpp v10, v64, v10 row_newbcast:2 row_mask:0xf bank_mask:0xf
	v_mul_f32_dpp v11, v64, v11 row_newbcast:3 row_mask:0xf bank_mask:0xf
	v_mul_f32_dpp v12, v64, v12 row_newbcast:4 row_mask:0xf bank_mask:0xf
	v_mul_f32_dpp v13, v64, v13 row_newbcast:5 row_mask:0xf bank_mask:0xf
	v_mul_f32_dpp v14, v64, v14 row_newbcast:6 row_mask:0xf bank_mask:0xf
	v_mul_f32_dpp v15, v64, v15 row_newbcast:7 row_mask:0xf bank_mask:0xf
	v_mul_f32_dpp v16, v64, v16 row_newbcast:8 row_mask:0xf bank_mask:0xf
	v_mul_f32_dpp v17, v64, v17 row_newbcast:9 row_mask:0xf bank_mask:0xf
	v_mul_f32_dpp v18, v64, v18 row_newbcast:10 row_mask:0xf bank_mask:0xf
	v_mul_f32_dpp v19, v64, v19 row_newbcast:11 row_mask:0xf bank_mask:0xf
	v_mul_f32_dpp v20, v64, v20 row_newbcast:12 row_mask:0xf bank_mask:0xf
	v_mul_f32_dpp v21, v64, v21 row_newbcast:13 row_mask:0xf bank_mask:0xf
	v_mul_f32_dpp v22, v64, v22 row_newbcast:14 row_mask:0xf bank_mask:0xf
	v_mul_f32_dpp v23, v64, v23 row_newbcast:15 row_mask:0xf bank_mask:0xf
	ds_write_b32 v107, v109 offset:12032
	v_cvt_pk_bf16_f32 v24, v8, v9
	v_cvt_pk_bf16_f32 v25, v10, v11
	v_cvt_pk_bf16_f32 v26, v12, v13
	v_cvt_pk_bf16_f32 v27, v14, v15
	v_cvt_pk_bf16_f32 v28, v16, v17
	v_cvt_pk_bf16_f32 v29, v18, v19
	s_waitcnt lgkmcnt(10)
	v_mfma_f32_16x16x32_bf16 v[32:35], v[70:73], v[24:27], 0
	v_cvt_pk_bf16_f32 v30, v20, v21
	v_cvt_pk_bf16_f32 v31, v22, v23
	v_fmac_f32_dpp v8, v95, v96 row_newbcast:0 row_mask:0xf bank_mask:0xf
	v_fmac_f32_dpp v9, v95, v96 row_newbcast:1 row_mask:0xf bank_mask:0xf
	v_mfma_f32_16x16x32_bf16 v[32:35], v[74:77], v[28:31], v[32:35]
	v_fmac_f32_dpp v10, v95, v96 row_newbcast:2 row_mask:0xf bank_mask:0xf
	v_fmac_f32_dpp v11, v95, v96 row_newbcast:3 row_mask:0xf bank_mask:0xf
	ds_read_b128 v[40:43], v104 offset:4608
	v_fmac_f32_dpp v12, v95, v96 row_newbcast:4 row_mask:0xf bank_mask:0xf
	v_fmac_f32_dpp v13, v95, v96 row_newbcast:5 row_mask:0xf bank_mask:0xf
	ds_read_b128 v[44:47], v104 offset:4624
	v_fmac_f32_dpp v14, v95, v96 row_newbcast:6 row_mask:0xf bank_mask:0xf
	v_fmac_f32_dpp v15, v95, v96 row_newbcast:7 row_mask:0xf bank_mask:0xf
	ds_read_b32 v65, v105 offset:20992
	v_fmac_f32_dpp v16, v95, v96 row_newbcast:8 row_mask:0xf bank_mask:0xf
	v_fmac_f32_dpp v17, v95, v96 row_newbcast:9 row_mask:0xf bank_mask:0xf
	ds_read_b32 v66, v107 offset:4608
	v_fmac_f32_dpp v18, v95, v96 row_newbcast:10 row_mask:0xf bank_mask:0xf
	v_fmac_f32_dpp v19, v95, v96 row_newbcast:11 row_mask:0xf bank_mask:0xf
	ds_read_b32 v48, v105 offset:12800
	v_fmac_f32_dpp v20, v95, v96 row_newbcast:12 row_mask:0xf bank_mask:0xf
	v_fmac_f32_dpp v21, v95, v96 row_newbcast:13 row_mask:0xf bank_mask:0xf
	ds_read_b64 v[68:69], v108 offset:49296
	v_fmac_f32_dpp v22, v95, v96 row_newbcast:14 row_mask:0xf bank_mask:0xf
	v_fmac_f32_dpp v23, v95, v96 row_newbcast:15 row_mask:0xf bank_mask:0xf
	s_waitcnt lgkmcnt(14)
; __device__ __forceinline__ void phase_rwkv_scan(const Params& p, int l, const int tidx) {
;     ...
;       for (int s = 0; s < RTC; s++) {
;         const bf16x8 A0 = nA0, A1 = nA1;
;         const float wA[8] = {nw0.x, nw0.y, nw0.z, nw0.w, nw1.x, nw1.y, nw1.z, nw1.w};
;         const float wB[8] = {nw2.x, nw2.y, nw2.z, nw2.w, nw3.x, nw3.y, nw3.z, nw3.w};
;         const float kaA[8] = {nka0.x, nka0.y, nka0.z, nka0.w, nka1.x, nka1.y, nka1.z, nka1.w};
;         const float kaB[8] = {nka2.x, nka2.y, nka2.z, nka2.w, nka3.x, nka3.y, nka3.z, nka3.w};
;         const float kdA[8] = {nkd0.x, nkd0.y, nkd0.z, nkd0.w, nkd1.x, nkd1.y, nkd1.z, nkd1.w};
;         const float kdB[8] = {nkd2.x, nkd2.y, nkd2.z, nkd2.w, nkd3.x, nkd3.y, nkd3.z, nkd3.w};
;         const float v = nv;
;         float c1 = nc.x, c2 = nc.y;
;         asm volatile("" : "+v"(c1), "+v"(c2));
;         if (s + 1 < RTC) RW_LD(s + 1);
;         u32x4 pa = {pack2(Sa[0], Sa[1]), pack2(Sa[2], Sa[3]), pack2(Sa[4], Sa[5]), pack2(Sa[6], Sa[7])};
;         u32x4 pb = {pack2(Sb[0], Sb[1]), pack2(Sb[2], Sb[3]), pack2(Sb[4], Sb[5]), pack2(Sb[6], Sb[7])};
;         f32x4 acc = {0.f, 0.f, 0.f, 0.f};
;         acc = __builtin_amdgcn_mfma_f32_16x16x32_bf16(A0, __builtin_bit_cast(bf16x8, pa), acc, 0, 0, 0);
;         acc = __builtin_amdgcn_mfma_f32_16x16x32_bf16(A1, __builtin_bit_cast(bf16x8, pb), acc, 0, 0, 0);
;         float tA[8], tB[8];
; #pragma unroll
;         for (int c = 0; c < 8; c++) { tA[c] = Sa[c] * wA[c] + v * kdA[c]; tB[c] = Sb[c] * wB[c] + v * kdB[c]; }
;         const float sa = -acc[0];
;         const float yq = acc[1];
; #pragma unroll
;         for (int c = 0; c < 8; c++) { Sa[c] = tA[c] + sa * kaA[c]; Sb[c] = tB[c] + sa * kaB[c]; }
;         const float y = yq + sa * c1 + v * c2;
;         if (quad == 0) by[s * 64 + row] = y;
;       }
	v_fmac_f32_dpp v8, v78, v32 row_newbcast:0 row_mask:0xf bank_mask:0xf
	v_fmac_f32_dpp v9, v78, v32 row_newbcast:1 row_mask:0xf bank_mask:0xf
	v_fmac_f32_dpp v10, v78, v32 row_newbcast:2 row_mask:0xf bank_mask:0xf
	v_fmac_f32_dpp v11, v78, v32 row_newbcast:3 row_mask:0xf bank_mask:0xf
	v_fmac_f32_dpp v12, v78, v32 row_newbcast:4 row_mask:0xf bank_mask:0xf
	v_fmac_f32_dpp v13, v78, v32 row_newbcast:5 row_mask:0xf bank_mask:0xf
	v_fmac_f32_dpp v14, v78, v32 row_newbcast:6 row_mask:0xf bank_mask:0xf
	v_fmac_f32_dpp v15, v78, v32 row_newbcast:7 row_mask:0xf bank_mask:0xf
	v_fmac_f32_dpp v16, v78, v32 row_newbcast:8 row_mask:0xf bank_mask:0xf
	v_fmac_f32_dpp v17, v78, v32 row_newbcast:9 row_mask:0xf bank_mask:0xf
	v_fmac_f32_dpp v18, v78, v32 row_newbcast:10 row_mask:0xf bank_mask:0xf
	v_fmac_f32_dpp v19, v78, v32 row_newbcast:11 row_mask:0xf bank_mask:0xf
	v_fmac_f32_dpp v20, v78, v32 row_newbcast:12 row_mask:0xf bank_mask:0xf
	v_fmac_f32_dpp v21, v78, v32 row_newbcast:13 row_mask:0xf bank_mask:0xf
	v_fmac_f32_dpp v22, v78, v32 row_newbcast:14 row_mask:0xf bank_mask:0xf
	v_fmac_f32_dpp v23, v78, v32 row_newbcast:15 row_mask:0xf bank_mask:0xf
	v_fma_f32 v109, -v32, v98, v33
	v_fma_f32 v109, v96, v99, v109
	ds_write_b32 v107, v109 offset:12288
	v_cvt_pk_bf16_f32 v24, v8, v9
	v_cvt_pk_bf16_f32 v25, v10, v11
	v_cvt_pk_bf16_f32 v26, v12, v13
	v_cvt_pk_bf16_f32 v27, v14, v15
	v_cvt_pk_bf16_f32 v28, v16, v17
	v_cvt_pk_bf16_f32 v29, v18, v19
	s_waitcnt lgkmcnt(10)
	v_mfma_f32_16x16x32_bf16 v[32:35], v[112:115], v[24:27], 0
	v_cvt_pk_bf16_f32 v30, v20, v21
	v_cvt_pk_bf16_f32 v31, v22, v23
	v_fmac_f32_dpp v8, v137, v138 row_newbcast:0 row_mask:0xf bank_mask:0xf
	v_fmac_f32_dpp v9, v137, v138 row_newbcast:1 row_mask:0xf bank_mask:0xf
	v_mfma_f32_16x16x32_bf16 v[32:35], v[116:119], v[28:31], v[32:35]
	v_fmac_f32_dpp v10, v137, v138 row_newbcast:2 row_mask:0xf bank_mask:0xf
	v_fmac_f32_dpp v11, v137, v138 row_newbcast:3 row_mask:0xf bank_mask:0xf
	ds_read_b128 v[70:73], v104 offset:4864
	v_fmac_f32_dpp v12, v137, v138 row_newbcast:4 row_mask:0xf bank_mask:0xf
	v_fmac_f32_dpp v13, v137, v138 row_newbcast:5 row_mask:0xf bank_mask:0xf
	ds_read_b128 v[74:77], v104 offset:4880
	v_fmac_f32_dpp v14, v137, v138 row_newbcast:6 row_mask:0xf bank_mask:0xf
	v_fmac_f32_dpp v15, v137, v138 row_newbcast:7 row_mask:0xf bank_mask:0xf
	ds_read_b32 v95, v105 offset:21248
	v_fmac_f32_dpp v16, v137, v138 row_newbcast:8 row_mask:0xf bank_mask:0xf
	v_fmac_f32_dpp v17, v137, v138 row_newbcast:9 row_mask:0xf bank_mask:0xf
	ds_read_b32 v96, v107 offset:4864
	v_fmac_f32_dpp v18, v137, v138 row_newbcast:10 row_mask:0xf bank_mask:0xf
	v_fmac_f32_dpp v19, v137, v138 row_newbcast:11 row_mask:0xf bank_mask:0xf
	ds_read_b32 v78, v105 offset:13056
	v_fmac_f32_dpp v20, v137, v138 row_newbcast:12 row_mask:0xf bank_mask:0xf
	v_fmac_f32_dpp v21, v137, v138 row_newbcast:13 row_mask:0xf bank_mask:0xf
	ds_read_b64 v[98:99], v108 offset:49304
	v_fmac_f32_dpp v22, v137, v138 row_newbcast:14 row_mask:0xf bank_mask:0xf
	v_fmac_f32_dpp v23, v137, v138 row_newbcast:15 row_mask:0xf bank_mask:0xf
	s_waitcnt lgkmcnt(14)
	v_fmac_f32_dpp v8, v120, v32 row_newbcast:0 row_mask:0xf bank_mask:0xf
	v_fmac_f32_dpp v9, v120, v32 row_newbcast:1 row_mask:0xf bank_mask:0xf
	v_fmac_f32_dpp v10, v120, v32 row_newbcast:2 row_mask:0xf bank_mask:0xf
	v_fmac_f32_dpp v11, v120, v32 row_newbcast:3 row_mask:0xf bank_mask:0xf
	v_fmac_f32_dpp v12, v120, v32 row_newbcast:4 row_mask:0xf bank_mask:0xf
	v_fmac_f32_dpp v13, v120, v32 row_newbcast:5 row_mask:0xf bank_mask:0xf
	v_fmac_f32_dpp v14, v120, v32 row_newbcast:6 row_mask:0xf bank_mask:0xf
	v_fmac_f32_dpp v15, v120, v32 row_newbcast:7 row_mask:0xf bank_mask:0xf
	v_fmac_f32_dpp v16, v120, v32 row_newbcast:8 row_mask:0xf bank_mask:0xf
	v_fmac_f32_dpp v17, v120, v32 row_newbcast:9 row_mask:0xf bank_mask:0xf
	v_fmac_f32_dpp v18, v120, v32 row_newbcast:10 row_mask:0xf bank_mask:0xf
	v_fmac_f32_dpp v19, v120, v32 row_newbcast:11 row_mask:0xf bank_mask:0xf
	v_fmac_f32_dpp v20, v120, v32 row_newbcast:12 row_mask:0xf bank_mask:0xf
	v_fmac_f32_dpp v21, v120, v32 row_newbcast:13 row_mask:0xf bank_mask:0xf
	v_fmac_f32_dpp v22, v120, v32 row_newbcast:14 row_mask:0xf bank_mask:0xf
	v_fmac_f32_dpp v23, v120, v32 row_newbcast:15 row_mask:0xf bank_mask:0xf
	v_fma_f32 v109, -v32, v140, v33
	v_fma_f32 v109, v138, v141, v109
	ds_write_b32 v107, v109 offset:12544
	v_cvt_pk_bf16_f32 v24, v8, v9
	v_cvt_pk_bf16_f32 v25, v10, v11
	v_cvt_pk_bf16_f32 v26, v12, v13
	v_cvt_pk_bf16_f32 v27, v14, v15
	v_cvt_pk_bf16_f32 v28, v16, v17
	v_cvt_pk_bf16_f32 v29, v18, v19
	s_waitcnt lgkmcnt(10)
	v_mfma_f32_16x16x32_bf16 v[32:35], v[40:43], v[24:27], 0
	v_cvt_pk_bf16_f32 v30, v20, v21
	v_cvt_pk_bf16_f32 v31, v22, v23
	v_fmac_f32_dpp v8, v65, v66 row_newbcast:0 row_mask:0xf bank_mask:0xf
	v_fmac_f32_dpp v9, v65, v66 row_newbcast:1 row_mask:0xf bank_mask:0xf
	v_mfma_f32_16x16x32_bf16 v[32:35], v[44:47], v[28:31], v[32:35]
	v_fmac_f32_dpp v10, v65, v66 row_newbcast:2 row_mask:0xf bank_mask:0xf
	v_fmac_f32_dpp v11, v65, v66 row_newbcast:3 row_mask:0xf bank_mask:0xf
	ds_read_b128 v[112:115], v104 offset:5120
	v_fmac_f32_dpp v12, v65, v66 row_newbcast:4 row_mask:0xf bank_mask:0xf
	v_fmac_f32_dpp v13, v65, v66 row_newbcast:5 row_mask:0xf bank_mask:0xf
	ds_read_b128 v[116:119], v104 offset:5136
	v_fmac_f32_dpp v14, v65, v66 row_newbcast:6 row_mask:0xf bank_mask:0xf
	v_fmac_f32_dpp v15, v65, v66 row_newbcast:7 row_mask:0xf bank_mask:0xf
	ds_read_b32 v137, v105 offset:21504
	v_fmac_f32_dpp v16, v65, v66 row_newbcast:8 row_mask:0xf bank_mask:0xf
	v_fmac_f32_dpp v17, v65, v66 row_newbcast:9 row_mask:0xf bank_mask:0xf
	ds_read_b32 v138, v107 offset:5120
	v_fmac_f32_dpp v18, v65, v66 row_newbcast:10 row_mask:0xf bank_mask:0xf
	v_fmac_f32_dpp v19, v65, v66 row_newbcast:11 row_mask:0xf bank_mask:0xf
	ds_read_b32 v120, v105 offset:13312
	v_fmac_f32_dpp v20, v65, v66 row_newbcast:12 row_mask:0xf bank_mask:0xf
	v_fmac_f32_dpp v21, v65, v66 row_newbcast:13 row_mask:0xf bank_mask:0xf
	ds_read_b64 v[140:141], v108 offset:49312
	v_fmac_f32_dpp v22, v65, v66 row_newbcast:14 row_mask:0xf bank_mask:0xf
	v_fmac_f32_dpp v23, v65, v66 row_newbcast:15 row_mask:0xf bank_mask:0xf
	s_waitcnt lgkmcnt(14)
; __device__ __forceinline__ void phase_rwkv_scan(const Params& p, int l, const int tidx) {
;     ...
;       for (int s = 0; s < RTC; s++) {
;         const bf16x8 A0 = nA0, A1 = nA1;
;         const float wA[8] = {nw0.x, nw0.y, nw0.z, nw0.w, nw1.x, nw1.y, nw1.z, nw1.w};
;         const float wB[8] = {nw2.x, nw2.y, nw2.z, nw2.w, nw3.x, nw3.y, nw3.z, nw3.w};
;         const float kaA[8] = {nka0.x, nka0.y, nka0.z, nka0.w, nka1.x, nka1.y, nka1.z, nka1.w};
;         const float kaB[8] = {nka2.x, nka2.y, nka2.z, nka2.w, nka3.x, nka3.y, nka3.z, nka3.w};
;         const float kdA[8] = {nkd0.x, nkd0.y, nkd0.z, nkd0.w, nkd1.x, nkd1.y, nkd1.z, nkd1.w};
;         const float kdB[8] = {nkd2.x, nkd2.y, nkd2.z, nkd2.w, nkd3.x, nkd3.y, nkd3.z, nkd3.w};
;         const float v = nv;
;         float c1 = nc.x, c2 = nc.y;
;         asm volatile("" : "+v"(c1), "+v"(c2));
;         if (s + 1 < RTC) RW_LD(s + 1);
;         u32x4 pa = {pack2(Sa[0], Sa[1]), pack2(Sa[2], Sa[3]), pack2(Sa[4], Sa[5]), pack2(Sa[6], Sa[7])};
;         u32x4 pb = {pack2(Sb[0], Sb[1]), pack2(Sb[2], Sb[3]), pack2(Sb[4], Sb[5]), pack2(Sb[6], Sb[7])};
;         f32x4 acc = {0.f, 0.f, 0.f, 0.f};
;         acc = __builtin_amdgcn_mfma_f32_16x16x32_bf16(A0, __builtin_bit_cast(bf16x8, pa), acc, 0, 0, 0);
;         acc = __builtin_amdgcn_mfma_f32_16x16x32_bf16(A1, __builtin_bit_cast(bf16x8, pb), acc, 0, 0, 0);
;         float tA[8], tB[8];
; #pragma unroll
;         for (int c = 0; c < 8; c++) { tA[c] = Sa[c] * wA[c] + v * kdA[c]; tB[c] = Sb[c] * wB[c] + v * kdB[c]; }
;         const float sa = -acc[0];
;         const float yq = acc[1];
; #pragma unroll
;         for (int c = 0; c < 8; c++) { Sa[c] = tA[c] + sa * kaA[c]; Sb[c] = tB[c] + sa * kaB[c]; }
;         const float y = yq + sa * c1 + v * c2;
;         if (quad == 0) by[s * 64 + row] = y;
;       }
	v_fmac_f32_dpp v8, v48, v32 row_newbcast:0 row_mask:0xf bank_mask:0xf
	v_fmac_f32_dpp v9, v48, v32 row_newbcast:1 row_mask:0xf bank_mask:0xf
	v_fmac_f32_dpp v10, v48, v32 row_newbcast:2 row_mask:0xf bank_mask:0xf
	v_fmac_f32_dpp v11, v48, v32 row_newbcast:3 row_mask:0xf bank_mask:0xf
	v_fmac_f32_dpp v12, v48, v32 row_newbcast:4 row_mask:0xf bank_mask:0xf
	v_fmac_f32_dpp v13, v48, v32 row_newbcast:5 row_mask:0xf bank_mask:0xf
	v_fmac_f32_dpp v14, v48, v32 row_newbcast:6 row_mask:0xf bank_mask:0xf
	v_fmac_f32_dpp v15, v48, v32 row_newbcast:7 row_mask:0xf bank_mask:0xf
	v_fmac_f32_dpp v16, v48, v32 row_newbcast:8 row_mask:0xf bank_mask:0xf
	v_fmac_f32_dpp v17, v48, v32 row_newbcast:9 row_mask:0xf bank_mask:0xf
	v_fmac_f32_dpp v18, v48, v32 row_newbcast:10 row_mask:0xf bank_mask:0xf
	v_fmac_f32_dpp v19, v48, v32 row_newbcast:11 row_mask:0xf bank_mask:0xf
	v_fmac_f32_dpp v20, v48, v32 row_newbcast:12 row_mask:0xf bank_mask:0xf
	v_fmac_f32_dpp v21, v48, v32 row_newbcast:13 row_mask:0xf bank_mask:0xf
	v_fmac_f32_dpp v22, v48, v32 row_newbcast:14 row_mask:0xf bank_mask:0xf
	v_fmac_f32_dpp v23, v48, v32 row_newbcast:15 row_mask:0xf bank_mask:0xf
	v_fma_f32 v109, -v32, v68, v33
	v_fma_f32 v109, v66, v69, v109
	ds_write_b32 v107, v109 offset:12800
	v_cvt_pk_bf16_f32 v24, v8, v9
	v_cvt_pk_bf16_f32 v25, v10, v11
	v_cvt_pk_bf16_f32 v26, v12, v13
	v_cvt_pk_bf16_f32 v27, v14, v15
	v_cvt_pk_bf16_f32 v28, v16, v17
	v_cvt_pk_bf16_f32 v29, v18, v19
	s_waitcnt lgkmcnt(10)
	v_mfma_f32_16x16x32_bf16 v[32:35], v[70:73], v[24:27], 0
	v_cvt_pk_bf16_f32 v30, v20, v21
	v_cvt_pk_bf16_f32 v31, v22, v23
	v_fmac_f32_dpp v8, v95, v96 row_newbcast:0 row_mask:0xf bank_mask:0xf
	v_fmac_f32_dpp v9, v95, v96 row_newbcast:1 row_mask:0xf bank_mask:0xf
	v_mfma_f32_16x16x32_bf16 v[32:35], v[74:77], v[28:31], v[32:35]
	v_fmac_f32_dpp v10, v95, v96 row_newbcast:2 row_mask:0xf bank_mask:0xf
	v_fmac_f32_dpp v11, v95, v96 row_newbcast:3 row_mask:0xf bank_mask:0xf
	ds_read_b128 v[40:43], v104 offset:5376
	v_fmac_f32_dpp v12, v95, v96 row_newbcast:4 row_mask:0xf bank_mask:0xf
	v_fmac_f32_dpp v13, v95, v96 row_newbcast:5 row_mask:0xf bank_mask:0xf
	ds_read_b128 v[44:47], v104 offset:5392
	v_fmac_f32_dpp v14, v95, v96 row_newbcast:6 row_mask:0xf bank_mask:0xf
	v_fmac_f32_dpp v15, v95, v96 row_newbcast:7 row_mask:0xf bank_mask:0xf
	ds_read_b32 v65, v105 offset:21760
	v_fmac_f32_dpp v16, v95, v96 row_newbcast:8 row_mask:0xf bank_mask:0xf
	v_fmac_f32_dpp v17, v95, v96 row_newbcast:9 row_mask:0xf bank_mask:0xf
	ds_read_b32 v66, v107 offset:5376
	v_fmac_f32_dpp v18, v95, v96 row_newbcast:10 row_mask:0xf bank_mask:0xf
	v_fmac_f32_dpp v19, v95, v96 row_newbcast:11 row_mask:0xf bank_mask:0xf
	ds_read_b32 v48, v105 offset:13568
	v_fmac_f32_dpp v20, v95, v96 row_newbcast:12 row_mask:0xf bank_mask:0xf
	v_fmac_f32_dpp v21, v95, v96 row_newbcast:13 row_mask:0xf bank_mask:0xf
	ds_read_b64 v[68:69], v108 offset:49320
	v_fmac_f32_dpp v22, v95, v96 row_newbcast:14 row_mask:0xf bank_mask:0xf
	v_fmac_f32_dpp v23, v95, v96 row_newbcast:15 row_mask:0xf bank_mask:0xf
	s_waitcnt lgkmcnt(14)
	v_fmac_f32_dpp v8, v78, v32 row_newbcast:0 row_mask:0xf bank_mask:0xf
	v_fmac_f32_dpp v9, v78, v32 row_newbcast:1 row_mask:0xf bank_mask:0xf
	v_fmac_f32_dpp v10, v78, v32 row_newbcast:2 row_mask:0xf bank_mask:0xf
	v_fmac_f32_dpp v11, v78, v32 row_newbcast:3 row_mask:0xf bank_mask:0xf
	v_fmac_f32_dpp v12, v78, v32 row_newbcast:4 row_mask:0xf bank_mask:0xf
	v_fmac_f32_dpp v13, v78, v32 row_newbcast:5 row_mask:0xf bank_mask:0xf
	v_fmac_f32_dpp v14, v78, v32 row_newbcast:6 row_mask:0xf bank_mask:0xf
	v_fmac_f32_dpp v15, v78, v32 row_newbcast:7 row_mask:0xf bank_mask:0xf
	v_fmac_f32_dpp v16, v78, v32 row_newbcast:8 row_mask:0xf bank_mask:0xf
	v_fmac_f32_dpp v17, v78, v32 row_newbcast:9 row_mask:0xf bank_mask:0xf
	v_fmac_f32_dpp v18, v78, v32 row_newbcast:10 row_mask:0xf bank_mask:0xf
	v_fmac_f32_dpp v19, v78, v32 row_newbcast:11 row_mask:0xf bank_mask:0xf
	v_fmac_f32_dpp v20, v78, v32 row_newbcast:12 row_mask:0xf bank_mask:0xf
	v_fmac_f32_dpp v21, v78, v32 row_newbcast:13 row_mask:0xf bank_mask:0xf
	v_fmac_f32_dpp v22, v78, v32 row_newbcast:14 row_mask:0xf bank_mask:0xf
	v_fmac_f32_dpp v23, v78, v32 row_newbcast:15 row_mask:0xf bank_mask:0xf
	v_fma_f32 v109, -v32, v98, v33
	v_fma_f32 v109, v96, v99, v109
	ds_write_b32 v107, v109 offset:13056
	v_cvt_pk_bf16_f32 v24, v8, v9
	v_cvt_pk_bf16_f32 v25, v10, v11
	v_cvt_pk_bf16_f32 v26, v12, v13
	v_cvt_pk_bf16_f32 v27, v14, v15
	v_cvt_pk_bf16_f32 v28, v16, v17
	v_cvt_pk_bf16_f32 v29, v18, v19
	s_waitcnt lgkmcnt(10)
	v_mfma_f32_16x16x32_bf16 v[32:35], v[112:115], v[24:27], 0
	v_cvt_pk_bf16_f32 v30, v20, v21
	v_cvt_pk_bf16_f32 v31, v22, v23
	v_fmac_f32_dpp v8, v137, v138 row_newbcast:0 row_mask:0xf bank_mask:0xf
	v_fmac_f32_dpp v9, v137, v138 row_newbcast:1 row_mask:0xf bank_mask:0xf
	v_mfma_f32_16x16x32_bf16 v[32:35], v[116:119], v[28:31], v[32:35]
	v_fmac_f32_dpp v10, v137, v138 row_newbcast:2 row_mask:0xf bank_mask:0xf
	v_fmac_f32_dpp v11, v137, v138 row_newbcast:3 row_mask:0xf bank_mask:0xf
	ds_read_b128 v[70:73], v104 offset:5632
	v_fmac_f32_dpp v12, v137, v138 row_newbcast:4 row_mask:0xf bank_mask:0xf
	v_fmac_f32_dpp v13, v137, v138 row_newbcast:5 row_mask:0xf bank_mask:0xf
	ds_read_b128 v[74:77], v104 offset:5648
	v_fmac_f32_dpp v14, v137, v138 row_newbcast:6 row_mask:0xf bank_mask:0xf
	v_fmac_f32_dpp v15, v137, v138 row_newbcast:7 row_mask:0xf bank_mask:0xf
	ds_read_b32 v95, v105 offset:22016
	v_fmac_f32_dpp v16, v137, v138 row_newbcast:8 row_mask:0xf bank_mask:0xf
	v_fmac_f32_dpp v17, v137, v138 row_newbcast:9 row_mask:0xf bank_mask:0xf
	ds_read_b32 v96, v107 offset:5632
	v_fmac_f32_dpp v18, v137, v138 row_newbcast:10 row_mask:0xf bank_mask:0xf
	v_fmac_f32_dpp v19, v137, v138 row_newbcast:11 row_mask:0xf bank_mask:0xf
	ds_read_b32 v78, v105 offset:13824
	v_fmac_f32_dpp v20, v137, v138 row_newbcast:12 row_mask:0xf bank_mask:0xf
	v_fmac_f32_dpp v21, v137, v138 row_newbcast:13 row_mask:0xf bank_mask:0xf
	ds_read_b64 v[98:99], v108 offset:49328
	v_fmac_f32_dpp v22, v137, v138 row_newbcast:14 row_mask:0xf bank_mask:0xf
	v_fmac_f32_dpp v23, v137, v138 row_newbcast:15 row_mask:0xf bank_mask:0xf
	s_waitcnt lgkmcnt(14)
; __device__ __forceinline__ void phase_rwkv_scan(const Params& p, int l, const int tidx) {
;     ...
;       for (int s = 0; s < RTC; s++) {
;         const bf16x8 A0 = nA0, A1 = nA1;
;         const float wA[8] = {nw0.x, nw0.y, nw0.z, nw0.w, nw1.x, nw1.y, nw1.z, nw1.w};
;         const float wB[8] = {nw2.x, nw2.y, nw2.z, nw2.w, nw3.x, nw3.y, nw3.z, nw3.w};
;         const float kaA[8] = {nka0.x, nka0.y, nka0.z, nka0.w, nka1.x, nka1.y, nka1.z, nka1.w};
;         const float kaB[8] = {nka2.x, nka2.y, nka2.z, nka2.w, nka3.x, nka3.y, nka3.z, nka3.w};
;         const float kdA[8] = {nkd0.x, nkd0.y, nkd0.z, nkd0.w, nkd1.x, nkd1.y, nkd1.z, nkd1.w};
;         const float kdB[8] = {nkd2.x, nkd2.y, nkd2.z, nkd2.w, nkd3.x, nkd3.y, nkd3.z, nkd3.w};
;         const float v = nv;
;         float c1 = nc.x, c2 = nc.y;
;         asm volatile("" : "+v"(c1), "+v"(c2));
;         if (s + 1 < RTC) RW_LD(s + 1);
;         u32x4 pa = {pack2(Sa[0], Sa[1]), pack2(Sa[2], Sa[3]), pack2(Sa[4], Sa[5]), pack2(Sa[6], Sa[7])};
;         u32x4 pb = {pack2(Sb[0], Sb[1]), pack2(Sb[2], Sb[3]), pack2(Sb[4], Sb[5]), pack2(Sb[6], Sb[7])};
;         f32x4 acc = {0.f, 0.f, 0.f, 0.f};
;         acc = __builtin_amdgcn_mfma_f32_16x16x32_bf16(A0, __builtin_bit_cast(bf16x8, pa), acc, 0, 0, 0);
;         acc = __builtin_amdgcn_mfma_f32_16x16x32_bf16(A1, __builtin_bit_cast(bf16x8, pb), acc, 0, 0, 0);
;         float tA[8], tB[8];
; #pragma unroll
;         for (int c = 0; c < 8; c++) { tA[c] = Sa[c] * wA[c] + v * kdA[c]; tB[c] = Sb[c] * wB[c] + v * kdB[c]; }
;         const float sa = -acc[0];
;         const float yq = acc[1];
; #pragma unroll
;         for (int c = 0; c < 8; c++) { Sa[c] = tA[c] + sa * kaA[c]; Sb[c] = tB[c] + sa * kaB[c]; }
;         const float y = yq + sa * c1 + v * c2;
;         if (quad == 0) by[s * 64 + row] = y;
;       }
	v_fmac_f32_dpp v8, v120, v32 row_newbcast:0 row_mask:0xf bank_mask:0xf
	v_fmac_f32_dpp v9, v120, v32 row_newbcast:1 row_mask:0xf bank_mask:0xf
	v_fmac_f32_dpp v10, v120, v32 row_newbcast:2 row_mask:0xf bank_mask:0xf
	v_fmac_f32_dpp v11, v120, v32 row_newbcast:3 row_mask:0xf bank_mask:0xf
	v_fmac_f32_dpp v12, v120, v32 row_newbcast:4 row_mask:0xf bank_mask:0xf
	v_fmac_f32_dpp v13, v120, v32 row_newbcast:5 row_mask:0xf bank_mask:0xf
	v_fmac_f32_dpp v14, v120, v32 row_newbcast:6 row_mask:0xf bank_mask:0xf
	v_fmac_f32_dpp v15, v120, v32 row_newbcast:7 row_mask:0xf bank_mask:0xf
	v_fmac_f32_dpp v16, v120, v32 row_newbcast:8 row_mask:0xf bank_mask:0xf
	v_fmac_f32_dpp v17, v120, v32 row_newbcast:9 row_mask:0xf bank_mask:0xf
	v_fmac_f32_dpp v18, v120, v32 row_newbcast:10 row_mask:0xf bank_mask:0xf
	v_fmac_f32_dpp v19, v120, v32 row_newbcast:11 row_mask:0xf bank_mask:0xf
	v_fmac_f32_dpp v20, v120, v32 row_newbcast:12 row_mask:0xf bank_mask:0xf
	v_fmac_f32_dpp v21, v120, v32 row_newbcast:13 row_mask:0xf bank_mask:0xf
	v_fmac_f32_dpp v22, v120, v32 row_newbcast:14 row_mask:0xf bank_mask:0xf
	v_fmac_f32_dpp v23, v120, v32 row_newbcast:15 row_mask:0xf bank_mask:0xf
	v_fma_f32 v109, -v32, v140, v33
	v_fma_f32 v109, v138, v141, v109
	ds_write_b32 v107, v109 offset:13312
	v_cvt_pk_bf16_f32 v24, v8, v9
	v_cvt_pk_bf16_f32 v25, v10, v11
	v_cvt_pk_bf16_f32 v26, v12, v13
	v_cvt_pk_bf16_f32 v27, v14, v15
	v_cvt_pk_bf16_f32 v28, v16, v17
	v_cvt_pk_bf16_f32 v29, v18, v19
	s_waitcnt lgkmcnt(10)
	v_mfma_f32_16x16x32_bf16 v[32:35], v[40:43], v[24:27], 0
	v_cvt_pk_bf16_f32 v30, v20, v21
	v_cvt_pk_bf16_f32 v31, v22, v23
	v_fmac_f32_dpp v8, v65, v66 row_newbcast:0 row_mask:0xf bank_mask:0xf
	v_fmac_f32_dpp v9, v65, v66 row_newbcast:1 row_mask:0xf bank_mask:0xf
	v_mfma_f32_16x16x32_bf16 v[32:35], v[44:47], v[28:31], v[32:35]
	v_fmac_f32_dpp v10, v65, v66 row_newbcast:2 row_mask:0xf bank_mask:0xf
	v_fmac_f32_dpp v11, v65, v66 row_newbcast:3 row_mask:0xf bank_mask:0xf
	ds_read_b128 v[112:115], v104 offset:5888
	v_fmac_f32_dpp v12, v65, v66 row_newbcast:4 row_mask:0xf bank_mask:0xf
	v_fmac_f32_dpp v13, v65, v66 row_newbcast:5 row_mask:0xf bank_mask:0xf
	ds_read_b128 v[116:119], v104 offset:5904
	v_fmac_f32_dpp v14, v65, v66 row_newbcast:6 row_mask:0xf bank_mask:0xf
	v_fmac_f32_dpp v15, v65, v66 row_newbcast:7 row_mask:0xf bank_mask:0xf
	ds_read_b32 v137, v105 offset:22272
	v_fmac_f32_dpp v16, v65, v66 row_newbcast:8 row_mask:0xf bank_mask:0xf
	v_fmac_f32_dpp v17, v65, v66 row_newbcast:9 row_mask:0xf bank_mask:0xf
	ds_read_b32 v138, v107 offset:5888
	v_fmac_f32_dpp v18, v65, v66 row_newbcast:10 row_mask:0xf bank_mask:0xf
	v_fmac_f32_dpp v19, v65, v66 row_newbcast:11 row_mask:0xf bank_mask:0xf
	ds_read_b32 v136, v105 offset:5888
	v_fmac_f32_dpp v20, v65, v66 row_newbcast:12 row_mask:0xf bank_mask:0xf
	v_fmac_f32_dpp v21, v65, v66 row_newbcast:13 row_mask:0xf bank_mask:0xf
	ds_read_b32 v120, v105 offset:14080
	v_fmac_f32_dpp v22, v65, v66 row_newbcast:14 row_mask:0xf bank_mask:0xf
	v_fmac_f32_dpp v23, v65, v66 row_newbcast:15 row_mask:0xf bank_mask:0xf
	ds_read_b64 v[140:141], v108 offset:49336
	s_waitcnt lgkmcnt(15)
	v_fmac_f32_dpp v8, v48, v32 row_newbcast:0 row_mask:0xf bank_mask:0xf
	v_fmac_f32_dpp v9, v48, v32 row_newbcast:1 row_mask:0xf bank_mask:0xf
	v_fmac_f32_dpp v10, v48, v32 row_newbcast:2 row_mask:0xf bank_mask:0xf
	v_fmac_f32_dpp v11, v48, v32 row_newbcast:3 row_mask:0xf bank_mask:0xf
	v_fmac_f32_dpp v12, v48, v32 row_newbcast:4 row_mask:0xf bank_mask:0xf
	v_fmac_f32_dpp v13, v48, v32 row_newbcast:5 row_mask:0xf bank_mask:0xf
	v_fmac_f32_dpp v14, v48, v32 row_newbcast:6 row_mask:0xf bank_mask:0xf
	v_fmac_f32_dpp v15, v48, v32 row_newbcast:7 row_mask:0xf bank_mask:0xf
	v_fmac_f32_dpp v16, v48, v32 row_newbcast:8 row_mask:0xf bank_mask:0xf
	v_fmac_f32_dpp v17, v48, v32 row_newbcast:9 row_mask:0xf bank_mask:0xf
	v_fmac_f32_dpp v18, v48, v32 row_newbcast:10 row_mask:0xf bank_mask:0xf
	v_fmac_f32_dpp v19, v48, v32 row_newbcast:11 row_mask:0xf bank_mask:0xf
	v_fmac_f32_dpp v20, v48, v32 row_newbcast:12 row_mask:0xf bank_mask:0xf
	v_fmac_f32_dpp v21, v48, v32 row_newbcast:13 row_mask:0xf bank_mask:0xf
	v_fmac_f32_dpp v22, v48, v32 row_newbcast:14 row_mask:0xf bank_mask:0xf
	v_fmac_f32_dpp v23, v48, v32 row_newbcast:15 row_mask:0xf bank_mask:0xf
	v_fma_f32 v109, -v32, v68, v33
	v_fma_f32 v109, v66, v69, v109
	ds_write_b32 v107, v109 offset:13568
	v_cvt_pk_bf16_f32 v24, v8, v9
	v_cvt_pk_bf16_f32 v25, v10, v11
	v_cvt_pk_bf16_f32 v26, v12, v13
	v_cvt_pk_bf16_f32 v27, v14, v15
	v_cvt_pk_bf16_f32 v28, v16, v17
	v_cvt_pk_bf16_f32 v29, v18, v19
	s_waitcnt lgkmcnt(11)
	v_mfma_f32_16x16x32_bf16 v[32:35], v[70:73], v[24:27], 0
	v_cvt_pk_bf16_f32 v30, v20, v21
	v_cvt_pk_bf16_f32 v31, v22, v23
	v_fmac_f32_dpp v8, v95, v96 row_newbcast:0 row_mask:0xf bank_mask:0xf
	v_fmac_f32_dpp v9, v95, v96 row_newbcast:1 row_mask:0xf bank_mask:0xf
	v_mfma_f32_16x16x32_bf16 v[32:35], v[74:77], v[28:31], v[32:35]
	v_fmac_f32_dpp v10, v95, v96 row_newbcast:2 row_mask:0xf bank_mask:0xf
	v_fmac_f32_dpp v11, v95, v96 row_newbcast:3 row_mask:0xf bank_mask:0xf
	ds_read_b128 v[40:43], v104 offset:6144
	v_fmac_f32_dpp v12, v95, v96 row_newbcast:4 row_mask:0xf bank_mask:0xf
	v_fmac_f32_dpp v13, v95, v96 row_newbcast:5 row_mask:0xf bank_mask:0xf
	ds_read_b128 v[44:47], v104 offset:6160
	v_fmac_f32_dpp v14, v95, v96 row_newbcast:6 row_mask:0xf bank_mask:0xf
	v_fmac_f32_dpp v15, v95, v96 row_newbcast:7 row_mask:0xf bank_mask:0xf
	ds_read_b32 v65, v105 offset:22528
	v_fmac_f32_dpp v16, v95, v96 row_newbcast:8 row_mask:0xf bank_mask:0xf
	v_fmac_f32_dpp v17, v95, v96 row_newbcast:9 row_mask:0xf bank_mask:0xf
	ds_read_b32 v66, v107 offset:6144
	v_fmac_f32_dpp v18, v95, v96 row_newbcast:10 row_mask:0xf bank_mask:0xf
	v_fmac_f32_dpp v19, v95, v96 row_newbcast:11 row_mask:0xf bank_mask:0xf
	ds_read_b32 v48, v105 offset:14336
	v_fmac_f32_dpp v20, v95, v96 row_newbcast:12 row_mask:0xf bank_mask:0xf
	v_fmac_f32_dpp v21, v95, v96 row_newbcast:13 row_mask:0xf bank_mask:0xf
	ds_read_b64 v[68:69], v108 offset:49344
	v_fmac_f32_dpp v22, v95, v96 row_newbcast:14 row_mask:0xf bank_mask:0xf
	v_fmac_f32_dpp v23, v95, v96 row_newbcast:15 row_mask:0xf bank_mask:0xf
	s_waitcnt lgkmcnt(15)
; __device__ __forceinline__ void phase_rwkv_scan(const Params& p, int l, const int tidx) {
;     ...
;       for (int s = 0; s < RTC; s++) {
;         const bf16x8 A0 = nA0, A1 = nA1;
;         const float wA[8] = {nw0.x, nw0.y, nw0.z, nw0.w, nw1.x, nw1.y, nw1.z, nw1.w};
;         const float wB[8] = {nw2.x, nw2.y, nw2.z, nw2.w, nw3.x, nw3.y, nw3.z, nw3.w};
;         const float kaA[8] = {nka0.x, nka0.y, nka0.z, nka0.w, nka1.x, nka1.y, nka1.z, nka1.w};
;         const float kaB[8] = {nka2.x, nka2.y, nka2.z, nka2.w, nka3.x, nka3.y, nka3.z, nka3.w};
;         const float kdA[8] = {nkd0.x, nkd0.y, nkd0.z, nkd0.w, nkd1.x, nkd1.y, nkd1.z, nkd1.w};
;         const float kdB[8] = {nkd2.x, nkd2.y, nkd2.z, nkd2.w, nkd3.x, nkd3.y, nkd3.z, nkd3.w};
;         const float v = nv;
;         float c1 = nc.x, c2 = nc.y;
;         asm volatile("" : "+v"(c1), "+v"(c2));
;         if (s + 1 < RTC) RW_LD(s + 1);
;         u32x4 pa = {pack2(Sa[0], Sa[1]), pack2(Sa[2], Sa[3]), pack2(Sa[4], Sa[5]), pack2(Sa[6], Sa[7])};
;         u32x4 pb = {pack2(Sb[0], Sb[1]), pack2(Sb[2], Sb[3]), pack2(Sb[4], Sb[5]), pack2(Sb[6], Sb[7])};
;         f32x4 acc = {0.f, 0.f, 0.f, 0.f};
;         acc = __builtin_amdgcn_mfma_f32_16x16x32_bf16(A0, __builtin_bit_cast(bf16x8, pa), acc, 0, 0, 0);
;         acc = __builtin_amdgcn_mfma_f32_16x16x32_bf16(A1, __builtin_bit_cast(bf16x8, pb), acc, 0, 0, 0);
;         float tA[8], tB[8];
; #pragma unroll
;         for (int c = 0; c < 8; c++) { tA[c] = Sa[c] * wA[c] + v * kdA[c]; tB[c] = Sb[c] * wB[c] + v * kdB[c]; }
;         const float sa = -acc[0];
;         const float yq = acc[1];
; #pragma unroll
;         for (int c = 0; c < 8; c++) { Sa[c] = tA[c] + sa * kaA[c]; Sb[c] = tB[c] + sa * kaB[c]; }
;         const float y = yq + sa * c1 + v * c2;
;         if (quad == 0) by[s * 64 + row] = y;
;       }
	v_fmac_f32_dpp v8, v78, v32 row_newbcast:0 row_mask:0xf bank_mask:0xf
	v_fmac_f32_dpp v9, v78, v32 row_newbcast:1 row_mask:0xf bank_mask:0xf
	v_fmac_f32_dpp v10, v78, v32 row_newbcast:2 row_mask:0xf bank_mask:0xf
	v_fmac_f32_dpp v11, v78, v32 row_newbcast:3 row_mask:0xf bank_mask:0xf
	v_fmac_f32_dpp v12, v78, v32 row_newbcast:4 row_mask:0xf bank_mask:0xf
	v_fmac_f32_dpp v13, v78, v32 row_newbcast:5 row_mask:0xf bank_mask:0xf
	v_fmac_f32_dpp v14, v78, v32 row_newbcast:6 row_mask:0xf bank_mask:0xf
	v_fmac_f32_dpp v15, v78, v32 row_newbcast:7 row_mask:0xf bank_mask:0xf
	v_fmac_f32_dpp v16, v78, v32 row_newbcast:8 row_mask:0xf bank_mask:0xf
	v_fmac_f32_dpp v17, v78, v32 row_newbcast:9 row_mask:0xf bank_mask:0xf
	v_fmac_f32_dpp v18, v78, v32 row_newbcast:10 row_mask:0xf bank_mask:0xf
	v_fmac_f32_dpp v19, v78, v32 row_newbcast:11 row_mask:0xf bank_mask:0xf
	v_fmac_f32_dpp v20, v78, v32 row_newbcast:12 row_mask:0xf bank_mask:0xf
	v_fmac_f32_dpp v21, v78, v32 row_newbcast:13 row_mask:0xf bank_mask:0xf
	v_fmac_f32_dpp v22, v78, v32 row_newbcast:14 row_mask:0xf bank_mask:0xf
	v_fmac_f32_dpp v23, v78, v32 row_newbcast:15 row_mask:0xf bank_mask:0xf
	v_fma_f32 v109, -v32, v98, v33
	v_fma_f32 v109, v96, v99, v109
	ds_write_b32 v107, v109 offset:13824
	v_cvt_pk_bf16_f32 v24, v8, v9
	v_cvt_pk_bf16_f32 v25, v10, v11
	v_cvt_pk_bf16_f32 v26, v12, v13
	v_cvt_pk_bf16_f32 v27, v14, v15
	v_cvt_pk_bf16_f32 v28, v16, v17
	v_cvt_pk_bf16_f32 v29, v18, v19
	s_waitcnt lgkmcnt(11)
	v_mfma_f32_16x16x32_bf16 v[32:35], v[112:115], v[24:27], 0
	v_cvt_pk_bf16_f32 v30, v20, v21
	v_cvt_pk_bf16_f32 v31, v22, v23
	v_fmac_f32_dpp v8, v137, v138 row_newbcast:0 row_mask:0xf bank_mask:0xf
	v_fmac_f32_dpp v9, v137, v138 row_newbcast:1 row_mask:0xf bank_mask:0xf
	v_mfma_f32_16x16x32_bf16 v[32:35], v[116:119], v[28:31], v[32:35]
	v_fmac_f32_dpp v10, v137, v138 row_newbcast:2 row_mask:0xf bank_mask:0xf
	v_fmac_f32_dpp v11, v137, v138 row_newbcast:3 row_mask:0xf bank_mask:0xf
	ds_read_b128 v[70:73], v104 offset:6400
	v_fmac_f32_dpp v12, v137, v138 row_newbcast:4 row_mask:0xf bank_mask:0xf
	v_fmac_f32_dpp v13, v137, v138 row_newbcast:5 row_mask:0xf bank_mask:0xf
	ds_read_b128 v[74:77], v104 offset:6416
	v_fmac_f32_dpp v14, v137, v138 row_newbcast:6 row_mask:0xf bank_mask:0xf
	v_fmac_f32_dpp v15, v137, v138 row_newbcast:7 row_mask:0xf bank_mask:0xf
	ds_read_b32 v95, v105 offset:22784
	v_fmac_f32_dpp v16, v137, v138 row_newbcast:8 row_mask:0xf bank_mask:0xf
	v_fmac_f32_dpp v17, v137, v138 row_newbcast:9 row_mask:0xf bank_mask:0xf
	ds_read_b32 v96, v107 offset:6400
	v_fmac_f32_dpp v18, v137, v138 row_newbcast:10 row_mask:0xf bank_mask:0xf
	v_fmac_f32_dpp v19, v137, v138 row_newbcast:11 row_mask:0xf bank_mask:0xf
	ds_read_b32 v78, v105 offset:14592
	v_fmac_f32_dpp v20, v137, v138 row_newbcast:12 row_mask:0xf bank_mask:0xf
	v_fmac_f32_dpp v21, v137, v138 row_newbcast:13 row_mask:0xf bank_mask:0xf
	ds_read_b64 v[98:99], v108 offset:49352
	v_fmac_f32_dpp v22, v137, v138 row_newbcast:14 row_mask:0xf bank_mask:0xf
	v_fmac_f32_dpp v23, v137, v138 row_newbcast:15 row_mask:0xf bank_mask:0xf
	s_waitcnt lgkmcnt(14)
	v_fmac_f32_dpp v8, v120, v32 row_newbcast:0 row_mask:0xf bank_mask:0xf
	v_fmac_f32_dpp v9, v120, v32 row_newbcast:1 row_mask:0xf bank_mask:0xf
	v_fmac_f32_dpp v10, v120, v32 row_newbcast:2 row_mask:0xf bank_mask:0xf
	v_fmac_f32_dpp v11, v120, v32 row_newbcast:3 row_mask:0xf bank_mask:0xf
	v_fmac_f32_dpp v12, v120, v32 row_newbcast:4 row_mask:0xf bank_mask:0xf
	v_fmac_f32_dpp v13, v120, v32 row_newbcast:5 row_mask:0xf bank_mask:0xf
	v_fmac_f32_dpp v14, v120, v32 row_newbcast:6 row_mask:0xf bank_mask:0xf
	v_fmac_f32_dpp v15, v120, v32 row_newbcast:7 row_mask:0xf bank_mask:0xf
	v_fmac_f32_dpp v16, v120, v32 row_newbcast:8 row_mask:0xf bank_mask:0xf
	v_fmac_f32_dpp v17, v120, v32 row_newbcast:9 row_mask:0xf bank_mask:0xf
	v_fmac_f32_dpp v18, v120, v32 row_newbcast:10 row_mask:0xf bank_mask:0xf
	v_fmac_f32_dpp v19, v120, v32 row_newbcast:11 row_mask:0xf bank_mask:0xf
	v_fmac_f32_dpp v20, v120, v32 row_newbcast:12 row_mask:0xf bank_mask:0xf
	v_fmac_f32_dpp v21, v120, v32 row_newbcast:13 row_mask:0xf bank_mask:0xf
	v_fmac_f32_dpp v22, v120, v32 row_newbcast:14 row_mask:0xf bank_mask:0xf
	v_fmac_f32_dpp v23, v120, v32 row_newbcast:15 row_mask:0xf bank_mask:0xf
	v_fma_f32 v109, -v32, v140, v33
	v_fma_f32 v109, v138, v141, v109
	v_mul_f32_dpp v8, v136, v8 row_newbcast:0 row_mask:0xf bank_mask:0xf
	v_mul_f32_dpp v9, v136, v9 row_newbcast:1 row_mask:0xf bank_mask:0xf
	v_mul_f32_dpp v10, v136, v10 row_newbcast:2 row_mask:0xf bank_mask:0xf
	v_mul_f32_dpp v11, v136, v11 row_newbcast:3 row_mask:0xf bank_mask:0xf
	v_mul_f32_dpp v12, v136, v12 row_newbcast:4 row_mask:0xf bank_mask:0xf
	v_mul_f32_dpp v13, v136, v13 row_newbcast:5 row_mask:0xf bank_mask:0xf
	v_mul_f32_dpp v14, v136, v14 row_newbcast:6 row_mask:0xf bank_mask:0xf
	v_mul_f32_dpp v15, v136, v15 row_newbcast:7 row_mask:0xf bank_mask:0xf
	v_mul_f32_dpp v16, v136, v16 row_newbcast:8 row_mask:0xf bank_mask:0xf
	v_mul_f32_dpp v17, v136, v17 row_newbcast:9 row_mask:0xf bank_mask:0xf
	v_mul_f32_dpp v18, v136, v18 row_newbcast:10 row_mask:0xf bank_mask:0xf
	v_mul_f32_dpp v19, v136, v19 row_newbcast:11 row_mask:0xf bank_mask:0xf
	v_mul_f32_dpp v20, v136, v20 row_newbcast:12 row_mask:0xf bank_mask:0xf
	v_mul_f32_dpp v21, v136, v21 row_newbcast:13 row_mask:0xf bank_mask:0xf
	v_mul_f32_dpp v22, v136, v22 row_newbcast:14 row_mask:0xf bank_mask:0xf
	v_mul_f32_dpp v23, v136, v23 row_newbcast:15 row_mask:0xf bank_mask:0xf
	ds_write_b32 v107, v109 offset:14080
	v_cvt_pk_bf16_f32 v24, v8, v9
	v_cvt_pk_bf16_f32 v25, v10, v11
	v_cvt_pk_bf16_f32 v26, v12, v13
	v_cvt_pk_bf16_f32 v27, v14, v15
	v_cvt_pk_bf16_f32 v28, v16, v17
	v_cvt_pk_bf16_f32 v29, v18, v19
	s_waitcnt lgkmcnt(10)
; __device__ __forceinline__ void phase_rwkv_scan(const Params& p, int l, const int tidx) {
;     ...
;       for (int s = 0; s < RTC; s++) {
;         const bf16x8 A0 = nA0, A1 = nA1;
;         const float wA[8] = {nw0.x, nw0.y, nw0.z, nw0.w, nw1.x, nw1.y, nw1.z, nw1.w};
;         const float wB[8] = {nw2.x, nw2.y, nw2.z, nw2.w, nw3.x, nw3.y, nw3.z, nw3.w};
;         const float kaA[8] = {nka0.x, nka0.y, nka0.z, nka0.w, nka1.x, nka1.y, nka1.z, nka1.w};
;         const float kaB[8] = {nka2.x, nka2.y, nka2.z, nka2.w, nka3.x, nka3.y, nka3.z, nka3.w};
;         const float kdA[8] = {nkd0.x, nkd0.y, nkd0.z, nkd0.w, nkd1.x, nkd1.y, nkd1.z, nkd1.w};
;         const float kdB[8] = {nkd2.x, nkd2.y, nkd2.z, nkd2.w, nkd3.x, nkd3.y, nkd3.z, nkd3.w};
;         const float v = nv;
;         float c1 = nc.x, c2 = nc.y;
;         asm volatile("" : "+v"(c1), "+v"(c2));
;         if (s + 1 < RTC) RW_LD(s + 1);
;         u32x4 pa = {pack2(Sa[0], Sa[1]), pack2(Sa[2], Sa[3]), pack2(Sa[4], Sa[5]), pack2(Sa[6], Sa[7])};
;         u32x4 pb = {pack2(Sb[0], Sb[1]), pack2(Sb[2], Sb[3]), pack2(Sb[4], Sb[5]), pack2(Sb[6], Sb[7])};
;         f32x4 acc = {0.f, 0.f, 0.f, 0.f};
;         acc = __builtin_amdgcn_mfma_f32_16x16x32_bf16(A0, __builtin_bit_cast(bf16x8, pa), acc, 0, 0, 0);
;         acc = __builtin_amdgcn_mfma_f32_16x16x32_bf16(A1, __builtin_bit_cast(bf16x8, pb), acc, 0, 0, 0);
;         float tA[8], tB[8];
; #pragma unroll
;         for (int c = 0; c < 8; c++) { tA[c] = Sa[c] * wA[c] + v * kdA[c]; tB[c] = Sb[c] * wB[c] + v * kdB[c]; }
;         const float sa = -acc[0];
;         const float yq = acc[1];
; #pragma unroll
;         for (int c = 0; c < 8; c++) { Sa[c] = tA[c] + sa * kaA[c]; Sb[c] = tB[c] + sa * kaB[c]; }
;         const float y = yq + sa * c1 + v * c2;
;         if (quad == 0) by[s * 64 + row] = y;
;       }
	v_mfma_f32_16x16x32_bf16 v[32:35], v[40:43], v[24:27], 0
	v_cvt_pk_bf16_f32 v30, v20, v21
	v_cvt_pk_bf16_f32 v31, v22, v23
	v_fmac_f32_dpp v8, v65, v66 row_newbcast:0 row_mask:0xf bank_mask:0xf
	v_fmac_f32_dpp v9, v65, v66 row_newbcast:1 row_mask:0xf bank_mask:0xf
	v_mfma_f32_16x16x32_bf16 v[32:35], v[44:47], v[28:31], v[32:35]
	v_fmac_f32_dpp v10, v65, v66 row_newbcast:2 row_mask:0xf bank_mask:0xf
	v_fmac_f32_dpp v11, v65, v66 row_newbcast:3 row_mask:0xf bank_mask:0xf
	ds_read_b128 v[112:115], v104 offset:6656
	v_fmac_f32_dpp v12, v65, v66 row_newbcast:4 row_mask:0xf bank_mask:0xf
	v_fmac_f32_dpp v13, v65, v66 row_newbcast:5 row_mask:0xf bank_mask:0xf
	ds_read_b128 v[116:119], v104 offset:6672
	v_fmac_f32_dpp v14, v65, v66 row_newbcast:6 row_mask:0xf bank_mask:0xf
	v_fmac_f32_dpp v15, v65, v66 row_newbcast:7 row_mask:0xf bank_mask:0xf
	ds_read_b32 v137, v105 offset:23040
	v_fmac_f32_dpp v16, v65, v66 row_newbcast:8 row_mask:0xf bank_mask:0xf
	v_fmac_f32_dpp v17, v65, v66 row_newbcast:9 row_mask:0xf bank_mask:0xf
	ds_read_b32 v138, v107 offset:6656
	v_fmac_f32_dpp v18, v65, v66 row_newbcast:10 row_mask:0xf bank_mask:0xf
	v_fmac_f32_dpp v19, v65, v66 row_newbcast:11 row_mask:0xf bank_mask:0xf
	ds_read_b32 v120, v105 offset:14848
	v_fmac_f32_dpp v20, v65, v66 row_newbcast:12 row_mask:0xf bank_mask:0xf
	v_fmac_f32_dpp v21, v65, v66 row_newbcast:13 row_mask:0xf bank_mask:0xf
	ds_read_b64 v[140:141], v108 offset:49360
	v_fmac_f32_dpp v22, v65, v66 row_newbcast:14 row_mask:0xf bank_mask:0xf
	v_fmac_f32_dpp v23, v65, v66 row_newbcast:15 row_mask:0xf bank_mask:0xf
	s_waitcnt lgkmcnt(14)
	v_fmac_f32_dpp v8, v48, v32 row_newbcast:0 row_mask:0xf bank_mask:0xf
	v_fmac_f32_dpp v9, v48, v32 row_newbcast:1 row_mask:0xf bank_mask:0xf
	v_fmac_f32_dpp v10, v48, v32 row_newbcast:2 row_mask:0xf bank_mask:0xf
	v_fmac_f32_dpp v11, v48, v32 row_newbcast:3 row_mask:0xf bank_mask:0xf
	v_fmac_f32_dpp v12, v48, v32 row_newbcast:4 row_mask:0xf bank_mask:0xf
	v_fmac_f32_dpp v13, v48, v32 row_newbcast:5 row_mask:0xf bank_mask:0xf
	v_fmac_f32_dpp v14, v48, v32 row_newbcast:6 row_mask:0xf bank_mask:0xf
	v_fmac_f32_dpp v15, v48, v32 row_newbcast:7 row_mask:0xf bank_mask:0xf
	v_fmac_f32_dpp v16, v48, v32 row_newbcast:8 row_mask:0xf bank_mask:0xf
	v_fmac_f32_dpp v17, v48, v32 row_newbcast:9 row_mask:0xf bank_mask:0xf
	v_fmac_f32_dpp v18, v48, v32 row_newbcast:10 row_mask:0xf bank_mask:0xf
	v_fmac_f32_dpp v19, v48, v32 row_newbcast:11 row_mask:0xf bank_mask:0xf
	v_fmac_f32_dpp v20, v48, v32 row_newbcast:12 row_mask:0xf bank_mask:0xf
	v_fmac_f32_dpp v21, v48, v32 row_newbcast:13 row_mask:0xf bank_mask:0xf
	v_fmac_f32_dpp v22, v48, v32 row_newbcast:14 row_mask:0xf bank_mask:0xf
	v_fmac_f32_dpp v23, v48, v32 row_newbcast:15 row_mask:0xf bank_mask:0xf
	v_fma_f32 v109, -v32, v68, v33
	v_fma_f32 v109, v66, v69, v109
	ds_write_b32 v107, v109 offset:14336
	v_cvt_pk_bf16_f32 v24, v8, v9
	v_cvt_pk_bf16_f32 v25, v10, v11
	v_cvt_pk_bf16_f32 v26, v12, v13
	v_cvt_pk_bf16_f32 v27, v14, v15
	v_cvt_pk_bf16_f32 v28, v16, v17
	v_cvt_pk_bf16_f32 v29, v18, v19
	s_waitcnt lgkmcnt(10)
	v_mfma_f32_16x16x32_bf16 v[32:35], v[70:73], v[24:27], 0
	v_cvt_pk_bf16_f32 v30, v20, v21
	v_cvt_pk_bf16_f32 v31, v22, v23
	v_fmac_f32_dpp v8, v95, v96 row_newbcast:0 row_mask:0xf bank_mask:0xf
	v_fmac_f32_dpp v9, v95, v96 row_newbcast:1 row_mask:0xf bank_mask:0xf
	v_mfma_f32_16x16x32_bf16 v[32:35], v[74:77], v[28:31], v[32:35]
	v_fmac_f32_dpp v10, v95, v96 row_newbcast:2 row_mask:0xf bank_mask:0xf
	v_fmac_f32_dpp v11, v95, v96 row_newbcast:3 row_mask:0xf bank_mask:0xf
	ds_read_b128 v[40:43], v104 offset:6912
	v_fmac_f32_dpp v12, v95, v96 row_newbcast:4 row_mask:0xf bank_mask:0xf
	v_fmac_f32_dpp v13, v95, v96 row_newbcast:5 row_mask:0xf bank_mask:0xf
	ds_read_b128 v[44:47], v104 offset:6928
	v_fmac_f32_dpp v14, v95, v96 row_newbcast:6 row_mask:0xf bank_mask:0xf
	v_fmac_f32_dpp v15, v95, v96 row_newbcast:7 row_mask:0xf bank_mask:0xf
	ds_read_b32 v65, v105 offset:23296
	v_fmac_f32_dpp v16, v95, v96 row_newbcast:8 row_mask:0xf bank_mask:0xf
	v_fmac_f32_dpp v17, v95, v96 row_newbcast:9 row_mask:0xf bank_mask:0xf
	ds_read_b32 v66, v107 offset:6912
	v_fmac_f32_dpp v18, v95, v96 row_newbcast:10 row_mask:0xf bank_mask:0xf
	v_fmac_f32_dpp v19, v95, v96 row_newbcast:11 row_mask:0xf bank_mask:0xf
	ds_read_b32 v48, v105 offset:15104
	v_fmac_f32_dpp v20, v95, v96 row_newbcast:12 row_mask:0xf bank_mask:0xf
	v_fmac_f32_dpp v21, v95, v96 row_newbcast:13 row_mask:0xf bank_mask:0xf
	ds_read_b64 v[68:69], v108 offset:49368
	v_fmac_f32_dpp v22, v95, v96 row_newbcast:14 row_mask:0xf bank_mask:0xf
	v_fmac_f32_dpp v23, v95, v96 row_newbcast:15 row_mask:0xf bank_mask:0xf
	s_waitcnt lgkmcnt(14)
	v_fmac_f32_dpp v8, v78, v32 row_newbcast:0 row_mask:0xf bank_mask:0xf
	v_fmac_f32_dpp v9, v78, v32 row_newbcast:1 row_mask:0xf bank_mask:0xf
	v_fmac_f32_dpp v10, v78, v32 row_newbcast:2 row_mask:0xf bank_mask:0xf
	v_fmac_f32_dpp v11, v78, v32 row_newbcast:3 row_mask:0xf bank_mask:0xf
	v_fmac_f32_dpp v12, v78, v32 row_newbcast:4 row_mask:0xf bank_mask:0xf
	v_fmac_f32_dpp v13, v78, v32 row_newbcast:5 row_mask:0xf bank_mask:0xf
	v_fmac_f32_dpp v14, v78, v32 row_newbcast:6 row_mask:0xf bank_mask:0xf
	v_fmac_f32_dpp v15, v78, v32 row_newbcast:7 row_mask:0xf bank_mask:0xf
	v_fmac_f32_dpp v16, v78, v32 row_newbcast:8 row_mask:0xf bank_mask:0xf
	v_fmac_f32_dpp v17, v78, v32 row_newbcast:9 row_mask:0xf bank_mask:0xf
	v_fmac_f32_dpp v18, v78, v32 row_newbcast:10 row_mask:0xf bank_mask:0xf
	v_fmac_f32_dpp v19, v78, v32 row_newbcast:11 row_mask:0xf bank_mask:0xf
	v_fmac_f32_dpp v20, v78, v32 row_newbcast:12 row_mask:0xf bank_mask:0xf
	v_fmac_f32_dpp v21, v78, v32 row_newbcast:13 row_mask:0xf bank_mask:0xf
	v_fmac_f32_dpp v22, v78, v32 row_newbcast:14 row_mask:0xf bank_mask:0xf
	v_fmac_f32_dpp v23, v78, v32 row_newbcast:15 row_mask:0xf bank_mask:0xf
	v_fma_f32 v109, -v32, v98, v33
	v_fma_f32 v109, v96, v99, v109
	ds_write_b32 v107, v109 offset:14592
	v_cvt_pk_bf16_f32 v24, v8, v9
	v_cvt_pk_bf16_f32 v25, v10, v11
	v_cvt_pk_bf16_f32 v26, v12, v13
	v_cvt_pk_bf16_f32 v27, v14, v15
	v_cvt_pk_bf16_f32 v28, v16, v17
	v_cvt_pk_bf16_f32 v29, v18, v19
	s_waitcnt lgkmcnt(10)
; __device__ __forceinline__ void phase_rwkv_scan(const Params& p, int l, const int tidx) {
;     ...
;       for (int s = 0; s < RTC; s++) {
;         const bf16x8 A0 = nA0, A1 = nA1;
;         const float wA[8] = {nw0.x, nw0.y, nw0.z, nw0.w, nw1.x, nw1.y, nw1.z, nw1.w};
;         const float wB[8] = {nw2.x, nw2.y, nw2.z, nw2.w, nw3.x, nw3.y, nw3.z, nw3.w};
;         const float kaA[8] = {nka0.x, nka0.y, nka0.z, nka0.w, nka1.x, nka1.y, nka1.z, nka1.w};
;         const float kaB[8] = {nka2.x, nka2.y, nka2.z, nka2.w, nka3.x, nka3.y, nka3.z, nka3.w};
;         const float kdA[8] = {nkd0.x, nkd0.y, nkd0.z, nkd0.w, nkd1.x, nkd1.y, nkd1.z, nkd1.w};
;         const float kdB[8] = {nkd2.x, nkd2.y, nkd2.z, nkd2.w, nkd3.x, nkd3.y, nkd3.z, nkd3.w};
;         const float v = nv;
;         float c1 = nc.x, c2 = nc.y;
;         asm volatile("" : "+v"(c1), "+v"(c2));
;         if (s + 1 < RTC) RW_LD(s + 1);
;         u32x4 pa = {pack2(Sa[0], Sa[1]), pack2(Sa[2], Sa[3]), pack2(Sa[4], Sa[5]), pack2(Sa[6], Sa[7])};
;         u32x4 pb = {pack2(Sb[0], Sb[1]), pack2(Sb[2], Sb[3]), pack2(Sb[4], Sb[5]), pack2(Sb[6], Sb[7])};
;         f32x4 acc = {0.f, 0.f, 0.f, 0.f};
;         acc = __builtin_amdgcn_mfma_f32_16x16x32_bf16(A0, __builtin_bit_cast(bf16x8, pa), acc, 0, 0, 0);
;         acc = __builtin_amdgcn_mfma_f32_16x16x32_bf16(A1, __builtin_bit_cast(bf16x8, pb), acc, 0, 0, 0);
;         float tA[8], tB[8];
; #pragma unroll
;         for (int c = 0; c < 8; c++) { tA[c] = Sa[c] * wA[c] + v * kdA[c]; tB[c] = Sb[c] * wB[c] + v * kdB[c]; }
;         const float sa = -acc[0];
;         const float yq = acc[1];
; #pragma unroll
;         for (int c = 0; c < 8; c++) { Sa[c] = tA[c] + sa * kaA[c]; Sb[c] = tB[c] + sa * kaB[c]; }
;         const float y = yq + sa * c1 + v * c2;
;         if (quad == 0) by[s * 64 + row] = y;
;       }
	v_mfma_f32_16x16x32_bf16 v[32:35], v[112:115], v[24:27], 0
	v_cvt_pk_bf16_f32 v30, v20, v21
	v_cvt_pk_bf16_f32 v31, v22, v23
	v_fmac_f32_dpp v8, v137, v138 row_newbcast:0 row_mask:0xf bank_mask:0xf
	v_fmac_f32_dpp v9, v137, v138 row_newbcast:1 row_mask:0xf bank_mask:0xf
	v_mfma_f32_16x16x32_bf16 v[32:35], v[116:119], v[28:31], v[32:35]
	v_fmac_f32_dpp v10, v137, v138 row_newbcast:2 row_mask:0xf bank_mask:0xf
	v_fmac_f32_dpp v11, v137, v138 row_newbcast:3 row_mask:0xf bank_mask:0xf
	ds_read_b128 v[70:73], v104 offset:7168
	v_fmac_f32_dpp v12, v137, v138 row_newbcast:4 row_mask:0xf bank_mask:0xf
	v_fmac_f32_dpp v13, v137, v138 row_newbcast:5 row_mask:0xf bank_mask:0xf
	ds_read_b128 v[74:77], v104 offset:7184
	v_fmac_f32_dpp v14, v137, v138 row_newbcast:6 row_mask:0xf bank_mask:0xf
	v_fmac_f32_dpp v15, v137, v138 row_newbcast:7 row_mask:0xf bank_mask:0xf
	ds_read_b32 v95, v105 offset:23552
	v_fmac_f32_dpp v16, v137, v138 row_newbcast:8 row_mask:0xf bank_mask:0xf
	v_fmac_f32_dpp v17, v137, v138 row_newbcast:9 row_mask:0xf bank_mask:0xf
	ds_read_b32 v96, v107 offset:7168
	v_fmac_f32_dpp v18, v137, v138 row_newbcast:10 row_mask:0xf bank_mask:0xf
	v_fmac_f32_dpp v19, v137, v138 row_newbcast:11 row_mask:0xf bank_mask:0xf
	ds_read_b32 v78, v105 offset:15360
	v_fmac_f32_dpp v20, v137, v138 row_newbcast:12 row_mask:0xf bank_mask:0xf
	v_fmac_f32_dpp v21, v137, v138 row_newbcast:13 row_mask:0xf bank_mask:0xf
	ds_read_b64 v[98:99], v108 offset:49376
	v_fmac_f32_dpp v22, v137, v138 row_newbcast:14 row_mask:0xf bank_mask:0xf
	v_fmac_f32_dpp v23, v137, v138 row_newbcast:15 row_mask:0xf bank_mask:0xf
	s_waitcnt lgkmcnt(14)
	v_fmac_f32_dpp v8, v120, v32 row_newbcast:0 row_mask:0xf bank_mask:0xf
	v_fmac_f32_dpp v9, v120, v32 row_newbcast:1 row_mask:0xf bank_mask:0xf
	v_fmac_f32_dpp v10, v120, v32 row_newbcast:2 row_mask:0xf bank_mask:0xf
	v_fmac_f32_dpp v11, v120, v32 row_newbcast:3 row_mask:0xf bank_mask:0xf
	v_fmac_f32_dpp v12, v120, v32 row_newbcast:4 row_mask:0xf bank_mask:0xf
	v_fmac_f32_dpp v13, v120, v32 row_newbcast:5 row_mask:0xf bank_mask:0xf
	v_fmac_f32_dpp v14, v120, v32 row_newbcast:6 row_mask:0xf bank_mask:0xf
	v_fmac_f32_dpp v15, v120, v32 row_newbcast:7 row_mask:0xf bank_mask:0xf
	v_fmac_f32_dpp v16, v120, v32 row_newbcast:8 row_mask:0xf bank_mask:0xf
	v_fmac_f32_dpp v17, v120, v32 row_newbcast:9 row_mask:0xf bank_mask:0xf
	v_fmac_f32_dpp v18, v120, v32 row_newbcast:10 row_mask:0xf bank_mask:0xf
	v_fmac_f32_dpp v19, v120, v32 row_newbcast:11 row_mask:0xf bank_mask:0xf
	v_fmac_f32_dpp v20, v120, v32 row_newbcast:12 row_mask:0xf bank_mask:0xf
	v_fmac_f32_dpp v21, v120, v32 row_newbcast:13 row_mask:0xf bank_mask:0xf
	v_fmac_f32_dpp v22, v120, v32 row_newbcast:14 row_mask:0xf bank_mask:0xf
	v_fmac_f32_dpp v23, v120, v32 row_newbcast:15 row_mask:0xf bank_mask:0xf
	v_fma_f32 v109, -v32, v140, v33
	v_fma_f32 v109, v138, v141, v109
	ds_write_b32 v107, v109 offset:14848
	v_cvt_pk_bf16_f32 v24, v8, v9
	v_cvt_pk_bf16_f32 v25, v10, v11
	v_cvt_pk_bf16_f32 v26, v12, v13
	v_cvt_pk_bf16_f32 v27, v14, v15
	v_cvt_pk_bf16_f32 v28, v16, v17
	v_cvt_pk_bf16_f32 v29, v18, v19
	s_waitcnt lgkmcnt(10)
	v_mfma_f32_16x16x32_bf16 v[32:35], v[40:43], v[24:27], 0
	v_cvt_pk_bf16_f32 v30, v20, v21
	v_cvt_pk_bf16_f32 v31, v22, v23
	v_fmac_f32_dpp v8, v65, v66 row_newbcast:0 row_mask:0xf bank_mask:0xf
	v_fmac_f32_dpp v9, v65, v66 row_newbcast:1 row_mask:0xf bank_mask:0xf
	v_mfma_f32_16x16x32_bf16 v[32:35], v[44:47], v[28:31], v[32:35]
	v_fmac_f32_dpp v10, v65, v66 row_newbcast:2 row_mask:0xf bank_mask:0xf
	v_fmac_f32_dpp v11, v65, v66 row_newbcast:3 row_mask:0xf bank_mask:0xf
	ds_read_b128 v[112:115], v104 offset:7424
	v_fmac_f32_dpp v12, v65, v66 row_newbcast:4 row_mask:0xf bank_mask:0xf
	v_fmac_f32_dpp v13, v65, v66 row_newbcast:5 row_mask:0xf bank_mask:0xf
	ds_read_b128 v[116:119], v104 offset:7440
	v_fmac_f32_dpp v14, v65, v66 row_newbcast:6 row_mask:0xf bank_mask:0xf
	v_fmac_f32_dpp v15, v65, v66 row_newbcast:7 row_mask:0xf bank_mask:0xf
	ds_read_b32 v137, v105 offset:23808
	v_fmac_f32_dpp v16, v65, v66 row_newbcast:8 row_mask:0xf bank_mask:0xf
	v_fmac_f32_dpp v17, v65, v66 row_newbcast:9 row_mask:0xf bank_mask:0xf
	ds_read_b32 v138, v107 offset:7424
	v_fmac_f32_dpp v18, v65, v66 row_newbcast:10 row_mask:0xf bank_mask:0xf
	v_fmac_f32_dpp v19, v65, v66 row_newbcast:11 row_mask:0xf bank_mask:0xf
	ds_read_b32 v120, v105 offset:15616
	v_fmac_f32_dpp v20, v65, v66 row_newbcast:12 row_mask:0xf bank_mask:0xf
	v_fmac_f32_dpp v21, v65, v66 row_newbcast:13 row_mask:0xf bank_mask:0xf
	ds_read_b64 v[140:141], v108 offset:49384
	v_fmac_f32_dpp v22, v65, v66 row_newbcast:14 row_mask:0xf bank_mask:0xf
	v_fmac_f32_dpp v23, v65, v66 row_newbcast:15 row_mask:0xf bank_mask:0xf
	s_waitcnt lgkmcnt(14)
	v_fmac_f32_dpp v8, v48, v32 row_newbcast:0 row_mask:0xf bank_mask:0xf
	v_fmac_f32_dpp v9, v48, v32 row_newbcast:1 row_mask:0xf bank_mask:0xf
	v_fmac_f32_dpp v10, v48, v32 row_newbcast:2 row_mask:0xf bank_mask:0xf
	v_fmac_f32_dpp v11, v48, v32 row_newbcast:3 row_mask:0xf bank_mask:0xf
	v_fmac_f32_dpp v12, v48, v32 row_newbcast:4 row_mask:0xf bank_mask:0xf
	v_fmac_f32_dpp v13, v48, v32 row_newbcast:5 row_mask:0xf bank_mask:0xf
	v_fmac_f32_dpp v14, v48, v32 row_newbcast:6 row_mask:0xf bank_mask:0xf
	v_fmac_f32_dpp v15, v48, v32 row_newbcast:7 row_mask:0xf bank_mask:0xf
	v_fmac_f32_dpp v16, v48, v32 row_newbcast:8 row_mask:0xf bank_mask:0xf
	v_fmac_f32_dpp v17, v48, v32 row_newbcast:9 row_mask:0xf bank_mask:0xf
	v_fmac_f32_dpp v18, v48, v32 row_newbcast:10 row_mask:0xf bank_mask:0xf
	v_fmac_f32_dpp v19, v48, v32 row_newbcast:11 row_mask:0xf bank_mask:0xf
	v_fmac_f32_dpp v20, v48, v32 row_newbcast:12 row_mask:0xf bank_mask:0xf
	v_fmac_f32_dpp v21, v48, v32 row_newbcast:13 row_mask:0xf bank_mask:0xf
	v_fmac_f32_dpp v22, v48, v32 row_newbcast:14 row_mask:0xf bank_mask:0xf
	v_fmac_f32_dpp v23, v48, v32 row_newbcast:15 row_mask:0xf bank_mask:0xf
	v_fma_f32 v109, -v32, v68, v33
	v_fma_f32 v109, v66, v69, v109
	ds_write_b32 v107, v109 offset:15104
	v_cvt_pk_bf16_f32 v24, v8, v9
	v_cvt_pk_bf16_f32 v25, v10, v11
	v_cvt_pk_bf16_f32 v26, v12, v13
	v_cvt_pk_bf16_f32 v27, v14, v15
	v_cvt_pk_bf16_f32 v28, v16, v17
	v_cvt_pk_bf16_f32 v29, v18, v19
	s_waitcnt lgkmcnt(10)
; __device__ __forceinline__ void phase_rwkv_scan(const Params& p, int l, const int tidx) {
;     ...
;       for (int s = 0; s < RTC; s++) {
;         const bf16x8 A0 = nA0, A1 = nA1;
;         const float wA[8] = {nw0.x, nw0.y, nw0.z, nw0.w, nw1.x, nw1.y, nw1.z, nw1.w};
;         const float wB[8] = {nw2.x, nw2.y, nw2.z, nw2.w, nw3.x, nw3.y, nw3.z, nw3.w};
;         const float kaA[8] = {nka0.x, nka0.y, nka0.z, nka0.w, nka1.x, nka1.y, nka1.z, nka1.w};
;         const float kaB[8] = {nka2.x, nka2.y, nka2.z, nka2.w, nka3.x, nka3.y, nka3.z, nka3.w};
;         const float kdA[8] = {nkd0.x, nkd0.y, nkd0.z, nkd0.w, nkd1.x, nkd1.y, nkd1.z, nkd1.w};
;         const float kdB[8] = {nkd2.x, nkd2.y, nkd2.z, nkd2.w, nkd3.x, nkd3.y, nkd3.z, nkd3.w};
;         const float v = nv;
;         float c1 = nc.x, c2 = nc.y;
;         asm volatile("" : "+v"(c1), "+v"(c2));
;         if (s + 1 < RTC) RW_LD(s + 1);
;         u32x4 pa = {pack2(Sa[0], Sa[1]), pack2(Sa[2], Sa[3]), pack2(Sa[4], Sa[5]), pack2(Sa[6], Sa[7])};
;         u32x4 pb = {pack2(Sb[0], Sb[1]), pack2(Sb[2], Sb[3]), pack2(Sb[4], Sb[5]), pack2(Sb[6], Sb[7])};
;         f32x4 acc = {0.f, 0.f, 0.f, 0.f};
;         acc = __builtin_amdgcn_mfma_f32_16x16x32_bf16(A0, __builtin_bit_cast(bf16x8, pa), acc, 0, 0, 0);
;         acc = __builtin_amdgcn_mfma_f32_16x16x32_bf16(A1, __builtin_bit_cast(bf16x8, pb), acc, 0, 0, 0);
;         float tA[8], tB[8];
; #pragma unroll
;         for (int c = 0; c < 8; c++) { tA[c] = Sa[c] * wA[c] + v * kdA[c]; tB[c] = Sb[c] * wB[c] + v * kdB[c]; }
;         const float sa = -acc[0];
;         const float yq = acc[1];
; #pragma unroll
;         for (int c = 0; c < 8; c++) { Sa[c] = tA[c] + sa * kaA[c]; Sb[c] = tB[c] + sa * kaB[c]; }
;         const float y = yq + sa * c1 + v * c2;
;         if (quad == 0) by[s * 64 + row] = y;
;       }
	v_mfma_f32_16x16x32_bf16 v[32:35], v[70:73], v[24:27], 0
	v_cvt_pk_bf16_f32 v30, v20, v21
	v_cvt_pk_bf16_f32 v31, v22, v23
	v_fmac_f32_dpp v8, v95, v96 row_newbcast:0 row_mask:0xf bank_mask:0xf
	v_fmac_f32_dpp v9, v95, v96 row_newbcast:1 row_mask:0xf bank_mask:0xf
	v_mfma_f32_16x16x32_bf16 v[32:35], v[74:77], v[28:31], v[32:35]
	v_fmac_f32_dpp v10, v95, v96 row_newbcast:2 row_mask:0xf bank_mask:0xf
	v_fmac_f32_dpp v11, v95, v96 row_newbcast:3 row_mask:0xf bank_mask:0xf
	ds_read_b128 v[40:43], v104 offset:7680
	v_fmac_f32_dpp v12, v95, v96 row_newbcast:4 row_mask:0xf bank_mask:0xf
	v_fmac_f32_dpp v13, v95, v96 row_newbcast:5 row_mask:0xf bank_mask:0xf
	ds_read_b128 v[44:47], v104 offset:7696
	v_fmac_f32_dpp v14, v95, v96 row_newbcast:6 row_mask:0xf bank_mask:0xf
	v_fmac_f32_dpp v15, v95, v96 row_newbcast:7 row_mask:0xf bank_mask:0xf
	ds_read_b32 v65, v105 offset:24064
	v_fmac_f32_dpp v16, v95, v96 row_newbcast:8 row_mask:0xf bank_mask:0xf
	v_fmac_f32_dpp v17, v95, v96 row_newbcast:9 row_mask:0xf bank_mask:0xf
	ds_read_b32 v66, v107 offset:7680
	v_fmac_f32_dpp v18, v95, v96 row_newbcast:10 row_mask:0xf bank_mask:0xf
	v_fmac_f32_dpp v19, v95, v96 row_newbcast:11 row_mask:0xf bank_mask:0xf
	ds_read_b32 v48, v105 offset:15872
	v_fmac_f32_dpp v20, v95, v96 row_newbcast:12 row_mask:0xf bank_mask:0xf
	v_fmac_f32_dpp v21, v95, v96 row_newbcast:13 row_mask:0xf bank_mask:0xf
	ds_read_b64 v[68:69], v108 offset:49392
	v_fmac_f32_dpp v22, v95, v96 row_newbcast:14 row_mask:0xf bank_mask:0xf
	v_fmac_f32_dpp v23, v95, v96 row_newbcast:15 row_mask:0xf bank_mask:0xf
	s_waitcnt lgkmcnt(14)
	v_fmac_f32_dpp v8, v78, v32 row_newbcast:0 row_mask:0xf bank_mask:0xf
	v_fmac_f32_dpp v9, v78, v32 row_newbcast:1 row_mask:0xf bank_mask:0xf
	v_fmac_f32_dpp v10, v78, v32 row_newbcast:2 row_mask:0xf bank_mask:0xf
	v_fmac_f32_dpp v11, v78, v32 row_newbcast:3 row_mask:0xf bank_mask:0xf
	v_fmac_f32_dpp v12, v78, v32 row_newbcast:4 row_mask:0xf bank_mask:0xf
	v_fmac_f32_dpp v13, v78, v32 row_newbcast:5 row_mask:0xf bank_mask:0xf
	v_fmac_f32_dpp v14, v78, v32 row_newbcast:6 row_mask:0xf bank_mask:0xf
	v_fmac_f32_dpp v15, v78, v32 row_newbcast:7 row_mask:0xf bank_mask:0xf
	v_fmac_f32_dpp v16, v78, v32 row_newbcast:8 row_mask:0xf bank_mask:0xf
	v_fmac_f32_dpp v17, v78, v32 row_newbcast:9 row_mask:0xf bank_mask:0xf
	v_fmac_f32_dpp v18, v78, v32 row_newbcast:10 row_mask:0xf bank_mask:0xf
	v_fmac_f32_dpp v19, v78, v32 row_newbcast:11 row_mask:0xf bank_mask:0xf
	v_fmac_f32_dpp v20, v78, v32 row_newbcast:12 row_mask:0xf bank_mask:0xf
	v_fmac_f32_dpp v21, v78, v32 row_newbcast:13 row_mask:0xf bank_mask:0xf
	v_fmac_f32_dpp v22, v78, v32 row_newbcast:14 row_mask:0xf bank_mask:0xf
	v_fmac_f32_dpp v23, v78, v32 row_newbcast:15 row_mask:0xf bank_mask:0xf
	v_fma_f32 v109, -v32, v98, v33
	v_fma_f32 v109, v96, v99, v109
	ds_write_b32 v107, v109 offset:15360
	v_cvt_pk_bf16_f32 v24, v8, v9
	v_cvt_pk_bf16_f32 v25, v10, v11
	v_cvt_pk_bf16_f32 v26, v12, v13
	v_cvt_pk_bf16_f32 v27, v14, v15
	v_cvt_pk_bf16_f32 v28, v16, v17
	v_cvt_pk_bf16_f32 v29, v18, v19
	s_waitcnt lgkmcnt(10)
	v_mfma_f32_16x16x32_bf16 v[32:35], v[112:115], v[24:27], 0
	v_cvt_pk_bf16_f32 v30, v20, v21
	v_cvt_pk_bf16_f32 v31, v22, v23
	v_fmac_f32_dpp v8, v137, v138 row_newbcast:0 row_mask:0xf bank_mask:0xf
	v_fmac_f32_dpp v9, v137, v138 row_newbcast:1 row_mask:0xf bank_mask:0xf
	v_mfma_f32_16x16x32_bf16 v[32:35], v[116:119], v[28:31], v[32:35]
	v_fmac_f32_dpp v10, v137, v138 row_newbcast:2 row_mask:0xf bank_mask:0xf
	v_fmac_f32_dpp v11, v137, v138 row_newbcast:3 row_mask:0xf bank_mask:0xf
	ds_read_b128 v[70:73], v104 offset:7936
	v_fmac_f32_dpp v12, v137, v138 row_newbcast:4 row_mask:0xf bank_mask:0xf
	v_fmac_f32_dpp v13, v137, v138 row_newbcast:5 row_mask:0xf bank_mask:0xf
	ds_read_b128 v[74:77], v104 offset:7952
	v_fmac_f32_dpp v14, v137, v138 row_newbcast:6 row_mask:0xf bank_mask:0xf
	v_fmac_f32_dpp v15, v137, v138 row_newbcast:7 row_mask:0xf bank_mask:0xf
	ds_read_b32 v95, v105 offset:24320
	v_fmac_f32_dpp v16, v137, v138 row_newbcast:8 row_mask:0xf bank_mask:0xf
	v_fmac_f32_dpp v17, v137, v138 row_newbcast:9 row_mask:0xf bank_mask:0xf
	ds_read_b32 v96, v107 offset:7936
	v_fmac_f32_dpp v18, v137, v138 row_newbcast:10 row_mask:0xf bank_mask:0xf
	v_fmac_f32_dpp v19, v137, v138 row_newbcast:11 row_mask:0xf bank_mask:0xf
	ds_read_b32 v94, v105 offset:7936
	v_fmac_f32_dpp v20, v137, v138 row_newbcast:12 row_mask:0xf bank_mask:0xf
	v_fmac_f32_dpp v21, v137, v138 row_newbcast:13 row_mask:0xf bank_mask:0xf
	ds_read_b32 v78, v105 offset:16128
	v_fmac_f32_dpp v22, v137, v138 row_newbcast:14 row_mask:0xf bank_mask:0xf
	v_fmac_f32_dpp v23, v137, v138 row_newbcast:15 row_mask:0xf bank_mask:0xf
	ds_read_b64 v[98:99], v108 offset:49400
	s_waitcnt lgkmcnt(15)
	v_fmac_f32_dpp v8, v120, v32 row_newbcast:0 row_mask:0xf bank_mask:0xf
	v_fmac_f32_dpp v9, v120, v32 row_newbcast:1 row_mask:0xf bank_mask:0xf
	v_fmac_f32_dpp v10, v120, v32 row_newbcast:2 row_mask:0xf bank_mask:0xf
	v_fmac_f32_dpp v11, v120, v32 row_newbcast:3 row_mask:0xf bank_mask:0xf
	v_fmac_f32_dpp v12, v120, v32 row_newbcast:4 row_mask:0xf bank_mask:0xf
	v_fmac_f32_dpp v13, v120, v32 row_newbcast:5 row_mask:0xf bank_mask:0xf
	v_fmac_f32_dpp v14, v120, v32 row_newbcast:6 row_mask:0xf bank_mask:0xf
	v_fmac_f32_dpp v15, v120, v32 row_newbcast:7 row_mask:0xf bank_mask:0xf
	v_fmac_f32_dpp v16, v120, v32 row_newbcast:8 row_mask:0xf bank_mask:0xf
	v_fmac_f32_dpp v17, v120, v32 row_newbcast:9 row_mask:0xf bank_mask:0xf
	v_fmac_f32_dpp v18, v120, v32 row_newbcast:10 row_mask:0xf bank_mask:0xf
	v_fmac_f32_dpp v19, v120, v32 row_newbcast:11 row_mask:0xf bank_mask:0xf
	v_fmac_f32_dpp v20, v120, v32 row_newbcast:12 row_mask:0xf bank_mask:0xf
	v_fmac_f32_dpp v21, v120, v32 row_newbcast:13 row_mask:0xf bank_mask:0xf
	v_fmac_f32_dpp v22, v120, v32 row_newbcast:14 row_mask:0xf bank_mask:0xf
	v_fmac_f32_dpp v23, v120, v32 row_newbcast:15 row_mask:0xf bank_mask:0xf
	v_fma_f32 v109, -v32, v140, v33
	v_fma_f32 v109, v138, v141, v109
	ds_write_b32 v107, v109 offset:15616
	v_cvt_pk_bf16_f32 v24, v8, v9
	v_cvt_pk_bf16_f32 v25, v10, v11
	v_cvt_pk_bf16_f32 v26, v12, v13
	v_cvt_pk_bf16_f32 v27, v14, v15
	v_cvt_pk_bf16_f32 v28, v16, v17
	v_cvt_pk_bf16_f32 v29, v18, v19
	s_waitcnt lgkmcnt(11)
; __device__ __forceinline__ void phase_rwkv_scan(const Params& p, int l, const int tidx) {
;     ...
;       for (int s = 0; s < RTC; s++) {
;         const bf16x8 A0 = nA0, A1 = nA1;
;         const float wA[8] = {nw0.x, nw0.y, nw0.z, nw0.w, nw1.x, nw1.y, nw1.z, nw1.w};
;         const float wB[8] = {nw2.x, nw2.y, nw2.z, nw2.w, nw3.x, nw3.y, nw3.z, nw3.w};
;         const float kaA[8] = {nka0.x, nka0.y, nka0.z, nka0.w, nka1.x, nka1.y, nka1.z, nka1.w};
;         const float kaB[8] = {nka2.x, nka2.y, nka2.z, nka2.w, nka3.x, nka3.y, nka3.z, nka3.w};
;         const float kdA[8] = {nkd0.x, nkd0.y, nkd0.z, nkd0.w, nkd1.x, nkd1.y, nkd1.z, nkd1.w};
;         const float kdB[8] = {nkd2.x, nkd2.y, nkd2.z, nkd2.w, nkd3.x, nkd3.y, nkd3.z, nkd3.w};
;         const float v = nv;
;         float c1 = nc.x, c2 = nc.y;
;         asm volatile("" : "+v"(c1), "+v"(c2));
;         if (s + 1 < RTC) RW_LD(s + 1);
;         u32x4 pa = {pack2(Sa[0], Sa[1]), pack2(Sa[2], Sa[3]), pack2(Sa[4], Sa[5]), pack2(Sa[6], Sa[7])};
;         u32x4 pb = {pack2(Sb[0], Sb[1]), pack2(Sb[2], Sb[3]), pack2(Sb[4], Sb[5]), pack2(Sb[6], Sb[7])};
;         f32x4 acc = {0.f, 0.f, 0.f, 0.f};
;         acc = __builtin_amdgcn_mfma_f32_16x16x32_bf16(A0, __builtin_bit_cast(bf16x8, pa), acc, 0, 0, 0);
;         acc = __builtin_amdgcn_mfma_f32_16x16x32_bf16(A1, __builtin_bit_cast(bf16x8, pb), acc, 0, 0, 0);
;         float tA[8], tB[8];
; #pragma unroll
;         for (int c = 0; c < 8; c++) { tA[c] = Sa[c] * wA[c] + v * kdA[c]; tB[c] = Sb[c] * wB[c] + v * kdB[c]; }
;         const float sa = -acc[0];
;         const float yq = acc[1];
; #pragma unroll
;         for (int c = 0; c < 8; c++) { Sa[c] = tA[c] + sa * kaA[c]; Sb[c] = tB[c] + sa * kaB[c]; }
;         const float y = yq + sa * c1 + v * c2;
;         if (quad == 0) by[s * 64 + row] = y;
;       }
;     ...
;       __syncthreads();
	v_mfma_f32_16x16x32_bf16 v[32:35], v[40:43], v[24:27], 0
	v_cvt_pk_bf16_f32 v30, v20, v21
	v_cvt_pk_bf16_f32 v31, v22, v23
	v_fmac_f32_dpp v8, v65, v66 row_newbcast:0 row_mask:0xf bank_mask:0xf
	v_fmac_f32_dpp v9, v65, v66 row_newbcast:1 row_mask:0xf bank_mask:0xf
	v_mfma_f32_16x16x32_bf16 v[32:35], v[44:47], v[28:31], v[32:35]
	v_fmac_f32_dpp v10, v65, v66 row_newbcast:2 row_mask:0xf bank_mask:0xf
	v_fmac_f32_dpp v11, v65, v66 row_newbcast:3 row_mask:0xf bank_mask:0xf
	v_fmac_f32_dpp v12, v65, v66 row_newbcast:4 row_mask:0xf bank_mask:0xf
	v_fmac_f32_dpp v13, v65, v66 row_newbcast:5 row_mask:0xf bank_mask:0xf
	v_fmac_f32_dpp v14, v65, v66 row_newbcast:6 row_mask:0xf bank_mask:0xf
	v_fmac_f32_dpp v15, v65, v66 row_newbcast:7 row_mask:0xf bank_mask:0xf
	v_fmac_f32_dpp v16, v65, v66 row_newbcast:8 row_mask:0xf bank_mask:0xf
	v_fmac_f32_dpp v17, v65, v66 row_newbcast:9 row_mask:0xf bank_mask:0xf
	v_fmac_f32_dpp v18, v65, v66 row_newbcast:10 row_mask:0xf bank_mask:0xf
	v_fmac_f32_dpp v19, v65, v66 row_newbcast:11 row_mask:0xf bank_mask:0xf
	v_fmac_f32_dpp v20, v65, v66 row_newbcast:12 row_mask:0xf bank_mask:0xf
	v_fmac_f32_dpp v21, v65, v66 row_newbcast:13 row_mask:0xf bank_mask:0xf
	v_fmac_f32_dpp v22, v65, v66 row_newbcast:14 row_mask:0xf bank_mask:0xf
	v_fmac_f32_dpp v23, v65, v66 row_newbcast:15 row_mask:0xf bank_mask:0xf
	s_waitcnt lgkmcnt(9)
	v_fmac_f32_dpp v8, v48, v32 row_newbcast:0 row_mask:0xf bank_mask:0xf
	v_fmac_f32_dpp v9, v48, v32 row_newbcast:1 row_mask:0xf bank_mask:0xf
	v_fmac_f32_dpp v10, v48, v32 row_newbcast:2 row_mask:0xf bank_mask:0xf
	v_fmac_f32_dpp v11, v48, v32 row_newbcast:3 row_mask:0xf bank_mask:0xf
	v_fmac_f32_dpp v12, v48, v32 row_newbcast:4 row_mask:0xf bank_mask:0xf
	v_fmac_f32_dpp v13, v48, v32 row_newbcast:5 row_mask:0xf bank_mask:0xf
	v_fmac_f32_dpp v14, v48, v32 row_newbcast:6 row_mask:0xf bank_mask:0xf
	v_fmac_f32_dpp v15, v48, v32 row_newbcast:7 row_mask:0xf bank_mask:0xf
	v_fmac_f32_dpp v16, v48, v32 row_newbcast:8 row_mask:0xf bank_mask:0xf
	v_fmac_f32_dpp v17, v48, v32 row_newbcast:9 row_mask:0xf bank_mask:0xf
	v_fmac_f32_dpp v18, v48, v32 row_newbcast:10 row_mask:0xf bank_mask:0xf
	v_fmac_f32_dpp v19, v48, v32 row_newbcast:11 row_mask:0xf bank_mask:0xf
	v_fmac_f32_dpp v20, v48, v32 row_newbcast:12 row_mask:0xf bank_mask:0xf
	v_fmac_f32_dpp v21, v48, v32 row_newbcast:13 row_mask:0xf bank_mask:0xf
	v_fmac_f32_dpp v22, v48, v32 row_newbcast:14 row_mask:0xf bank_mask:0xf
	v_fmac_f32_dpp v23, v48, v32 row_newbcast:15 row_mask:0xf bank_mask:0xf
	v_fma_f32 v109, -v32, v68, v33
	v_fma_f32 v109, v66, v69, v109
	ds_write_b32 v107, v109 offset:15872
	v_cvt_pk_bf16_f32 v24, v8, v9
	v_cvt_pk_bf16_f32 v25, v10, v11
	v_cvt_pk_bf16_f32 v26, v12, v13
	v_cvt_pk_bf16_f32 v27, v14, v15
	v_cvt_pk_bf16_f32 v28, v16, v17
	v_cvt_pk_bf16_f32 v29, v18, v19
	s_waitcnt lgkmcnt(5)
	v_mfma_f32_16x16x32_bf16 v[32:35], v[70:73], v[24:27], 0
	v_cvt_pk_bf16_f32 v30, v20, v21
	v_cvt_pk_bf16_f32 v31, v22, v23
	v_fmac_f32_dpp v8, v95, v96 row_newbcast:0 row_mask:0xf bank_mask:0xf
	v_fmac_f32_dpp v9, v95, v96 row_newbcast:1 row_mask:0xf bank_mask:0xf
	v_mfma_f32_16x16x32_bf16 v[32:35], v[74:77], v[28:31], v[32:35]
	v_fmac_f32_dpp v10, v95, v96 row_newbcast:2 row_mask:0xf bank_mask:0xf
	v_fmac_f32_dpp v11, v95, v96 row_newbcast:3 row_mask:0xf bank_mask:0xf
	v_fmac_f32_dpp v12, v95, v96 row_newbcast:4 row_mask:0xf bank_mask:0xf
	v_fmac_f32_dpp v13, v95, v96 row_newbcast:5 row_mask:0xf bank_mask:0xf
	v_fmac_f32_dpp v14, v95, v96 row_newbcast:6 row_mask:0xf bank_mask:0xf
	v_fmac_f32_dpp v15, v95, v96 row_newbcast:7 row_mask:0xf bank_mask:0xf
	v_fmac_f32_dpp v16, v95, v96 row_newbcast:8 row_mask:0xf bank_mask:0xf
	v_fmac_f32_dpp v17, v95, v96 row_newbcast:9 row_mask:0xf bank_mask:0xf
	v_fmac_f32_dpp v18, v95, v96 row_newbcast:10 row_mask:0xf bank_mask:0xf
	v_fmac_f32_dpp v19, v95, v96 row_newbcast:11 row_mask:0xf bank_mask:0xf
	v_fmac_f32_dpp v20, v95, v96 row_newbcast:12 row_mask:0xf bank_mask:0xf
	v_fmac_f32_dpp v21, v95, v96 row_newbcast:13 row_mask:0xf bank_mask:0xf
	v_fmac_f32_dpp v22, v95, v96 row_newbcast:14 row_mask:0xf bank_mask:0xf
	v_fmac_f32_dpp v23, v95, v96 row_newbcast:15 row_mask:0xf bank_mask:0xf
	s_waitcnt lgkmcnt(2)
	v_fmac_f32_dpp v8, v78, v32 row_newbcast:0 row_mask:0xf bank_mask:0xf
	v_fmac_f32_dpp v9, v78, v32 row_newbcast:1 row_mask:0xf bank_mask:0xf
	v_fmac_f32_dpp v10, v78, v32 row_newbcast:2 row_mask:0xf bank_mask:0xf
	v_fmac_f32_dpp v11, v78, v32 row_newbcast:3 row_mask:0xf bank_mask:0xf
	v_fmac_f32_dpp v12, v78, v32 row_newbcast:4 row_mask:0xf bank_mask:0xf
	v_fmac_f32_dpp v13, v78, v32 row_newbcast:5 row_mask:0xf bank_mask:0xf
	v_fmac_f32_dpp v14, v78, v32 row_newbcast:6 row_mask:0xf bank_mask:0xf
	v_fmac_f32_dpp v15, v78, v32 row_newbcast:7 row_mask:0xf bank_mask:0xf
	v_fmac_f32_dpp v16, v78, v32 row_newbcast:8 row_mask:0xf bank_mask:0xf
	v_fmac_f32_dpp v17, v78, v32 row_newbcast:9 row_mask:0xf bank_mask:0xf
	v_fmac_f32_dpp v18, v78, v32 row_newbcast:10 row_mask:0xf bank_mask:0xf
	v_fmac_f32_dpp v19, v78, v32 row_newbcast:11 row_mask:0xf bank_mask:0xf
	v_fmac_f32_dpp v20, v78, v32 row_newbcast:12 row_mask:0xf bank_mask:0xf
	v_fmac_f32_dpp v21, v78, v32 row_newbcast:13 row_mask:0xf bank_mask:0xf
	v_fmac_f32_dpp v22, v78, v32 row_newbcast:14 row_mask:0xf bank_mask:0xf
	v_fmac_f32_dpp v23, v78, v32 row_newbcast:15 row_mask:0xf bank_mask:0xf
	v_fma_f32 v109, -v32, v98, v33
	v_fma_f32 v109, v96, v99, v109
	v_mul_f32_dpp v8, v94, v8 row_newbcast:0 row_mask:0xf bank_mask:0xf
	v_mul_f32_dpp v9, v94, v9 row_newbcast:1 row_mask:0xf bank_mask:0xf
	v_mul_f32_dpp v10, v94, v10 row_newbcast:2 row_mask:0xf bank_mask:0xf
	v_mul_f32_dpp v11, v94, v11 row_newbcast:3 row_mask:0xf bank_mask:0xf
	v_mul_f32_dpp v12, v94, v12 row_newbcast:4 row_mask:0xf bank_mask:0xf
	v_mul_f32_dpp v13, v94, v13 row_newbcast:5 row_mask:0xf bank_mask:0xf
	v_mul_f32_dpp v14, v94, v14 row_newbcast:6 row_mask:0xf bank_mask:0xf
	v_mul_f32_dpp v15, v94, v15 row_newbcast:7 row_mask:0xf bank_mask:0xf
	v_mul_f32_dpp v16, v94, v16 row_newbcast:8 row_mask:0xf bank_mask:0xf
	v_mul_f32_dpp v17, v94, v17 row_newbcast:9 row_mask:0xf bank_mask:0xf
	v_mul_f32_dpp v18, v94, v18 row_newbcast:10 row_mask:0xf bank_mask:0xf
	v_mul_f32_dpp v19, v94, v19 row_newbcast:11 row_mask:0xf bank_mask:0xf
	v_mul_f32_dpp v20, v94, v20 row_newbcast:12 row_mask:0xf bank_mask:0xf
	v_mul_f32_dpp v21, v94, v21 row_newbcast:13 row_mask:0xf bank_mask:0xf
	v_mul_f32_dpp v22, v94, v22 row_newbcast:14 row_mask:0xf bank_mask:0xf
	v_mul_f32_dpp v23, v94, v23 row_newbcast:15 row_mask:0xf bank_mask:0xf
	ds_write_b32 v107, v109 offset:16128
	s_add_i32 s0, s0, 1
	s_cmpk_eq_i32 s0, 0x80
	s_waitcnt lgkmcnt(0)
	s_barrier
	s_cbranch_scc0 .Lrw_chunk

; __device__ __forceinline__ void phase_prep_layer(const Params& p, int l, const int tidx) {
;     ...
;         const float* wv = p.in[I_WV] + (size_t)l * 4 * 16384 + (size_t)h * 16384 + d * 128;
; #pragma unroll 4
;         for (int e = e0; e < e0 + 32; e++) sacc += wv[e] * gw[(1024 + h * 128 + e) * 16 + o];
;       }
.LBB0_726:
	v_lshl_add_u64 v[228:229], v[14:15], 0, s[16:17]
	v_lshl_add_u64 v[230:231], v[12:13], 0, s[16:17]
	v_lshl_add_u64 v[232:233], v[10:11], 0, s[16:17]
	v_lshl_add_u64 v[234:235], v[8:9], 0, s[16:17]
	global_load_dwordx4 v[74:77], v[72:73], off offset:-8
	global_load_dword v220, v[228:229], off
	global_load_dword v221, v[230:231], off
	global_load_dword v222, v[232:233], off
	global_load_dword v223, v[234:235], off
	v_lshl_add_u64 v[72:73], v[72:73], 0, 16
	s_add_u32 s16, s16, 0x100
	s_addc_u32 s17, s17, 0
	s_waitcnt vmcnt(0)
	v_fmac_f32_e32 v84, v74, v220
	v_fmac_f32_e32 v84, v75, v221
	v_fmac_f32_e32 v84, v76, v222
	v_fmac_f32_e32 v84, v77, v223
	s_cmpk_lg_i32 s16, 0x800
	s_cbranch_scc1 .LBB0_726

; __device__ __forceinline__ void phase_prep_layer(const Params& p, int l, const int tidx) {
;     ...
;       if (which == 0) {
;         const float* wq = p.in[I_WQ] + (size_t)l * 4 * 16384 + (size_t)h * 16384 + d * 128;
;         const float* wk = p.in[I_WK] + (size_t)l * 4 * 16384 + (size_t)h * 16384 + d * 128;
; #pragma unroll 4
;         for (int e = e0; e < e0 + 32; e++)
;           sacc += wq[e] * gw[(h * 128 + e) * 16 + o] + wk[e] * gw[(512 + h * 128 + e) * 16 + o];
.LBB0_730:
	v_lshl_add_u64 v[86:87], v[82:83], 0, v[30:31]
	v_lshl_add_u64 v[156:157], v[80:81], 0, v[30:31]
	global_load_dwordx4 v[86:89], v[86:87], off
	global_load_dwordx4 v[156:159], v[156:157], off
	v_lshl_add_u64 v[228:229], v[78:79], 0, s[26:27]
	v_lshl_add_u64 v[230:231], v[76:77], 0, s[26:27]
	global_load_dword v220, v[228:229], off
	global_load_dword v221, v[230:231], off
	v_lshl_add_u64 v[228:229], v[72:73], 0, s[26:27]
	v_lshl_add_u64 v[230:231], v[74:75], 0, s[26:27]
	global_load_dword v222, v[228:229], off
	global_load_dword v223, v[230:231], off
	v_lshl_add_u64 v[228:229], v[12:13], 0, s[26:27]
	v_lshl_add_u64 v[230:231], v[14:15], 0, s[26:27]
	global_load_dword v224, v[228:229], off
	global_load_dword v225, v[230:231], off
	v_lshl_add_u64 v[228:229], v[8:9], 0, s[26:27]
	v_lshl_add_u64 v[230:231], v[10:11], 0, s[26:27]
	global_load_dword v226, v[228:229], off
	global_load_dword v227, v[230:231], off
	v_lshl_add_u64 v[80:81], v[80:81], 0, 16
	v_lshl_add_u64 v[82:83], v[82:83], 0, 16
	s_add_u32 s26, s26, 0x100
	s_addc_u32 s27, s27, 0
	s_waitcnt vmcnt(0)
	v_mov_b32_e32 v244, v86
	v_mov_b32_e32 v245, v156
	v_mov_b32_e32 v246, v87
	v_mov_b32_e32 v247, v157
	v_mov_b32_e32 v248, v88
	v_mov_b32_e32 v249, v158
	v_mov_b32_e32 v158, v89
	v_pk_mul_f32 v[220:221], v[244:245], v[220:221]
	v_pk_mul_f32 v[222:223], v[246:247], v[222:223]
	v_pk_mul_f32 v[224:225], v[248:249], v[224:225]
	v_pk_mul_f32 v[226:227], v[158:159], v[226:227]
	v_add_f32_e32 v0, v220, v221
	v_add_f32_e32 v0, v84, v0
	v_add_f32_e32 v84, v222, v223
	v_add_f32_e32 v0, v0, v84
	v_add_f32_e32 v84, v224, v225
	v_add_f32_e32 v0, v0, v84
	v_add_f32_e32 v84, v226, v227
	v_add_f32_e32 v84, v0, v84
	s_cmpk_eq_i32 s26, 0x800
	s_cbranch_scc0 .LBB0_730
